# phase-0 weight conversion: next element's W load hoisted above previous wait with renamed regs; per-element vmcnt(0) became counted waits (2 elements in flight)
# speedup vs baseline: 1.0050x; 1.0023x over previous
.LBB0_117:
	s_movk_i32 s0, 0xaff
	v_cmp_lt_i32_e32 vcc, s0, v6
	s_and_saveexec_b64 s[0:1], vcc
	s_xor_b64 s[22:23], exec, s[0:1]
	s_cbranch_execz .LBB0_267
	s_movk_i32 s0, 0x15ff
	v_cmp_lt_u32_e32 vcc, s0, v6
	s_and_saveexec_b64 s[0:1], vcc
	s_xor_b64 s[24:25], exec, s[0:1]
	s_cbranch_execz .LBB0_200
	s_movk_i32 s0, 0x1b7f
	v_cmp_lt_u32_e32 vcc, s0, v6
	s_and_saveexec_b64 s[0:1], vcc
	s_xor_b64 s[26:27], exec, s[0:1]
	s_cbranch_execz .LBB0_197
	s_movk_i32 s0, 0x20ff
	v_cmp_lt_u32_e32 vcc, s0, v6
	s_and_saveexec_b64 s[0:1], vcc
	s_xor_b64 s[28:29], exec, s[0:1]
	s_cbranch_execz .LBB0_194
	s_movk_i32 s0, 0x283f
	v_cmp_lt_u32_e32 vcc, s0, v6
	s_and_saveexec_b64 s[0:1], vcc
	s_xor_b64 s[0:1], exec, s[0:1]
	s_cbranch_execz .LBB0_127
	s_movk_i32 s4, 0x2a3f
	v_and_b32_e32 v3, 0x3e0, v42
	v_cmp_lt_u32_e32 vcc, s4, v6
	v_lshlrev_b32_e32 v2, 2, v3
	v_or_b32_e32 v45, v3, v113
	v_or_b32_e32 v44, v3, v115
	v_or_b32_e32 v5, v3, v116
	v_or_b32_e32 v4, v3, v117
	s_and_saveexec_b64 s[4:5], vcc
	s_xor_b64 s[4:5], exec, s[4:5]
	s_cbranch_execz .LBB0_124
	v_and_b32_e32 v46, 0x1ffc0, v118
	v_mov_b32_e32 v3, v0
	v_or_b32_e32 v47, v46, v8
	v_lshl_add_u64 v[2:3], v[28:29], 0, v[2:3]
	v_lshlrev_b32_e32 v48, 12, v47
	v_mov_b32_e32 v49, v0
	v_lshl_add_u64 v[48:49], v[2:3], 0, v[48:49]
	global_load_dword v47, v[48:49], off
	v_or_b32_e32 v48, v46, v58
	v_lshlrev_b32_e32 v48, 12, v48
	v_mov_b32_e32 v49, v0
	v_lshl_add_u64 v[48:49], v[2:3], 0, v[48:49]
	global_load_dword v48, v[48:49], off
	v_add_u32_e32 v50, v7, v13
	v_mov_b32_e32 v49, v0
	v_lshlrev_b32_e32 v128, 11, v45
	v_mov_b32_e32 v129, v0
	v_lshlrev_b32_e32 v44, 11, v44
	v_lshlrev_b32_e32 v4, 11, v4
	v_or_b32_e32 v170, v46, v60
	v_lshlrev_b32_e32 v168, 12, v170
	v_mov_b32_e32 v169, v0
	v_lshl_add_u64 v[168:169], v[2:3], 0, v[168:169]
	global_load_dword v170, v[168:169], off
	v_or_b32_e32 v168, v46, v62
	v_lshlrev_b32_e32 v168, 12, v168
	v_mov_b32_e32 v169, v0
	v_lshl_add_u64 v[168:169], v[2:3], 0, v[168:169]
	global_load_dword v168, v[168:169], off
	s_waitcnt vmcnt(2)
	ds_write2_b32 v50, v47, v48 offset1:66
	v_mov_b32_e32 v49, v0
	v_or_b32_e32 v162, v46, v64
	v_lshlrev_b32_e32 v160, 12, v162
	v_mov_b32_e32 v161, v0
	v_lshl_add_u64 v[160:161], v[2:3], 0, v[160:161]
	global_load_dword v162, v[160:161], off
	v_or_b32_e32 v160, v46, v66
	v_lshlrev_b32_e32 v160, 12, v160
	v_mov_b32_e32 v161, v0
	v_lshl_add_u64 v[160:161], v[2:3], 0, v[160:161]
	global_load_dword v160, v[160:161], off
	s_waitcnt vmcnt(2)
	ds_write2_b32 v50, v170, v168 offset0:132 offset1:198
	v_add_u32_e32 v49, 0x400, v50
	v_add_u32_e32 v50, v7, v69
	v_or_b32_e32 v170, v46, v68
	v_lshlrev_b32_e32 v168, 12, v170
	v_mov_b32_e32 v169, v0
	v_lshl_add_u64 v[168:169], v[2:3], 0, v[168:169]
	global_load_dword v170, v[168:169], off
	v_or_b32_e32 v168, v46, v70
	v_lshlrev_b32_e32 v168, 12, v168
	v_mov_b32_e32 v169, v0
	v_lshl_add_u64 v[168:169], v[2:3], 0, v[168:169]
	global_load_dword v168, v[168:169], off
	s_waitcnt vmcnt(2)
	ds_write2_b32 v49, v162, v160 offset0:8 offset1:74
	v_mov_b32_e32 v49, v0
	v_or_b32_e32 v162, v46, v72
	v_lshlrev_b32_e32 v160, 12, v162
	v_mov_b32_e32 v161, v0
	v_lshl_add_u64 v[160:161], v[2:3], 0, v[160:161]
	global_load_dword v162, v[160:161], off
	v_or_b32_e32 v160, v46, v74
	v_lshlrev_b32_e32 v160, 12, v160
	v_mov_b32_e32 v161, v0
	v_lshl_add_u64 v[160:161], v[2:3], 0, v[160:161]
	global_load_dword v160, v[160:161], off
	s_waitcnt vmcnt(2)
	ds_write2_b32 v50, v170, v168 offset1:66
	v_mov_b32_e32 v49, v0
	v_or_b32_e32 v170, v46, v76
	v_lshlrev_b32_e32 v168, 12, v170
	v_mov_b32_e32 v169, v0
	v_lshl_add_u64 v[168:169], v[2:3], 0, v[168:169]
	global_load_dword v170, v[168:169], off
	v_or_b32_e32 v168, v46, v78
	v_lshlrev_b32_e32 v168, 12, v168
	v_mov_b32_e32 v169, v0
	v_lshl_add_u64 v[168:169], v[2:3], 0, v[168:169]
	global_load_dword v168, v[168:169], off
	s_waitcnt vmcnt(2)
	ds_write2_b32 v50, v162, v160 offset0:132 offset1:198
	v_add_u32_e32 v49, 0x400, v50
	v_add_u32_e32 v50, v7, v81
	v_or_b32_e32 v162, v46, v80
	v_lshlrev_b32_e32 v160, 12, v162
	v_mov_b32_e32 v161, v0
	v_lshl_add_u64 v[160:161], v[2:3], 0, v[160:161]
	global_load_dword v162, v[160:161], off
	v_or_b32_e32 v160, v46, v82
	v_lshlrev_b32_e32 v160, 12, v160
	v_mov_b32_e32 v161, v0
	v_lshl_add_u64 v[160:161], v[2:3], 0, v[160:161]
	global_load_dword v160, v[160:161], off
	s_waitcnt vmcnt(2)
	ds_write2_b32 v49, v170, v168 offset0:8 offset1:74
	v_mov_b32_e32 v49, v0
	v_or_b32_e32 v170, v46, v84
	v_lshlrev_b32_e32 v168, 12, v170
	v_mov_b32_e32 v169, v0
	v_lshl_add_u64 v[168:169], v[2:3], 0, v[168:169]
	global_load_dword v170, v[168:169], off
	v_or_b32_e32 v168, v46, v86
	v_lshlrev_b32_e32 v168, 12, v168
	v_mov_b32_e32 v169, v0
	v_lshl_add_u64 v[168:169], v[2:3], 0, v[168:169]
	global_load_dword v168, v[168:169], off
	s_waitcnt vmcnt(2)
	ds_write2_b32 v50, v162, v160 offset1:66
	v_mov_b32_e32 v49, v0
	v_or_b32_e32 v162, v46, v88
	v_lshlrev_b32_e32 v160, 12, v162
	v_mov_b32_e32 v161, v0
	v_lshl_add_u64 v[160:161], v[2:3], 0, v[160:161]
	global_load_dword v162, v[160:161], off
	v_or_b32_e32 v160, v46, v90
	v_lshlrev_b32_e32 v160, 12, v160
	v_mov_b32_e32 v161, v0
	v_lshl_add_u64 v[160:161], v[2:3], 0, v[160:161]
	global_load_dword v160, v[160:161], off
	s_waitcnt vmcnt(2)
	ds_write2_b32 v50, v170, v168 offset0:132 offset1:198
	v_add_u32_e32 v49, 0x400, v50
	v_add_u32_e32 v50, v7, v93
	v_or_b32_e32 v170, v46, v92
	v_lshlrev_b32_e32 v168, 12, v170
	v_mov_b32_e32 v169, v0
	v_lshl_add_u64 v[168:169], v[2:3], 0, v[168:169]
	global_load_dword v170, v[168:169], off
	v_or_b32_e32 v168, v46, v94
	v_lshlrev_b32_e32 v168, 12, v168
	v_mov_b32_e32 v169, v0
	v_lshl_add_u64 v[168:169], v[2:3], 0, v[168:169]
	global_load_dword v168, v[168:169], off
	s_waitcnt vmcnt(2)
	ds_write2_b32 v49, v162, v160 offset0:8 offset1:74
	v_mov_b32_e32 v49, v0
	v_or_b32_e32 v162, v46, v96
	v_lshlrev_b32_e32 v160, 12, v162
	v_mov_b32_e32 v161, v0
	v_lshl_add_u64 v[160:161], v[2:3], 0, v[160:161]
	global_load_dword v162, v[160:161], off
	v_or_b32_e32 v160, v46, v98
	v_lshlrev_b32_e32 v160, 12, v160
	v_mov_b32_e32 v161, v0
	v_lshl_add_u64 v[160:161], v[2:3], 0, v[160:161]
	global_load_dword v160, v[160:161], off
	s_waitcnt vmcnt(2)
	ds_write2_b32 v50, v170, v168 offset1:66
	v_mov_b32_e32 v49, v0
	v_or_b32_e32 v170, v46, v100
	v_lshlrev_b32_e32 v168, 12, v170
	v_mov_b32_e32 v169, v0
	v_lshl_add_u64 v[168:169], v[2:3], 0, v[168:169]
	global_load_dword v170, v[168:169], off
	v_or_b32_e32 v168, v46, v102
	v_lshlrev_b32_e32 v168, 12, v168
	v_mov_b32_e32 v169, v0
	v_lshl_add_u64 v[168:169], v[2:3], 0, v[168:169]
	global_load_dword v168, v[168:169], off
	s_waitcnt vmcnt(2)
	ds_write2_b32 v50, v162, v160 offset0:132 offset1:198
	v_add_u32_e32 v49, 0x400, v50
	v_add_u32_e32 v50, v7, v105
	v_or_b32_e32 v162, v46, v104
	v_lshlrev_b32_e32 v160, 12, v162
	v_mov_b32_e32 v161, v0
	v_lshl_add_u64 v[160:161], v[2:3], 0, v[160:161]
	global_load_dword v162, v[160:161], off
	v_or_b32_e32 v160, v46, v106
	v_lshlrev_b32_e32 v160, 12, v160
	v_mov_b32_e32 v161, v0
	v_lshl_add_u64 v[160:161], v[2:3], 0, v[160:161]
	global_load_dword v160, v[160:161], off
	s_waitcnt vmcnt(2)
	ds_write2_b32 v49, v170, v168 offset0:8 offset1:74
	v_mov_b32_e32 v49, v0
	v_or_b32_e32 v170, v46, v107
	v_lshlrev_b32_e32 v168, 12, v170
	v_mov_b32_e32 v169, v0
	v_lshl_add_u64 v[168:169], v[2:3], 0, v[168:169]
	global_load_dword v170, v[168:169], off
	v_or_b32_e32 v168, v46, v108
	v_lshlrev_b32_e32 v168, 12, v168
	v_mov_b32_e32 v169, v0
	v_lshl_add_u64 v[168:169], v[2:3], 0, v[168:169]
	global_load_dword v168, v[168:169], off
	s_waitcnt vmcnt(2)
	ds_write2_b32 v50, v162, v160 offset1:66
	v_mov_b32_e32 v49, v0
	v_or_b32_e32 v162, v46, v109
	v_lshlrev_b32_e32 v160, 12, v162
	v_mov_b32_e32 v161, v0
	v_lshl_add_u64 v[160:161], v[2:3], 0, v[160:161]
	global_load_dword v162, v[160:161], off
	v_or_b32_e32 v160, v46, v110
	v_lshlrev_b32_e32 v160, 12, v160
	v_mov_b32_e32 v161, v0
	v_lshl_add_u64 v[160:161], v[2:3], 0, v[160:161]
	global_load_dword v160, v[160:161], off
	s_waitcnt vmcnt(2)
	ds_write2_b32 v50, v170, v168 offset0:132 offset1:198
	v_add_u32_e32 v50, 0x400, v50
	v_mov_b32_e32 v49, v0
	v_or_b32_e32 v172, v46, v111
	v_lshlrev_b32_e32 v170, 12, v172
	v_mov_b32_e32 v171, v0
	v_lshl_add_u64 v[170:171], v[2:3], 0, v[170:171]
	global_load_dword v172, v[170:171], off
	v_or_b32_e32 v170, v46, v112
	v_lshlrev_b32_e32 v170, 12, v170
	v_mov_b32_e32 v171, v0
	v_lshl_add_u64 v[168:169], v[2:3], 0, v[170:171]
	global_load_dword v168, v[168:169], off
	s_waitcnt vmcnt(2)
	ds_write2_b32 v50, v162, v160 offset0:8 offset1:74
	v_mov_b32_e32 v3, v0
	s_waitcnt vmcnt(0)
	ds_write2_b32 v50, v172, v168 offset0:140 offset1:206
	s_waitcnt lgkmcnt(0)
	ds_read2_b32 v[50:51], v114 offset0:33 offset1:41
	ds_read2_b32 v[52:53], v114 offset1:8
	ds_read2_b32 v[54:55], v114 offset0:66 offset1:74
	ds_read2_b32 v[56:57], v114 offset0:99 offset1:107
	v_lshlrev_b32_e32 v2, 1, v46
	ds_read2_b32 v[120:121], v114 offset0:132 offset1:140
	ds_read2_b32 v[122:123], v114 offset0:165 offset1:173
	s_waitcnt lgkmcnt(5)
	v_bfe_u32 v47, v50, 16, 1
	s_waitcnt lgkmcnt(4)
	v_bfe_u32 v46, v52, 16, 1
	v_add3_u32 v46, v52, v46, s51
	v_lshrrev_b32_e32 v46, 16, v46
	v_add3_u32 v47, v50, v47, s51
	v_and_or_b32 v46, v47, s33, v46
	s_waitcnt lgkmcnt(3)
	v_bfe_u32 v47, v54, 16, 1
	v_add3_u32 v47, v54, v47, s51
	s_waitcnt lgkmcnt(2)
	v_bfe_u32 v48, v56, 16, 1
	v_lshrrev_b32_e32 v47, 16, v47
	v_add3_u32 v48, v56, v48, s51
	ds_read2_b32 v[124:125], v114 offset0:198 offset1:206
	ds_read2_b32 v[126:127], v114 offset0:231 offset1:239
	v_and_or_b32 v47, v48, s33, v47
	s_waitcnt lgkmcnt(3)
	v_bfe_u32 v48, v120, 16, 1
	v_add3_u32 v48, v120, v48, s51
	s_waitcnt lgkmcnt(2)
	v_bfe_u32 v49, v122, 16, 1
	v_lshrrev_b32_e32 v48, 16, v48
	v_add3_u32 v49, v122, v49, s51
	v_and_or_b32 v48, v49, s33, v48
	s_waitcnt lgkmcnt(1)
	v_bfe_u32 v49, v124, 16, 1
	v_add3_u32 v49, v124, v49, s51
	s_waitcnt lgkmcnt(0)
	v_bfe_u32 v50, v126, 16, 1
	v_lshl_add_u64 v[2:3], v[14:15], 0, v[2:3]
	v_lshrrev_b32_e32 v49, 16, v49
	v_add3_u32 v50, v126, v50, s51
	v_and_or_b32 v49, v50, s33, v49
	v_lshl_add_u64 v[128:129], v[2:3], 0, v[128:129]
	v_bfe_u32 v45, v53, 16, 1
	global_store_dwordx4 v[128:129], v[46:49], off
	v_add3_u32 v45, v53, v45, s51
	v_lshrrev_b32_e32 v45, 16, v45
	v_bfe_u32 v46, v51, 16, 1
	v_add3_u32 v46, v51, v46, s51
	v_and_or_b32 v46, v46, s33, v45
	v_bfe_u32 v45, v55, 16, 1
	v_add3_u32 v45, v55, v45, s51
	v_bfe_u32 v47, v57, 16, 1
	v_lshrrev_b32_e32 v45, 16, v45
	v_add3_u32 v47, v57, v47, s51
	v_and_or_b32 v47, v47, s33, v45
	v_bfe_u32 v45, v121, 16, 1
	v_add3_u32 v45, v121, v45, s51
	v_bfe_u32 v48, v123, 16, 1
	v_lshrrev_b32_e32 v45, 16, v45
	v_add3_u32 v48, v123, v48, s51
	v_and_or_b32 v48, v48, s33, v45
	v_bfe_u32 v45, v125, 16, 1
	v_add3_u32 v45, v125, v45, s51
	v_bfe_u32 v49, v127, 16, 1
	v_lshrrev_b32_e32 v45, 16, v45
	v_add3_u32 v49, v127, v49, s51
	v_and_or_b32 v49, v49, s33, v45
	v_mov_b32_e32 v45, v0
	v_lshl_add_u64 v[44:45], v[2:3], 0, v[44:45]
	global_store_dwordx4 v[44:45], v[46:49], off
	ds_read2_b32 v[48:49], v114 offset0:49 offset1:57
	ds_read2_b32 v[50:51], v114 offset0:16 offset1:24
	ds_read2_b32 v[52:53], v114 offset0:82 offset1:90
	ds_read2_b32 v[54:55], v114 offset0:115 offset1:123
	ds_read2_b32 v[56:57], v114 offset0:148 offset1:156
	ds_read2_b32 v[120:121], v114 offset0:181 offset1:189
	ds_read2_b32 v[122:123], v114 offset0:214 offset1:222
	ds_read2_b32 v[124:125], v114 offset0:247 offset1:255
	s_waitcnt lgkmcnt(7)
	v_bfe_u32 v45, v48, 16, 1
	s_waitcnt lgkmcnt(6)
	v_bfe_u32 v44, v50, 16, 1
	v_add3_u32 v44, v50, v44, s51
	v_lshrrev_b32_e32 v44, 16, v44
	v_add3_u32 v45, v48, v45, s51
	v_and_or_b32 v44, v45, s33, v44
	s_waitcnt lgkmcnt(5)
	v_bfe_u32 v45, v52, 16, 1
	v_add3_u32 v45, v52, v45, s51
	s_waitcnt lgkmcnt(4)
	v_bfe_u32 v46, v54, 16, 1
	v_lshrrev_b32_e32 v45, 16, v45
	v_add3_u32 v46, v54, v46, s51
	v_and_or_b32 v45, v46, s33, v45
	s_waitcnt lgkmcnt(3)
	v_bfe_u32 v46, v56, 16, 1
	v_add3_u32 v46, v56, v46, s51
	s_waitcnt lgkmcnt(2)
	v_bfe_u32 v47, v120, 16, 1
	v_lshrrev_b32_e32 v46, 16, v46
	v_add3_u32 v47, v120, v47, s51
	v_and_or_b32 v46, v47, s33, v46
	s_waitcnt lgkmcnt(1)
	v_bfe_u32 v47, v122, 16, 1
	v_add3_u32 v47, v122, v47, s51
	s_waitcnt lgkmcnt(0)
	v_bfe_u32 v48, v124, 16, 1
	v_lshrrev_b32_e32 v47, 16, v47
	v_add3_u32 v48, v124, v48, s51
	v_lshlrev_b32_e32 v126, 11, v5
	v_mov_b32_e32 v127, v0
	v_and_or_b32 v47, v48, s33, v47
	v_lshl_add_u64 v[126:127], v[2:3], 0, v[126:127]
	v_bfe_u32 v5, v51, 16, 1
	global_store_dwordx4 v[126:127], v[44:47], off
	v_add3_u32 v5, v51, v5, s51
	v_lshrrev_b32_e32 v5, 16, v5
	v_bfe_u32 v44, v49, 16, 1
	v_add3_u32 v44, v49, v44, s51
	v_and_or_b32 v44, v44, s33, v5
	v_bfe_u32 v5, v53, 16, 1
	v_add3_u32 v5, v53, v5, s51
	v_bfe_u32 v45, v55, 16, 1
	v_lshrrev_b32_e32 v5, 16, v5
	v_add3_u32 v45, v55, v45, s51
	v_and_or_b32 v45, v45, s33, v5
	v_bfe_u32 v5, v57, 16, 1
	v_add3_u32 v5, v57, v5, s51
	v_bfe_u32 v46, v121, 16, 1
	v_lshrrev_b32_e32 v5, 16, v5
	v_add3_u32 v46, v121, v46, s51
	v_and_or_b32 v46, v46, s33, v5
	v_bfe_u32 v5, v123, 16, 1
	v_add3_u32 v5, v123, v5, s51
	v_bfe_u32 v47, v125, 16, 1
	v_lshrrev_b32_e32 v5, 16, v5
	v_add3_u32 v47, v125, v47, s51
	v_and_or_b32 v47, v47, s33, v5
	v_mov_b32_e32 v5, v0
	v_lshl_add_u64 v[2:3], v[2:3], 0, v[4:5]
	global_store_dwordx4 v[2:3], v[44:47], off
	s_waitcnt lgkmcnt(0)
.LBB0_124:
	s_andn2_saveexec_b64 s[4:5], s[4:5]
	s_cbranch_execz .LBB0_126
	v_add_u32_e32 v3, 0x400, v118
	v_and_b32_e32 v46, 0x1ffc0, v3
	v_mov_b32_e32 v3, v0
	v_or_b32_e32 v47, v46, v8
	v_lshl_add_u64 v[2:3], v[30:31], 0, v[2:3]
	v_lshlrev_b32_e32 v48, 12, v47
	v_mov_b32_e32 v49, v0
	v_lshl_add_u64 v[48:49], v[2:3], 0, v[48:49]
	global_load_dword v47, v[48:49], off
	v_or_b32_e32 v48, v46, v58
	v_lshlrev_b32_e32 v48, 12, v48
	v_mov_b32_e32 v49, v0
	v_lshl_add_u64 v[48:49], v[2:3], 0, v[48:49]
	global_load_dword v48, v[48:49], off
	v_add_u32_e32 v50, v7, v13
	v_mov_b32_e32 v49, v0
	v_lshlrev_b32_e32 v128, 11, v45
	v_mov_b32_e32 v129, v0
	v_lshlrev_b32_e32 v44, 11, v44
	v_lshlrev_b32_e32 v4, 11, v4
	v_or_b32_e32 v170, v46, v60
	v_lshlrev_b32_e32 v168, 12, v170
	v_mov_b32_e32 v169, v0
	v_lshl_add_u64 v[168:169], v[2:3], 0, v[168:169]
	global_load_dword v170, v[168:169], off
	v_or_b32_e32 v168, v46, v62
	v_lshlrev_b32_e32 v168, 12, v168
	v_mov_b32_e32 v169, v0
	v_lshl_add_u64 v[168:169], v[2:3], 0, v[168:169]
	global_load_dword v168, v[168:169], off
	s_waitcnt vmcnt(2)
	ds_write2_b32 v50, v47, v48 offset1:66
	v_mov_b32_e32 v49, v0
	v_or_b32_e32 v162, v46, v64
	v_lshlrev_b32_e32 v160, 12, v162
	v_mov_b32_e32 v161, v0
	v_lshl_add_u64 v[160:161], v[2:3], 0, v[160:161]
	global_load_dword v162, v[160:161], off
	v_or_b32_e32 v160, v46, v66
	v_lshlrev_b32_e32 v160, 12, v160
	v_mov_b32_e32 v161, v0
	v_lshl_add_u64 v[160:161], v[2:3], 0, v[160:161]
	global_load_dword v160, v[160:161], off
	s_waitcnt vmcnt(2)
	ds_write2_b32 v50, v170, v168 offset0:132 offset1:198
	v_add_u32_e32 v49, 0x400, v50
	v_add_u32_e32 v50, v7, v69
	v_or_b32_e32 v170, v46, v68
	v_lshlrev_b32_e32 v168, 12, v170
	v_mov_b32_e32 v169, v0
	v_lshl_add_u64 v[168:169], v[2:3], 0, v[168:169]
	global_load_dword v170, v[168:169], off
	v_or_b32_e32 v168, v46, v70
	v_lshlrev_b32_e32 v168, 12, v168
	v_mov_b32_e32 v169, v0
	v_lshl_add_u64 v[168:169], v[2:3], 0, v[168:169]
	global_load_dword v168, v[168:169], off
	s_waitcnt vmcnt(2)
	ds_write2_b32 v49, v162, v160 offset0:8 offset1:74
	v_mov_b32_e32 v49, v0
	v_or_b32_e32 v162, v46, v72
	v_lshlrev_b32_e32 v160, 12, v162
	v_mov_b32_e32 v161, v0
	v_lshl_add_u64 v[160:161], v[2:3], 0, v[160:161]
	global_load_dword v162, v[160:161], off
	v_or_b32_e32 v160, v46, v74
	v_lshlrev_b32_e32 v160, 12, v160
	v_mov_b32_e32 v161, v0
	v_lshl_add_u64 v[160:161], v[2:3], 0, v[160:161]
	global_load_dword v160, v[160:161], off
	s_waitcnt vmcnt(2)
	ds_write2_b32 v50, v170, v168 offset1:66
	v_mov_b32_e32 v49, v0
	v_or_b32_e32 v170, v46, v76
	v_lshlrev_b32_e32 v168, 12, v170
	v_mov_b32_e32 v169, v0
	v_lshl_add_u64 v[168:169], v[2:3], 0, v[168:169]
	global_load_dword v170, v[168:169], off
	v_or_b32_e32 v168, v46, v78
	v_lshlrev_b32_e32 v168, 12, v168
	v_mov_b32_e32 v169, v0
	v_lshl_add_u64 v[168:169], v[2:3], 0, v[168:169]
	global_load_dword v168, v[168:169], off
	s_waitcnt vmcnt(2)
	ds_write2_b32 v50, v162, v160 offset0:132 offset1:198
	v_add_u32_e32 v49, 0x400, v50
	v_add_u32_e32 v50, v7, v81
	v_or_b32_e32 v162, v46, v80
	v_lshlrev_b32_e32 v160, 12, v162
	v_mov_b32_e32 v161, v0
	v_lshl_add_u64 v[160:161], v[2:3], 0, v[160:161]
	global_load_dword v162, v[160:161], off
	v_or_b32_e32 v160, v46, v82
	v_lshlrev_b32_e32 v160, 12, v160
	v_mov_b32_e32 v161, v0
	v_lshl_add_u64 v[160:161], v[2:3], 0, v[160:161]
	global_load_dword v160, v[160:161], off
	s_waitcnt vmcnt(2)
	ds_write2_b32 v49, v170, v168 offset0:8 offset1:74
	v_mov_b32_e32 v49, v0
	v_or_b32_e32 v170, v46, v84
	v_lshlrev_b32_e32 v168, 12, v170
	v_mov_b32_e32 v169, v0
	v_lshl_add_u64 v[168:169], v[2:3], 0, v[168:169]
	global_load_dword v170, v[168:169], off
	v_or_b32_e32 v168, v46, v86
	v_lshlrev_b32_e32 v168, 12, v168
	v_mov_b32_e32 v169, v0
	v_lshl_add_u64 v[168:169], v[2:3], 0, v[168:169]
	global_load_dword v168, v[168:169], off
	s_waitcnt vmcnt(2)
	ds_write2_b32 v50, v162, v160 offset1:66
	v_mov_b32_e32 v49, v0
	v_or_b32_e32 v162, v46, v88
	v_lshlrev_b32_e32 v160, 12, v162
	v_mov_b32_e32 v161, v0
	v_lshl_add_u64 v[160:161], v[2:3], 0, v[160:161]
	global_load_dword v162, v[160:161], off
	v_or_b32_e32 v160, v46, v90
	v_lshlrev_b32_e32 v160, 12, v160
	v_mov_b32_e32 v161, v0
	v_lshl_add_u64 v[160:161], v[2:3], 0, v[160:161]
	global_load_dword v160, v[160:161], off
	s_waitcnt vmcnt(2)
	ds_write2_b32 v50, v170, v168 offset0:132 offset1:198
	v_add_u32_e32 v49, 0x400, v50
	v_add_u32_e32 v50, v7, v93
	v_or_b32_e32 v170, v46, v92
	v_lshlrev_b32_e32 v168, 12, v170
	v_mov_b32_e32 v169, v0
	v_lshl_add_u64 v[168:169], v[2:3], 0, v[168:169]
	global_load_dword v170, v[168:169], off
	v_or_b32_e32 v168, v46, v94
	v_lshlrev_b32_e32 v168, 12, v168
	v_mov_b32_e32 v169, v0
	v_lshl_add_u64 v[168:169], v[2:3], 0, v[168:169]
	global_load_dword v168, v[168:169], off
	s_waitcnt vmcnt(2)
	ds_write2_b32 v49, v162, v160 offset0:8 offset1:74
	v_mov_b32_e32 v49, v0
	v_or_b32_e32 v162, v46, v96
	v_lshlrev_b32_e32 v160, 12, v162
	v_mov_b32_e32 v161, v0
	v_lshl_add_u64 v[160:161], v[2:3], 0, v[160:161]
	global_load_dword v162, v[160:161], off
	v_or_b32_e32 v160, v46, v98
	v_lshlrev_b32_e32 v160, 12, v160
	v_mov_b32_e32 v161, v0
	v_lshl_add_u64 v[160:161], v[2:3], 0, v[160:161]
	global_load_dword v160, v[160:161], off
	s_waitcnt vmcnt(2)
	ds_write2_b32 v50, v170, v168 offset1:66
	v_mov_b32_e32 v49, v0
	v_or_b32_e32 v170, v46, v100
	v_lshlrev_b32_e32 v168, 12, v170
	v_mov_b32_e32 v169, v0
	v_lshl_add_u64 v[168:169], v[2:3], 0, v[168:169]
	global_load_dword v170, v[168:169], off
	v_or_b32_e32 v168, v46, v102
	v_lshlrev_b32_e32 v168, 12, v168
	v_mov_b32_e32 v169, v0
	v_lshl_add_u64 v[168:169], v[2:3], 0, v[168:169]
	global_load_dword v168, v[168:169], off
	s_waitcnt vmcnt(2)
	ds_write2_b32 v50, v162, v160 offset0:132 offset1:198
	v_add_u32_e32 v49, 0x400, v50
	v_add_u32_e32 v50, v7, v105
	v_or_b32_e32 v162, v46, v104
	v_lshlrev_b32_e32 v160, 12, v162
	v_mov_b32_e32 v161, v0
	v_lshl_add_u64 v[160:161], v[2:3], 0, v[160:161]
	global_load_dword v162, v[160:161], off
	v_or_b32_e32 v160, v46, v106
	v_lshlrev_b32_e32 v160, 12, v160
	v_mov_b32_e32 v161, v0
	v_lshl_add_u64 v[160:161], v[2:3], 0, v[160:161]
	global_load_dword v160, v[160:161], off
	s_waitcnt vmcnt(2)
	ds_write2_b32 v49, v170, v168 offset0:8 offset1:74
	v_mov_b32_e32 v49, v0
	v_or_b32_e32 v170, v46, v107
	v_lshlrev_b32_e32 v168, 12, v170
	v_mov_b32_e32 v169, v0
	v_lshl_add_u64 v[168:169], v[2:3], 0, v[168:169]
	global_load_dword v170, v[168:169], off
	v_or_b32_e32 v168, v46, v108
	v_lshlrev_b32_e32 v168, 12, v168
	v_mov_b32_e32 v169, v0
	v_lshl_add_u64 v[168:169], v[2:3], 0, v[168:169]
	global_load_dword v168, v[168:169], off
	s_waitcnt vmcnt(2)
	ds_write2_b32 v50, v162, v160 offset1:66
	v_mov_b32_e32 v49, v0
	v_or_b32_e32 v162, v46, v109
	v_lshlrev_b32_e32 v160, 12, v162
	v_mov_b32_e32 v161, v0
	v_lshl_add_u64 v[160:161], v[2:3], 0, v[160:161]
	global_load_dword v162, v[160:161], off
	v_or_b32_e32 v160, v46, v110
	v_lshlrev_b32_e32 v160, 12, v160
	v_mov_b32_e32 v161, v0
	v_lshl_add_u64 v[160:161], v[2:3], 0, v[160:161]
	global_load_dword v160, v[160:161], off
	s_waitcnt vmcnt(2)
	ds_write2_b32 v50, v170, v168 offset0:132 offset1:198
	v_add_u32_e32 v50, 0x400, v50
	v_mov_b32_e32 v49, v0
	v_or_b32_e32 v172, v46, v111
	v_lshlrev_b32_e32 v170, 12, v172
	v_mov_b32_e32 v171, v0
	v_lshl_add_u64 v[170:171], v[2:3], 0, v[170:171]
	global_load_dword v172, v[170:171], off
	v_or_b32_e32 v170, v46, v112
	v_lshlrev_b32_e32 v170, 12, v170
	v_mov_b32_e32 v171, v0
	v_lshl_add_u64 v[168:169], v[2:3], 0, v[170:171]
	global_load_dword v168, v[168:169], off
	s_waitcnt vmcnt(2)
	ds_write2_b32 v50, v162, v160 offset0:8 offset1:74
	v_mov_b32_e32 v3, v0
	s_waitcnt vmcnt(0)
	ds_write2_b32 v50, v172, v168 offset0:140 offset1:206
	s_waitcnt lgkmcnt(0)
	ds_read2_b32 v[50:51], v114 offset0:33 offset1:41
	ds_read2_b32 v[52:53], v114 offset1:8
	ds_read2_b32 v[54:55], v114 offset0:66 offset1:74
	ds_read2_b32 v[56:57], v114 offset0:99 offset1:107
	v_lshlrev_b32_e32 v2, 1, v46
	ds_read2_b32 v[120:121], v114 offset0:132 offset1:140
	ds_read2_b32 v[122:123], v114 offset0:165 offset1:173
	s_waitcnt lgkmcnt(5)
	v_bfe_u32 v47, v50, 16, 1
	s_waitcnt lgkmcnt(4)
	v_bfe_u32 v46, v52, 16, 1
	v_add3_u32 v46, v52, v46, s51
	v_lshrrev_b32_e32 v46, 16, v46
	v_add3_u32 v47, v50, v47, s51
	v_and_or_b32 v46, v47, s33, v46
	s_waitcnt lgkmcnt(3)
	v_bfe_u32 v47, v54, 16, 1
	v_add3_u32 v47, v54, v47, s51
	s_waitcnt lgkmcnt(2)
	v_bfe_u32 v48, v56, 16, 1
	v_lshrrev_b32_e32 v47, 16, v47
	v_add3_u32 v48, v56, v48, s51
	ds_read2_b32 v[124:125], v114 offset0:198 offset1:206
	ds_read2_b32 v[126:127], v114 offset0:231 offset1:239
	v_and_or_b32 v47, v48, s33, v47
	s_waitcnt lgkmcnt(3)
	v_bfe_u32 v48, v120, 16, 1
	v_add3_u32 v48, v120, v48, s51
	s_waitcnt lgkmcnt(2)
	v_bfe_u32 v49, v122, 16, 1
	v_lshrrev_b32_e32 v48, 16, v48
	v_add3_u32 v49, v122, v49, s51
	v_and_or_b32 v48, v49, s33, v48
	s_waitcnt lgkmcnt(1)
	v_bfe_u32 v49, v124, 16, 1
	v_add3_u32 v49, v124, v49, s51
	s_waitcnt lgkmcnt(0)
	v_bfe_u32 v50, v126, 16, 1
	v_lshl_add_u64 v[2:3], v[16:17], 0, v[2:3]
	v_lshrrev_b32_e32 v49, 16, v49
	v_add3_u32 v50, v126, v50, s51
	v_and_or_b32 v49, v50, s33, v49
	v_lshl_add_u64 v[128:129], v[2:3], 0, v[128:129]
	v_bfe_u32 v45, v53, 16, 1
	global_store_dwordx4 v[128:129], v[46:49], off
	v_add3_u32 v45, v53, v45, s51
	v_lshrrev_b32_e32 v45, 16, v45
	v_bfe_u32 v46, v51, 16, 1
	v_add3_u32 v46, v51, v46, s51
	v_and_or_b32 v46, v46, s33, v45
	v_bfe_u32 v45, v55, 16, 1
	v_add3_u32 v45, v55, v45, s51
	v_bfe_u32 v47, v57, 16, 1
	v_lshrrev_b32_e32 v45, 16, v45
	v_add3_u32 v47, v57, v47, s51
	v_and_or_b32 v47, v47, s33, v45
	v_bfe_u32 v45, v121, 16, 1
	v_add3_u32 v45, v121, v45, s51
	v_bfe_u32 v48, v123, 16, 1
	v_lshrrev_b32_e32 v45, 16, v45
	v_add3_u32 v48, v123, v48, s51
	v_and_or_b32 v48, v48, s33, v45
	v_bfe_u32 v45, v125, 16, 1
	v_add3_u32 v45, v125, v45, s51
	v_bfe_u32 v49, v127, 16, 1
	v_lshrrev_b32_e32 v45, 16, v45
	v_add3_u32 v49, v127, v49, s51
	v_and_or_b32 v49, v49, s33, v45
	v_mov_b32_e32 v45, v0
	v_lshl_add_u64 v[44:45], v[2:3], 0, v[44:45]
	global_store_dwordx4 v[44:45], v[46:49], off
	ds_read2_b32 v[48:49], v114 offset0:49 offset1:57
	ds_read2_b32 v[50:51], v114 offset0:16 offset1:24
	ds_read2_b32 v[52:53], v114 offset0:82 offset1:90
	ds_read2_b32 v[54:55], v114 offset0:115 offset1:123
	ds_read2_b32 v[56:57], v114 offset0:148 offset1:156
	ds_read2_b32 v[120:121], v114 offset0:181 offset1:189
	ds_read2_b32 v[122:123], v114 offset0:214 offset1:222
	ds_read2_b32 v[124:125], v114 offset0:247 offset1:255
	s_waitcnt lgkmcnt(7)
	v_bfe_u32 v45, v48, 16, 1
	s_waitcnt lgkmcnt(6)
	v_bfe_u32 v44, v50, 16, 1
	v_add3_u32 v44, v50, v44, s51
	v_lshrrev_b32_e32 v44, 16, v44
	v_add3_u32 v45, v48, v45, s51
	v_and_or_b32 v44, v45, s33, v44
	s_waitcnt lgkmcnt(5)
	v_bfe_u32 v45, v52, 16, 1
	v_add3_u32 v45, v52, v45, s51
	s_waitcnt lgkmcnt(4)
	v_bfe_u32 v46, v54, 16, 1
	v_lshrrev_b32_e32 v45, 16, v45
	v_add3_u32 v46, v54, v46, s51
	v_and_or_b32 v45, v46, s33, v45
	s_waitcnt lgkmcnt(3)
	v_bfe_u32 v46, v56, 16, 1
	v_add3_u32 v46, v56, v46, s51
	s_waitcnt lgkmcnt(2)
	v_bfe_u32 v47, v120, 16, 1
	v_lshrrev_b32_e32 v46, 16, v46
	v_add3_u32 v47, v120, v47, s51
	v_and_or_b32 v46, v47, s33, v46
	s_waitcnt lgkmcnt(1)
	v_bfe_u32 v47, v122, 16, 1
	v_add3_u32 v47, v122, v47, s51
	s_waitcnt lgkmcnt(0)
	v_bfe_u32 v48, v124, 16, 1
	v_lshrrev_b32_e32 v47, 16, v47
	v_add3_u32 v48, v124, v48, s51
	v_lshlrev_b32_e32 v126, 11, v5
	v_mov_b32_e32 v127, v0
	v_and_or_b32 v47, v48, s33, v47
	v_lshl_add_u64 v[126:127], v[2:3], 0, v[126:127]
	v_bfe_u32 v5, v51, 16, 1
	global_store_dwordx4 v[126:127], v[44:47], off
	v_add3_u32 v5, v51, v5, s51
	v_lshrrev_b32_e32 v5, 16, v5
	v_bfe_u32 v44, v49, 16, 1
	v_add3_u32 v44, v49, v44, s51
	v_and_or_b32 v44, v44, s33, v5
	v_bfe_u32 v5, v53, 16, 1
	v_add3_u32 v5, v53, v5, s51
	v_bfe_u32 v45, v55, 16, 1
	v_lshrrev_b32_e32 v5, 16, v5
	v_add3_u32 v45, v55, v45, s51
	v_and_or_b32 v45, v45, s33, v5
	v_bfe_u32 v5, v57, 16, 1
	v_add3_u32 v5, v57, v5, s51
	v_bfe_u32 v46, v121, 16, 1
	v_lshrrev_b32_e32 v5, 16, v5
	v_add3_u32 v46, v121, v46, s51
	v_and_or_b32 v46, v46, s33, v5
	v_bfe_u32 v5, v123, 16, 1
	v_add3_u32 v5, v123, v5, s51
	v_bfe_u32 v47, v125, 16, 1
	v_lshrrev_b32_e32 v5, 16, v5
	v_add3_u32 v47, v125, v47, s51
	v_and_or_b32 v47, v47, s33, v5
	v_mov_b32_e32 v5, v0
	v_lshl_add_u64 v[2:3], v[2:3], 0, v[4:5]
	global_store_dwordx4 v[2:3], v[44:47], off
	s_waitcnt lgkmcnt(0)

.LBB0_130:
	v_mul_lo_u16_e32 v3, 0x74, v3
	v_sub_u16_e32 v2, v2, v3
	v_lshlrev_b16_e32 v119, 5, v2
	v_lshlrev_b32_e32 v2, 2, v119
	v_mov_b32_e32 v3, v0
	v_lshl_add_u64 v[2:3], v[32:33], 0, v[2:3]
	s_movk_i32 s8, 0x3a00
	v_mad_u64_u32 v[46:47], s[8:9], v5, s8, v[2:3]
	global_load_dword v5, v[46:47], off
	v_add_u32_e32 v46, v7, v13
	s_and_b64 vcc, exec, s[0:1]
	v_or_b32_e32 v170, v58, v4
	s_movk_i32 s8, 0x3a00
	v_mad_u64_u32 v[168:169], s[8:9], v170, s8, v[2:3]
	global_load_dword v168, v[168:169], off
	s_waitcnt vmcnt(1)
	v_mul_f32_e32 v5, v45, v5
	ds_write_b32 v46, v5
	v_add_lshl_u32 v5, v8, v4, 2
	s_cbranch_vccnz .LBB0_132
	v_readlane_b32 s52, v252, 14
	v_readlane_b32 s62, v252, 24
	v_readlane_b32 s63, v252, 25
	v_readlane_b32 s53, v252, 15
	v_readlane_b32 s54, v252, 16
	v_readlane_b32 s55, v252, 17
	v_readlane_b32 s56, v252, 18
	v_readlane_b32 s57, v252, 19
	global_load_dword v44, v5, s[62:63] offset:8
	v_readlane_b32 s58, v252, 20
	v_readlane_b32 s59, v252, 21
	v_readlane_b32 s60, v252, 22
	v_readlane_b32 s61, v252, 23
	v_readlane_b32 s64, v252, 26
	v_readlane_b32 s65, v252, 27
	v_readlane_b32 s66, v252, 28
	v_readlane_b32 s67, v252, 29
.LBB0_132:
	v_add_u32_e32 v47, v7, v59
	v_mov_b32_e32 v45, 1.0
	s_and_b64 vcc, exec, s[0:1]
	v_or_b32_e32 v160, v60, v4
	s_movk_i32 s8, 0x3a00
	v_mad_u64_u32 v[160:161], s[8:9], v160, s8, v[2:3]
	global_load_dword v160, v[160:161], off
	s_waitcnt vmcnt(1)
	v_mul_f32_e32 v44, v44, v168
	ds_write_b32 v47, v44
	v_mov_b32_e32 v44, 1.0
	s_cbranch_vccnz .LBB0_134
	v_readlane_b32 s52, v252, 14
	v_readlane_b32 s62, v252, 24
	v_readlane_b32 s63, v252, 25
	v_readlane_b32 s53, v252, 15
	v_readlane_b32 s54, v252, 16
	v_readlane_b32 s55, v252, 17
	v_readlane_b32 s56, v252, 18
	v_readlane_b32 s57, v252, 19
	global_load_dword v44, v5, s[62:63] offset:16
	v_readlane_b32 s58, v252, 20
	v_readlane_b32 s59, v252, 21
	v_readlane_b32 s60, v252, 22
	v_readlane_b32 s61, v252, 23
	v_readlane_b32 s64, v252, 26
	v_readlane_b32 s65, v252, 27
	v_readlane_b32 s66, v252, 28
	v_readlane_b32 s67, v252, 29
.LBB0_134:
	v_add_u32_e32 v47, v7, v61
	s_and_b64 vcc, exec, s[0:1]
	v_or_b32_e32 v170, v62, v4
	s_movk_i32 s8, 0x3a00
	v_mad_u64_u32 v[168:169], s[8:9], v170, s8, v[2:3]
	global_load_dword v168, v[168:169], off
	s_waitcnt vmcnt(1)
	v_mul_f32_e32 v44, v44, v160
	ds_write_b32 v47, v44
	s_cbranch_vccnz .LBB0_136
	v_readlane_b32 s52, v252, 14
	v_readlane_b32 s62, v252, 24
	v_readlane_b32 s63, v252, 25
	v_readlane_b32 s53, v252, 15
	v_readlane_b32 s54, v252, 16
	v_readlane_b32 s55, v252, 17
	v_readlane_b32 s56, v252, 18
	v_readlane_b32 s57, v252, 19
	global_load_dword v45, v5, s[62:63] offset:24
	v_readlane_b32 s58, v252, 20
	v_readlane_b32 s59, v252, 21
	v_readlane_b32 s60, v252, 22
	v_readlane_b32 s61, v252, 23
	v_readlane_b32 s64, v252, 26
	v_readlane_b32 s65, v252, 27
	v_readlane_b32 s66, v252, 28
	v_readlane_b32 s67, v252, 29
.LBB0_136:
	v_add_u32_e32 v47, v7, v63
	v_mov_b32_e32 v44, 1.0
	s_and_b64 vcc, exec, s[0:1]
	v_or_b32_e32 v160, v64, v4
	s_movk_i32 s8, 0x3a00
	v_mad_u64_u32 v[160:161], s[8:9], v160, s8, v[2:3]
	global_load_dword v160, v[160:161], off
	s_waitcnt vmcnt(1)
	v_mul_f32_e32 v45, v45, v168
	ds_write_b32 v47, v45
	v_mov_b32_e32 v45, 1.0
	s_cbranch_vccnz .LBB0_138
	v_readlane_b32 s52, v252, 14
	v_readlane_b32 s62, v252, 24
	v_readlane_b32 s63, v252, 25
	v_readlane_b32 s53, v252, 15
	v_readlane_b32 s54, v252, 16
	v_readlane_b32 s55, v252, 17
	v_readlane_b32 s56, v252, 18
	v_readlane_b32 s57, v252, 19
	global_load_dword v45, v5, s[62:63] offset:32
	v_readlane_b32 s58, v252, 20
	v_readlane_b32 s59, v252, 21
	v_readlane_b32 s60, v252, 22
	v_readlane_b32 s61, v252, 23
	v_readlane_b32 s64, v252, 26
	v_readlane_b32 s65, v252, 27
	v_readlane_b32 s66, v252, 28
	v_readlane_b32 s67, v252, 29
.LBB0_138:
	v_add_u32_e32 v47, v7, v65
	s_and_b64 vcc, exec, s[0:1]
	v_or_b32_e32 v170, v66, v4
	s_movk_i32 s8, 0x3a00
	v_mad_u64_u32 v[168:169], s[8:9], v170, s8, v[2:3]
	global_load_dword v168, v[168:169], off
	s_waitcnt vmcnt(1)
	v_mul_f32_e32 v45, v45, v160
	ds_write_b32 v47, v45
	s_cbranch_vccnz .LBB0_140
	v_readlane_b32 s52, v252, 14
	v_readlane_b32 s62, v252, 24
	v_readlane_b32 s63, v252, 25
	v_readlane_b32 s53, v252, 15
	v_readlane_b32 s54, v252, 16
	v_readlane_b32 s55, v252, 17
	v_readlane_b32 s56, v252, 18
	v_readlane_b32 s57, v252, 19
	global_load_dword v44, v5, s[62:63] offset:40
	v_readlane_b32 s58, v252, 20
	v_readlane_b32 s59, v252, 21
	v_readlane_b32 s60, v252, 22
	v_readlane_b32 s61, v252, 23
	v_readlane_b32 s64, v252, 26
	v_readlane_b32 s65, v252, 27
	v_readlane_b32 s66, v252, 28
	v_readlane_b32 s67, v252, 29
.LBB0_140:
	v_add_u32_e32 v47, v7, v67
	v_mov_b32_e32 v45, 1.0
	s_and_b64 vcc, exec, s[0:1]
	v_or_b32_e32 v160, v68, v4
	s_movk_i32 s8, 0x3a00
	v_mad_u64_u32 v[160:161], s[8:9], v160, s8, v[2:3]
	global_load_dword v160, v[160:161], off
	s_waitcnt vmcnt(1)
	v_mul_f32_e32 v44, v44, v168
	ds_write_b32 v47, v44
	v_mov_b32_e32 v44, 1.0
	s_cbranch_vccnz .LBB0_142
	v_readlane_b32 s52, v252, 14
	v_readlane_b32 s62, v252, 24
	v_readlane_b32 s63, v252, 25
	v_readlane_b32 s53, v252, 15
	v_readlane_b32 s54, v252, 16
	v_readlane_b32 s55, v252, 17
	v_readlane_b32 s56, v252, 18
	v_readlane_b32 s57, v252, 19
	global_load_dword v44, v5, s[62:63] offset:48
	v_readlane_b32 s58, v252, 20
	v_readlane_b32 s59, v252, 21
	v_readlane_b32 s60, v252, 22
	v_readlane_b32 s61, v252, 23
	v_readlane_b32 s64, v252, 26
	v_readlane_b32 s65, v252, 27
	v_readlane_b32 s66, v252, 28
	v_readlane_b32 s67, v252, 29
.LBB0_142:
	v_add_u32_e32 v47, v7, v69
	s_and_b64 vcc, exec, s[0:1]
	v_or_b32_e32 v170, v70, v4
	s_movk_i32 s8, 0x3a00
	v_mad_u64_u32 v[168:169], s[8:9], v170, s8, v[2:3]
	global_load_dword v168, v[168:169], off
	s_waitcnt vmcnt(1)
	v_mul_f32_e32 v44, v44, v160
	ds_write_b32 v47, v44
	s_cbranch_vccnz .LBB0_144
	v_readlane_b32 s52, v252, 14
	v_readlane_b32 s62, v252, 24
	v_readlane_b32 s63, v252, 25
	v_readlane_b32 s53, v252, 15
	v_readlane_b32 s54, v252, 16
	v_readlane_b32 s55, v252, 17
	v_readlane_b32 s56, v252, 18
	v_readlane_b32 s57, v252, 19
	global_load_dword v45, v5, s[62:63] offset:56
	v_readlane_b32 s58, v252, 20
	v_readlane_b32 s59, v252, 21
	v_readlane_b32 s60, v252, 22
	v_readlane_b32 s61, v252, 23
	v_readlane_b32 s64, v252, 26
	v_readlane_b32 s65, v252, 27
	v_readlane_b32 s66, v252, 28
	v_readlane_b32 s67, v252, 29
.LBB0_144:
	v_add_u32_e32 v47, v7, v71
	v_mov_b32_e32 v44, 1.0
	s_and_b64 vcc, exec, s[0:1]
	v_or_b32_e32 v160, v72, v4
	s_movk_i32 s8, 0x3a00
	v_mad_u64_u32 v[160:161], s[8:9], v160, s8, v[2:3]
	global_load_dword v160, v[160:161], off
	s_waitcnt vmcnt(1)
	v_mul_f32_e32 v45, v45, v168
	ds_write_b32 v47, v45
	v_mov_b32_e32 v45, 1.0
	s_cbranch_vccnz .LBB0_146
	v_readlane_b32 s52, v252, 14
	v_readlane_b32 s62, v252, 24
	v_readlane_b32 s63, v252, 25
	v_readlane_b32 s53, v252, 15
	v_readlane_b32 s54, v252, 16
	v_readlane_b32 s55, v252, 17
	v_readlane_b32 s56, v252, 18
	v_readlane_b32 s57, v252, 19
	global_load_dword v45, v5, s[62:63] offset:64
	v_readlane_b32 s58, v252, 20
	v_readlane_b32 s59, v252, 21
	v_readlane_b32 s60, v252, 22
	v_readlane_b32 s61, v252, 23
	v_readlane_b32 s64, v252, 26
	v_readlane_b32 s65, v252, 27
	v_readlane_b32 s66, v252, 28
	v_readlane_b32 s67, v252, 29
.LBB0_146:
	v_add_u32_e32 v47, v7, v73
	s_and_b64 vcc, exec, s[0:1]
	v_or_b32_e32 v170, v74, v4
	s_movk_i32 s8, 0x3a00
	v_mad_u64_u32 v[168:169], s[8:9], v170, s8, v[2:3]
	global_load_dword v168, v[168:169], off
	s_waitcnt vmcnt(1)
	v_mul_f32_e32 v45, v45, v160
	ds_write_b32 v47, v45
	s_cbranch_vccnz .LBB0_148
	v_readlane_b32 s52, v252, 14
	v_readlane_b32 s62, v252, 24
	v_readlane_b32 s63, v252, 25
	v_readlane_b32 s53, v252, 15
	v_readlane_b32 s54, v252, 16
	v_readlane_b32 s55, v252, 17
	v_readlane_b32 s56, v252, 18
	v_readlane_b32 s57, v252, 19
	global_load_dword v44, v5, s[62:63] offset:72
	v_readlane_b32 s58, v252, 20
	v_readlane_b32 s59, v252, 21
	v_readlane_b32 s60, v252, 22
	v_readlane_b32 s61, v252, 23
	v_readlane_b32 s64, v252, 26
	v_readlane_b32 s65, v252, 27
	v_readlane_b32 s66, v252, 28
	v_readlane_b32 s67, v252, 29
.LBB0_148:
	v_add_u32_e32 v47, v7, v75
	v_mov_b32_e32 v45, 1.0
	s_and_b64 vcc, exec, s[0:1]
	v_or_b32_e32 v160, v76, v4
	s_movk_i32 s8, 0x3a00
	v_mad_u64_u32 v[160:161], s[8:9], v160, s8, v[2:3]
	global_load_dword v160, v[160:161], off
	s_waitcnt vmcnt(1)
	v_mul_f32_e32 v44, v44, v168
	ds_write_b32 v47, v44
	v_mov_b32_e32 v44, 1.0
	s_cbranch_vccnz .LBB0_150
	v_readlane_b32 s52, v252, 14
	v_readlane_b32 s62, v252, 24
	v_readlane_b32 s63, v252, 25
	v_readlane_b32 s53, v252, 15
	v_readlane_b32 s54, v252, 16
	v_readlane_b32 s55, v252, 17
	v_readlane_b32 s56, v252, 18
	v_readlane_b32 s57, v252, 19
	global_load_dword v44, v5, s[62:63] offset:80
	v_readlane_b32 s58, v252, 20
	v_readlane_b32 s59, v252, 21
	v_readlane_b32 s60, v252, 22
	v_readlane_b32 s61, v252, 23
	v_readlane_b32 s64, v252, 26
	v_readlane_b32 s65, v252, 27
	v_readlane_b32 s66, v252, 28
	v_readlane_b32 s67, v252, 29
.LBB0_150:
	v_add_u32_e32 v47, v7, v77
	s_and_b64 vcc, exec, s[0:1]
	v_or_b32_e32 v170, v78, v4
	s_movk_i32 s8, 0x3a00
	v_mad_u64_u32 v[168:169], s[8:9], v170, s8, v[2:3]
	global_load_dword v168, v[168:169], off
	s_waitcnt vmcnt(1)
	v_mul_f32_e32 v44, v44, v160
	ds_write_b32 v47, v44
	s_cbranch_vccnz .LBB0_152
	v_readlane_b32 s52, v252, 14
	v_readlane_b32 s62, v252, 24
	v_readlane_b32 s63, v252, 25
	v_readlane_b32 s53, v252, 15
	v_readlane_b32 s54, v252, 16
	v_readlane_b32 s55, v252, 17
	v_readlane_b32 s56, v252, 18
	v_readlane_b32 s57, v252, 19
	global_load_dword v45, v5, s[62:63] offset:88
	v_readlane_b32 s58, v252, 20
	v_readlane_b32 s59, v252, 21
	v_readlane_b32 s60, v252, 22
	v_readlane_b32 s61, v252, 23
	v_readlane_b32 s64, v252, 26
	v_readlane_b32 s65, v252, 27
	v_readlane_b32 s66, v252, 28
	v_readlane_b32 s67, v252, 29
.LBB0_152:
	v_add_u32_e32 v47, v7, v79
	v_mov_b32_e32 v44, 1.0
	s_and_b64 vcc, exec, s[0:1]
	v_or_b32_e32 v160, v80, v4
	s_movk_i32 s8, 0x3a00
	v_mad_u64_u32 v[160:161], s[8:9], v160, s8, v[2:3]
	global_load_dword v160, v[160:161], off
	s_waitcnt vmcnt(1)
	v_mul_f32_e32 v45, v45, v168
	ds_write_b32 v47, v45
	v_mov_b32_e32 v45, 1.0
	s_cbranch_vccnz .LBB0_154
	v_readlane_b32 s52, v252, 14
	v_readlane_b32 s62, v252, 24
	v_readlane_b32 s63, v252, 25
	v_readlane_b32 s53, v252, 15
	v_readlane_b32 s54, v252, 16
	v_readlane_b32 s55, v252, 17
	v_readlane_b32 s56, v252, 18
	v_readlane_b32 s57, v252, 19
	global_load_dword v45, v5, s[62:63] offset:96
	v_readlane_b32 s58, v252, 20
	v_readlane_b32 s59, v252, 21
	v_readlane_b32 s60, v252, 22
	v_readlane_b32 s61, v252, 23
	v_readlane_b32 s64, v252, 26
	v_readlane_b32 s65, v252, 27
	v_readlane_b32 s66, v252, 28
	v_readlane_b32 s67, v252, 29
.LBB0_154:
	v_add_u32_e32 v47, v7, v81
	s_and_b64 vcc, exec, s[0:1]
	v_or_b32_e32 v170, v82, v4
	s_movk_i32 s8, 0x3a00
	v_mad_u64_u32 v[168:169], s[8:9], v170, s8, v[2:3]
	global_load_dword v168, v[168:169], off
	s_waitcnt vmcnt(1)
	v_mul_f32_e32 v45, v45, v160
	ds_write_b32 v47, v45
	s_cbranch_vccnz .LBB0_156
	v_readlane_b32 s52, v252, 14
	v_readlane_b32 s62, v252, 24
	v_readlane_b32 s63, v252, 25
	v_readlane_b32 s53, v252, 15
	v_readlane_b32 s54, v252, 16
	v_readlane_b32 s55, v252, 17
	v_readlane_b32 s56, v252, 18
	v_readlane_b32 s57, v252, 19
	global_load_dword v44, v5, s[62:63] offset:104
	v_readlane_b32 s58, v252, 20
	v_readlane_b32 s59, v252, 21
	v_readlane_b32 s60, v252, 22
	v_readlane_b32 s61, v252, 23
	v_readlane_b32 s64, v252, 26
	v_readlane_b32 s65, v252, 27
	v_readlane_b32 s66, v252, 28
	v_readlane_b32 s67, v252, 29
.LBB0_156:
	v_add_u32_e32 v47, v7, v83
	v_mov_b32_e32 v45, 1.0
	s_and_b64 vcc, exec, s[0:1]
	v_or_b32_e32 v160, v84, v4
	s_movk_i32 s8, 0x3a00
	v_mad_u64_u32 v[160:161], s[8:9], v160, s8, v[2:3]
	global_load_dword v160, v[160:161], off
	s_waitcnt vmcnt(1)
	v_mul_f32_e32 v44, v44, v168
	ds_write_b32 v47, v44
	v_mov_b32_e32 v44, 1.0
	s_cbranch_vccnz .LBB0_158
	v_readlane_b32 s52, v252, 14
	v_readlane_b32 s62, v252, 24
	v_readlane_b32 s63, v252, 25
	v_readlane_b32 s53, v252, 15
	v_readlane_b32 s54, v252, 16
	v_readlane_b32 s55, v252, 17
	v_readlane_b32 s56, v252, 18
	v_readlane_b32 s57, v252, 19
	global_load_dword v44, v5, s[62:63] offset:112
	v_readlane_b32 s58, v252, 20
	v_readlane_b32 s59, v252, 21
	v_readlane_b32 s60, v252, 22
	v_readlane_b32 s61, v252, 23
	v_readlane_b32 s64, v252, 26
	v_readlane_b32 s65, v252, 27
	v_readlane_b32 s66, v252, 28
	v_readlane_b32 s67, v252, 29
.LBB0_158:
	v_add_u32_e32 v47, v7, v85
	s_and_b64 vcc, exec, s[0:1]
	v_or_b32_e32 v170, v86, v4
	s_movk_i32 s8, 0x3a00
	v_mad_u64_u32 v[168:169], s[8:9], v170, s8, v[2:3]
	global_load_dword v168, v[168:169], off
	s_waitcnt vmcnt(1)
	v_mul_f32_e32 v44, v44, v160
	ds_write_b32 v47, v44
	s_cbranch_vccnz .LBB0_160
	v_readlane_b32 s52, v252, 14
	v_readlane_b32 s62, v252, 24
	v_readlane_b32 s63, v252, 25
	v_readlane_b32 s53, v252, 15
	v_readlane_b32 s54, v252, 16
	v_readlane_b32 s55, v252, 17
	v_readlane_b32 s56, v252, 18
	v_readlane_b32 s57, v252, 19
	global_load_dword v45, v5, s[62:63] offset:120
	v_readlane_b32 s58, v252, 20
	v_readlane_b32 s59, v252, 21
	v_readlane_b32 s60, v252, 22
	v_readlane_b32 s61, v252, 23
	v_readlane_b32 s64, v252, 26
	v_readlane_b32 s65, v252, 27
	v_readlane_b32 s66, v252, 28
	v_readlane_b32 s67, v252, 29
.LBB0_160:
	v_add_u32_e32 v47, v7, v87
	v_mov_b32_e32 v44, 1.0
	s_and_b64 vcc, exec, s[0:1]
	v_or_b32_e32 v160, v88, v4
	s_movk_i32 s8, 0x3a00
	v_mad_u64_u32 v[160:161], s[8:9], v160, s8, v[2:3]
	global_load_dword v160, v[160:161], off
	s_waitcnt vmcnt(1)
	v_mul_f32_e32 v45, v45, v168
	ds_write_b32 v47, v45
	v_mov_b32_e32 v45, 1.0
	s_cbranch_vccnz .LBB0_162
	v_readlane_b32 s52, v252, 14
	v_readlane_b32 s62, v252, 24
	v_readlane_b32 s63, v252, 25
	v_readlane_b32 s53, v252, 15
	v_readlane_b32 s54, v252, 16
	v_readlane_b32 s55, v252, 17
	v_readlane_b32 s56, v252, 18
	v_readlane_b32 s57, v252, 19
	global_load_dword v45, v5, s[62:63] offset:128
	v_readlane_b32 s58, v252, 20
	v_readlane_b32 s59, v252, 21
	v_readlane_b32 s60, v252, 22
	v_readlane_b32 s61, v252, 23
	v_readlane_b32 s64, v252, 26
	v_readlane_b32 s65, v252, 27
	v_readlane_b32 s66, v252, 28
	v_readlane_b32 s67, v252, 29
.LBB0_162:
	v_add_u32_e32 v47, v7, v89
	s_and_b64 vcc, exec, s[0:1]
	v_or_b32_e32 v170, v90, v4
	s_movk_i32 s8, 0x3a00
	v_mad_u64_u32 v[168:169], s[8:9], v170, s8, v[2:3]
	global_load_dword v168, v[168:169], off
	s_waitcnt vmcnt(1)
	v_mul_f32_e32 v45, v45, v160
	ds_write_b32 v47, v45
	s_cbranch_vccnz .LBB0_164
	v_readlane_b32 s52, v252, 14
	v_readlane_b32 s62, v252, 24
	v_readlane_b32 s63, v252, 25
	v_readlane_b32 s53, v252, 15
	v_readlane_b32 s54, v252, 16
	v_readlane_b32 s55, v252, 17
	v_readlane_b32 s56, v252, 18
	v_readlane_b32 s57, v252, 19
	global_load_dword v44, v5, s[62:63] offset:136
	v_readlane_b32 s58, v252, 20
	v_readlane_b32 s59, v252, 21
	v_readlane_b32 s60, v252, 22
	v_readlane_b32 s61, v252, 23
	v_readlane_b32 s64, v252, 26
	v_readlane_b32 s65, v252, 27
	v_readlane_b32 s66, v252, 28
	v_readlane_b32 s67, v252, 29
.LBB0_164:
	v_add_u32_e32 v47, v7, v91
	v_mov_b32_e32 v45, 1.0
	s_and_b64 vcc, exec, s[0:1]
	v_or_b32_e32 v160, v92, v4
	s_movk_i32 s8, 0x3a00
	v_mad_u64_u32 v[160:161], s[8:9], v160, s8, v[2:3]
	global_load_dword v160, v[160:161], off
	s_waitcnt vmcnt(1)
	v_mul_f32_e32 v44, v44, v168
	ds_write_b32 v47, v44
	v_mov_b32_e32 v44, 1.0
	s_cbranch_vccnz .LBB0_166
	v_readlane_b32 s52, v252, 14
	v_readlane_b32 s62, v252, 24
	v_readlane_b32 s63, v252, 25
	v_readlane_b32 s53, v252, 15
	v_readlane_b32 s54, v252, 16
	v_readlane_b32 s55, v252, 17
	v_readlane_b32 s56, v252, 18
	v_readlane_b32 s57, v252, 19
	global_load_dword v44, v5, s[62:63] offset:144
	v_readlane_b32 s58, v252, 20
	v_readlane_b32 s59, v252, 21
	v_readlane_b32 s60, v252, 22
	v_readlane_b32 s61, v252, 23
	v_readlane_b32 s64, v252, 26
	v_readlane_b32 s65, v252, 27
	v_readlane_b32 s66, v252, 28
	v_readlane_b32 s67, v252, 29
.LBB0_166:
	v_add_u32_e32 v47, v7, v93
	s_and_b64 vcc, exec, s[0:1]
	v_or_b32_e32 v170, v94, v4
	s_movk_i32 s8, 0x3a00
	v_mad_u64_u32 v[168:169], s[8:9], v170, s8, v[2:3]
	global_load_dword v168, v[168:169], off
	s_waitcnt vmcnt(1)
	v_mul_f32_e32 v44, v44, v160
	ds_write_b32 v47, v44
	s_cbranch_vccnz .LBB0_168
	v_readlane_b32 s52, v252, 14
	v_readlane_b32 s62, v252, 24
	v_readlane_b32 s63, v252, 25
	v_readlane_b32 s53, v252, 15
	v_readlane_b32 s54, v252, 16
	v_readlane_b32 s55, v252, 17
	v_readlane_b32 s56, v252, 18
	v_readlane_b32 s57, v252, 19
	global_load_dword v45, v5, s[62:63] offset:152
	v_readlane_b32 s58, v252, 20
	v_readlane_b32 s59, v252, 21
	v_readlane_b32 s60, v252, 22
	v_readlane_b32 s61, v252, 23
	v_readlane_b32 s64, v252, 26
	v_readlane_b32 s65, v252, 27
	v_readlane_b32 s66, v252, 28
	v_readlane_b32 s67, v252, 29
.LBB0_168:
	v_add_u32_e32 v47, v7, v95
	v_mov_b32_e32 v44, 1.0
	s_and_b64 vcc, exec, s[0:1]
	v_or_b32_e32 v160, v96, v4
	s_movk_i32 s8, 0x3a00
	v_mad_u64_u32 v[160:161], s[8:9], v160, s8, v[2:3]
	global_load_dword v160, v[160:161], off
	s_waitcnt vmcnt(1)
	v_mul_f32_e32 v45, v45, v168
	ds_write_b32 v47, v45
	v_mov_b32_e32 v45, 1.0
	s_cbranch_vccnz .LBB0_170
	v_readlane_b32 s52, v252, 14
	v_readlane_b32 s62, v252, 24
	v_readlane_b32 s63, v252, 25
	v_readlane_b32 s53, v252, 15
	v_readlane_b32 s54, v252, 16
	v_readlane_b32 s55, v252, 17
	v_readlane_b32 s56, v252, 18
	v_readlane_b32 s57, v252, 19
	global_load_dword v45, v5, s[62:63] offset:160
	v_readlane_b32 s58, v252, 20
	v_readlane_b32 s59, v252, 21
	v_readlane_b32 s60, v252, 22
	v_readlane_b32 s61, v252, 23
	v_readlane_b32 s64, v252, 26
	v_readlane_b32 s65, v252, 27
	v_readlane_b32 s66, v252, 28
	v_readlane_b32 s67, v252, 29
.LBB0_170:
	v_add_u32_e32 v47, v7, v97
	s_and_b64 vcc, exec, s[0:1]
	v_or_b32_e32 v170, v98, v4
	s_movk_i32 s8, 0x3a00
	v_mad_u64_u32 v[168:169], s[8:9], v170, s8, v[2:3]
	global_load_dword v168, v[168:169], off
	s_waitcnt vmcnt(1)
	v_mul_f32_e32 v45, v45, v160
	ds_write_b32 v47, v45
	s_cbranch_vccnz .LBB0_172
	v_readlane_b32 s52, v252, 14
	v_readlane_b32 s62, v252, 24
	v_readlane_b32 s63, v252, 25
	v_readlane_b32 s53, v252, 15
	v_readlane_b32 s54, v252, 16
	v_readlane_b32 s55, v252, 17
	v_readlane_b32 s56, v252, 18
	v_readlane_b32 s57, v252, 19
	global_load_dword v44, v5, s[62:63] offset:168
	v_readlane_b32 s58, v252, 20
	v_readlane_b32 s59, v252, 21
	v_readlane_b32 s60, v252, 22
	v_readlane_b32 s61, v252, 23
	v_readlane_b32 s64, v252, 26
	v_readlane_b32 s65, v252, 27
	v_readlane_b32 s66, v252, 28
	v_readlane_b32 s67, v252, 29
.LBB0_172:
	v_add_u32_e32 v47, v7, v99
	v_mov_b32_e32 v45, 1.0
	s_and_b64 vcc, exec, s[0:1]
	v_or_b32_e32 v160, v100, v4
	s_movk_i32 s8, 0x3a00
	v_mad_u64_u32 v[160:161], s[8:9], v160, s8, v[2:3]
	global_load_dword v160, v[160:161], off
	s_waitcnt vmcnt(1)
	v_mul_f32_e32 v44, v44, v168
	ds_write_b32 v47, v44
	v_mov_b32_e32 v44, 1.0
	s_cbranch_vccnz .LBB0_174
	v_readlane_b32 s52, v252, 14
	v_readlane_b32 s62, v252, 24
	v_readlane_b32 s63, v252, 25
	v_readlane_b32 s53, v252, 15
	v_readlane_b32 s54, v252, 16
	v_readlane_b32 s55, v252, 17
	v_readlane_b32 s56, v252, 18
	v_readlane_b32 s57, v252, 19
	global_load_dword v44, v5, s[62:63] offset:176
	v_readlane_b32 s58, v252, 20
	v_readlane_b32 s59, v252, 21
	v_readlane_b32 s60, v252, 22
	v_readlane_b32 s61, v252, 23
	v_readlane_b32 s64, v252, 26
	v_readlane_b32 s65, v252, 27
	v_readlane_b32 s66, v252, 28
	v_readlane_b32 s67, v252, 29
.LBB0_174:
	v_add_u32_e32 v47, v7, v101
	s_and_b64 vcc, exec, s[0:1]
	v_or_b32_e32 v170, v102, v4
	s_movk_i32 s8, 0x3a00
	v_mad_u64_u32 v[168:169], s[8:9], v170, s8, v[2:3]
	global_load_dword v170, v[168:169], off
	s_waitcnt vmcnt(1)
	v_mul_f32_e32 v44, v44, v160
	ds_write_b32 v47, v44
	s_cbranch_vccnz .LBB0_176
	v_readlane_b32 s52, v252, 14
	v_readlane_b32 s62, v252, 24
	v_readlane_b32 s63, v252, 25
	v_readlane_b32 s53, v252, 15
	v_readlane_b32 s54, v252, 16
	v_readlane_b32 s55, v252, 17
	v_readlane_b32 s56, v252, 18
	v_readlane_b32 s57, v252, 19
	global_load_dword v45, v5, s[62:63] offset:184
	v_readlane_b32 s58, v252, 20
	v_readlane_b32 s59, v252, 21
	v_readlane_b32 s60, v252, 22
	v_readlane_b32 s61, v252, 23
	v_readlane_b32 s64, v252, 26
	v_readlane_b32 s65, v252, 27
	v_readlane_b32 s66, v252, 28
	v_readlane_b32 s67, v252, 29
.LBB0_176:
	v_add_u32_e32 v47, v7, v103
	v_mov_b32_e32 v46, 1.0
	s_and_b64 vcc, exec, s[0:1]
	v_or_b32_e32 v162, v104, v4
	s_movk_i32 s8, 0x3a00
	v_mad_u64_u32 v[160:161], s[8:9], v162, s8, v[2:3]
	global_load_dword v163, v[160:161], off
	s_waitcnt vmcnt(1)
	v_mul_f32_e32 v44, v45, v170
	v_mov_b32_e32 v45, 1.0
	ds_write_b32 v47, v44
	s_cbranch_vccnz .LBB0_178
	v_readlane_b32 s52, v252, 14
	v_readlane_b32 s62, v252, 24
	v_readlane_b32 s63, v252, 25
	v_readlane_b32 s53, v252, 15
	v_readlane_b32 s54, v252, 16
	v_readlane_b32 s55, v252, 17
	v_readlane_b32 s56, v252, 18
	v_readlane_b32 s57, v252, 19
	global_load_dword v45, v5, s[62:63] offset:192
	v_readlane_b32 s58, v252, 20
	v_readlane_b32 s59, v252, 21
	v_readlane_b32 s60, v252, 22
	v_readlane_b32 s61, v252, 23
	v_readlane_b32 s64, v252, 26
	v_readlane_b32 s65, v252, 27
	v_readlane_b32 s66, v252, 28
	v_readlane_b32 s67, v252, 29
.LBB0_178:
	v_add_u32_e32 v44, v7, v105
	s_and_b64 vcc, exec, s[0:1]
	v_or_b32_e32 v170, v106, v4
	s_movk_i32 s8, 0x3a00
	v_mad_u64_u32 v[168:169], s[8:9], v170, s8, v[2:3]
	global_load_dword v171, v[168:169], off
	s_waitcnt vmcnt(1)
	v_mul_f32_e32 v45, v45, v163
	ds_write_b32 v44, v45
	s_cbranch_vccnz .LBB0_180
	v_readlane_b32 s52, v252, 14
	v_readlane_b32 s62, v252, 24
	v_readlane_b32 s63, v252, 25
	v_readlane_b32 s53, v252, 15
	v_readlane_b32 s54, v252, 16
	v_readlane_b32 s55, v252, 17
	v_readlane_b32 s56, v252, 18
	v_readlane_b32 s57, v252, 19
	global_load_dword v46, v5, s[62:63] offset:200
	v_readlane_b32 s58, v252, 20
	v_readlane_b32 s59, v252, 21
	v_readlane_b32 s60, v252, 22
	v_readlane_b32 s61, v252, 23
	v_readlane_b32 s64, v252, 26
	v_readlane_b32 s65, v252, 27
	v_readlane_b32 s66, v252, 28
	v_readlane_b32 s67, v252, 29
.LBB0_180:
	v_mov_b32_e32 v45, 1.0
	s_and_b64 vcc, exec, s[0:1]
	v_or_b32_e32 v162, v107, v4
	s_movk_i32 s8, 0x3a00
	v_mad_u64_u32 v[160:161], s[8:9], v162, s8, v[2:3]
	global_load_dword v162, v[160:161], off
	s_waitcnt vmcnt(1)
	v_mul_f32_e32 v46, v46, v171
	ds_write_b32 v44, v46 offset:264
	v_mov_b32_e32 v46, 1.0
	s_cbranch_vccnz .LBB0_182
	v_readlane_b32 s52, v252, 14
	v_readlane_b32 s62, v252, 24
	v_readlane_b32 s63, v252, 25
	v_readlane_b32 s53, v252, 15
	v_readlane_b32 s54, v252, 16
	v_readlane_b32 s55, v252, 17
	v_readlane_b32 s56, v252, 18
	v_readlane_b32 s57, v252, 19
	global_load_dword v46, v5, s[62:63] offset:208
	v_readlane_b32 s58, v252, 20
	v_readlane_b32 s59, v252, 21
	v_readlane_b32 s60, v252, 22
	v_readlane_b32 s61, v252, 23
	v_readlane_b32 s64, v252, 26
	v_readlane_b32 s65, v252, 27
	v_readlane_b32 s66, v252, 28
	v_readlane_b32 s67, v252, 29
.LBB0_182:
	s_and_b64 vcc, exec, s[0:1]
	v_or_b32_e32 v168, v108, v4
	s_movk_i32 s8, 0x3a00
	v_mad_u64_u32 v[168:169], s[8:9], v168, s8, v[2:3]
	global_load_dword v169, v[168:169], off
	s_waitcnt vmcnt(1)
	v_mul_f32_e32 v46, v46, v162
	ds_write_b32 v44, v46 offset:528
	s_cbranch_vccnz .LBB0_184
	v_readlane_b32 s52, v252, 14
	v_readlane_b32 s62, v252, 24
	v_readlane_b32 s63, v252, 25
	v_readlane_b32 s53, v252, 15
	v_readlane_b32 s54, v252, 16
	v_readlane_b32 s55, v252, 17
	v_readlane_b32 s56, v252, 18
	v_readlane_b32 s57, v252, 19
	global_load_dword v45, v5, s[62:63] offset:216
	v_readlane_b32 s58, v252, 20
	v_readlane_b32 s59, v252, 21
	v_readlane_b32 s60, v252, 22
	v_readlane_b32 s61, v252, 23
	v_readlane_b32 s64, v252, 26
	v_readlane_b32 s65, v252, 27
	v_readlane_b32 s66, v252, 28
	v_readlane_b32 s67, v252, 29
.LBB0_184:
	v_mov_b32_e32 v46, 1.0
	s_and_b64 vcc, exec, s[0:1]
	v_or_b32_e32 v162, v109, v4
	s_movk_i32 s8, 0x3a00
	v_mad_u64_u32 v[160:161], s[8:9], v162, s8, v[2:3]
	global_load_dword v162, v[160:161], off
	s_waitcnt vmcnt(1)
	v_mul_f32_e32 v45, v45, v169
	ds_write_b32 v44, v45 offset:792
	v_mov_b32_e32 v45, 1.0
	s_cbranch_vccnz .LBB0_186
	v_readlane_b32 s52, v252, 14
	v_readlane_b32 s62, v252, 24
	v_readlane_b32 s63, v252, 25
	v_readlane_b32 s53, v252, 15
	v_readlane_b32 s54, v252, 16
	v_readlane_b32 s55, v252, 17
	v_readlane_b32 s56, v252, 18
	v_readlane_b32 s57, v252, 19
	global_load_dword v45, v5, s[62:63] offset:224
	v_readlane_b32 s58, v252, 20
	v_readlane_b32 s59, v252, 21
	v_readlane_b32 s60, v252, 22
	v_readlane_b32 s61, v252, 23
	v_readlane_b32 s64, v252, 26
	v_readlane_b32 s65, v252, 27
	v_readlane_b32 s66, v252, 28
	v_readlane_b32 s67, v252, 29
.LBB0_186:
	s_and_b64 vcc, exec, s[0:1]
	v_or_b32_e32 v170, v110, v4
	s_movk_i32 s8, 0x3a00
	v_mad_u64_u32 v[168:169], s[8:9], v170, s8, v[2:3]
	global_load_dword v171, v[168:169], off
	s_waitcnt vmcnt(1)
	v_mul_f32_e32 v45, v45, v162
	ds_write_b32 v44, v45 offset:1056
	s_cbranch_vccnz .LBB0_188
	v_readlane_b32 s52, v252, 14
	v_readlane_b32 s62, v252, 24
	v_readlane_b32 s63, v252, 25
	v_readlane_b32 s53, v252, 15
	v_readlane_b32 s54, v252, 16
	v_readlane_b32 s55, v252, 17
	v_readlane_b32 s56, v252, 18
	v_readlane_b32 s57, v252, 19
	global_load_dword v46, v5, s[62:63] offset:232
	v_readlane_b32 s58, v252, 20
	v_readlane_b32 s59, v252, 21
	v_readlane_b32 s60, v252, 22
	v_readlane_b32 s61, v252, 23
	v_readlane_b32 s64, v252, 26
	v_readlane_b32 s65, v252, 27
	v_readlane_b32 s66, v252, 28
	v_readlane_b32 s67, v252, 29
.LBB0_188:
	v_mov_b32_e32 v45, 1.0
	s_and_b64 vcc, exec, s[0:1]
	v_or_b32_e32 v162, v111, v4
	s_movk_i32 s8, 0x3a00
	v_mad_u64_u32 v[160:161], s[8:9], v162, s8, v[2:3]
	global_load_dword v162, v[160:161], off
	s_waitcnt vmcnt(1)
	v_mul_f32_e32 v46, v46, v171
	ds_write_b32 v44, v46 offset:1320
	v_mov_b32_e32 v46, 1.0
	s_cbranch_vccnz .LBB0_190
	v_readlane_b32 s52, v252, 14
	v_readlane_b32 s62, v252, 24
	v_readlane_b32 s63, v252, 25
	v_readlane_b32 s53, v252, 15
	v_readlane_b32 s54, v252, 16
	v_readlane_b32 s55, v252, 17
	v_readlane_b32 s56, v252, 18
	v_readlane_b32 s57, v252, 19
	global_load_dword v46, v5, s[62:63] offset:240
	v_readlane_b32 s58, v252, 20
	v_readlane_b32 s59, v252, 21
	v_readlane_b32 s60, v252, 22
	v_readlane_b32 s61, v252, 23
	v_readlane_b32 s64, v252, 26
	v_readlane_b32 s65, v252, 27
	v_readlane_b32 s66, v252, 28
	v_readlane_b32 s67, v252, 29
.LBB0_190:
	s_and_b64 vcc, exec, s[0:1]
	v_or_b32_e32 v170, v112, v4
	s_movk_i32 s0, 0x3a00
	v_mad_u64_u32 v[168:169], s[0:1], v170, s0, v[2:3]
	global_load_dword v168, v[168:169], off
	s_waitcnt vmcnt(1)
	v_mul_f32_e32 v46, v46, v162
	ds_write_b32 v44, v46 offset:1584
	s_cbranch_vccnz .LBB0_192
	v_readlane_b32 s52, v252, 14
	v_readlane_b32 s62, v252, 24
	v_readlane_b32 s63, v252, 25
	v_readlane_b32 s53, v252, 15
	v_readlane_b32 s54, v252, 16
	v_readlane_b32 s55, v252, 17
	v_readlane_b32 s56, v252, 18
	v_readlane_b32 s57, v252, 19
	global_load_dword v45, v5, s[62:63] offset:248
	v_readlane_b32 s58, v252, 20
	v_readlane_b32 s59, v252, 21
	v_readlane_b32 s60, v252, 22
	v_readlane_b32 s61, v252, 23
	v_readlane_b32 s64, v252, 26
	v_readlane_b32 s65, v252, 27
	v_readlane_b32 s66, v252, 28
	v_readlane_b32 s67, v252, 29
.LBB0_192:
	v_mov_b32_e32 v3, v0
	v_mov_b32_e32 v125, v0
	s_waitcnt vmcnt(0)
	v_mul_f32_e32 v2, v45, v168
	ds_write_b32 v44, v2 offset:1848
	s_waitcnt lgkmcnt(0)
	ds_read2_b32 v[46:47], v114 offset0:33 offset1:41
	ds_read2_b32 v[48:49], v114 offset1:8
	v_lshlrev_b32_e32 v2, 1, v4
	ds_read2_b32 v[50:51], v114 offset0:66 offset1:74
	ds_read2_b32 v[52:53], v114 offset0:99 offset1:107
	v_lshl_add_u64 v[44:45], v[18:19], 0, v[2:3]
	s_waitcnt lgkmcnt(3)
	v_bfe_u32 v3, v46, 16, 1
	s_waitcnt lgkmcnt(2)
	v_bfe_u32 v2, v48, 16, 1
	v_add3_u32 v2, v48, v2, s51
	v_lshrrev_b32_e32 v2, 16, v2
	v_add3_u32 v3, v46, v3, s51
	ds_read2_b32 v[54:55], v114 offset0:132 offset1:140
	ds_read2_b32 v[56:57], v114 offset0:165 offset1:173
	v_and_or_b32 v2, v3, s33, v2
	s_waitcnt lgkmcnt(3)
	v_bfe_u32 v3, v50, 16, 1
	v_add3_u32 v3, v50, v3, s51
	s_waitcnt lgkmcnt(2)
	v_bfe_u32 v4, v52, 16, 1
	v_lshrrev_b32_e32 v3, 16, v3
	v_add3_u32 v4, v52, v4, s51
	ds_read2_b32 v[120:121], v114 offset0:198 offset1:206
	ds_read2_b32 v[122:123], v114 offset0:231 offset1:239
	v_and_or_b32 v3, v4, s33, v3
	s_waitcnt lgkmcnt(3)
	v_bfe_u32 v4, v54, 16, 1
	v_add3_u32 v4, v54, v4, s51
	s_waitcnt lgkmcnt(2)
	v_bfe_u32 v5, v56, 16, 1
	v_lshrrev_b32_e32 v4, 16, v4
	v_add3_u32 v5, v56, v5, s51
	v_and_or_b32 v4, v5, s33, v4
	s_waitcnt lgkmcnt(1)
	v_bfe_u32 v5, v120, 16, 1
	v_add3_u32 v5, v120, v5, s51
	s_waitcnt lgkmcnt(0)
	v_bfe_u32 v46, v122, 16, 1
	v_lshrrev_b32_e32 v5, 16, v5
	v_add3_u32 v46, v122, v46, s51
	v_and_or_b32 v5, v46, s33, v5
	v_or_b32_e32 v46, v113, v119
	v_lshlrev_b32_e32 v124, 11, v46
	v_lshl_add_u64 v[124:125], v[44:45], 0, v[124:125]
	global_store_dwordx4 v[124:125], v[2:5], off
	v_bfe_u32 v46, v123, 16, 1
	v_add3_u32 v46, v123, v46, s51
	v_bfe_u32 v2, v49, 16, 1
	v_add3_u32 v2, v49, v2, s51
	v_bfe_u32 v3, v47, 16, 1
	v_lshrrev_b32_e32 v2, 16, v2
	v_add3_u32 v3, v47, v3, s51
	v_and_or_b32 v2, v3, s33, v2
	v_bfe_u32 v3, v51, 16, 1
	v_add3_u32 v3, v51, v3, s51
	v_bfe_u32 v4, v53, 16, 1
	v_lshrrev_b32_e32 v3, 16, v3
	v_add3_u32 v4, v53, v4, s51
	v_and_or_b32 v3, v4, s33, v3
	v_bfe_u32 v4, v55, 16, 1
	v_add3_u32 v4, v55, v4, s51
	v_bfe_u32 v5, v57, 16, 1
	v_lshrrev_b32_e32 v4, 16, v4
	v_add3_u32 v5, v57, v5, s51
	v_and_or_b32 v4, v5, s33, v4
	v_bfe_u32 v5, v121, 16, 1
	v_add3_u32 v5, v121, v5, s51
	v_lshrrev_b32_e32 v5, 16, v5
	v_and_or_b32 v5, v46, s33, v5
	v_or_b32_e32 v46, v115, v119
	v_lshlrev_b32_e32 v46, 11, v46
	v_mov_b32_e32 v47, v0
	v_lshl_add_u64 v[46:47], v[44:45], 0, v[46:47]
	global_store_dwordx4 v[46:47], v[2:5], off
	ds_read2_b32 v[46:47], v114 offset0:49 offset1:57
	ds_read2_b32 v[48:49], v114 offset0:16 offset1:24
	ds_read2_b32 v[52:53], v114 offset0:82 offset1:90
	ds_read2_b32 v[50:51], v114 offset0:115 offset1:123
	ds_read2_b32 v[56:57], v114 offset0:148 offset1:156
	ds_read2_b32 v[54:55], v114 offset0:181 offset1:189
	ds_read2_b32 v[120:121], v114 offset0:214 offset1:222
	ds_read2_b32 v[122:123], v114 offset0:247 offset1:255
	s_waitcnt lgkmcnt(7)
	v_bfe_u32 v3, v46, 16, 1
	s_waitcnt lgkmcnt(6)
	v_bfe_u32 v2, v48, 16, 1
	v_add3_u32 v2, v48, v2, s51
	v_lshrrev_b32_e32 v2, 16, v2
	v_add3_u32 v3, v46, v3, s51
	v_and_or_b32 v2, v3, s33, v2
	s_waitcnt lgkmcnt(5)
	v_bfe_u32 v3, v52, 16, 1
	v_add3_u32 v3, v52, v3, s51
	s_waitcnt lgkmcnt(4)
	v_bfe_u32 v4, v50, 16, 1
	v_lshrrev_b32_e32 v3, 16, v3
	v_add3_u32 v4, v50, v4, s51
	v_and_or_b32 v3, v4, s33, v3
	s_waitcnt lgkmcnt(3)
	v_bfe_u32 v4, v56, 16, 1
	v_add3_u32 v4, v56, v4, s51
	s_waitcnt lgkmcnt(2)
	v_bfe_u32 v5, v54, 16, 1
	v_lshrrev_b32_e32 v4, 16, v4
	v_add3_u32 v5, v54, v5, s51
	v_and_or_b32 v4, v5, s33, v4
	s_waitcnt lgkmcnt(1)
	v_bfe_u32 v5, v120, 16, 1
	v_add3_u32 v5, v120, v5, s51
	s_waitcnt lgkmcnt(0)
	v_bfe_u32 v46, v122, 16, 1
	v_lshrrev_b32_e32 v5, 16, v5
	v_add3_u32 v46, v122, v46, s51
	v_and_or_b32 v5, v46, s33, v5
	v_or_b32_e32 v46, v116, v119
	v_lshlrev_b32_e32 v124, 11, v46
	v_mov_b32_e32 v125, v0
	v_lshl_add_u64 v[124:125], v[44:45], 0, v[124:125]
	global_store_dwordx4 v[124:125], v[2:5], off
	v_bfe_u32 v46, v123, 16, 1
	v_add3_u32 v46, v123, v46, s51
	v_bfe_u32 v2, v49, 16, 1
	v_add3_u32 v2, v49, v2, s51
	v_bfe_u32 v3, v47, 16, 1
	v_lshrrev_b32_e32 v2, 16, v2
	v_add3_u32 v3, v47, v3, s51
	v_and_or_b32 v2, v3, s33, v2
	v_bfe_u32 v3, v53, 16, 1
	v_add3_u32 v3, v53, v3, s51
	v_bfe_u32 v4, v51, 16, 1
	v_lshrrev_b32_e32 v3, 16, v3
	v_add3_u32 v4, v51, v4, s51
	v_and_or_b32 v3, v4, s33, v3
	v_bfe_u32 v4, v57, 16, 1
	v_add3_u32 v4, v57, v4, s51
	v_bfe_u32 v5, v55, 16, 1
	v_lshrrev_b32_e32 v4, 16, v4
	v_add3_u32 v5, v55, v5, s51
	v_and_or_b32 v4, v5, s33, v4
	v_bfe_u32 v5, v121, 16, 1
	v_add3_u32 v5, v121, v5, s51
	v_lshrrev_b32_e32 v5, 16, v5
	v_and_or_b32 v5, v46, s33, v5
	v_or_b32_e32 v46, v117, v119
	v_lshlrev_b32_e32 v46, 11, v46
	v_mov_b32_e32 v47, v0
	v_lshl_add_u64 v[44:45], v[44:45], 0, v[46:47]
	global_store_dwordx4 v[44:45], v[2:5], off
	s_waitcnt lgkmcnt(0)

.LBB0_194:
	s_andn2_saveexec_b64 s[0:1], s[28:29]
	s_cbranch_execz .LBB0_196
	v_add_u32_e32 v2, 0x1d80, v118
	v_and_b32_e32 v4, 0x3e0, v42
	v_and_b32_e32 v5, 0x1ffc0, v2
	v_lshlrev_b32_e32 v2, 2, v4
	v_mov_b32_e32 v3, v0
	v_or_b32_e32 v44, v5, v8
	v_lshl_add_u64 v[2:3], v[34:35], 0, v[2:3]
	v_lshlrev_b32_e32 v44, 12, v44
	v_mov_b32_e32 v45, v0
	v_lshl_add_u64 v[44:45], v[2:3], 0, v[44:45]
	global_load_dword v46, v[44:45], off
	v_or_b32_e32 v44, v5, v58
	v_lshlrev_b32_e32 v44, 12, v44
	v_mov_b32_e32 v45, v0
	v_lshl_add_u64 v[44:45], v[2:3], 0, v[44:45]
	global_load_dword v44, v[44:45], off
	v_add_u32_e32 v47, v7, v13
	v_mov_b32_e32 v45, v0
	v_mov_b32_e32 v127, v0
	v_or_b32_e32 v168, v5, v60
	v_lshlrev_b32_e32 v168, 12, v168
	v_mov_b32_e32 v169, v0
	v_lshl_add_u64 v[168:169], v[2:3], 0, v[168:169]
	global_load_dword v170, v[168:169], off
	v_or_b32_e32 v168, v5, v62
	v_lshlrev_b32_e32 v168, 12, v168
	v_mov_b32_e32 v169, v0
	v_lshl_add_u64 v[168:169], v[2:3], 0, v[168:169]
	global_load_dword v168, v[168:169], off
	s_waitcnt vmcnt(2)
	ds_write2_b32 v47, v46, v44 offset1:66
	v_mov_b32_e32 v45, v0
	v_or_b32_e32 v160, v5, v64
	v_lshlrev_b32_e32 v160, 12, v160
	v_mov_b32_e32 v161, v0
	v_lshl_add_u64 v[160:161], v[2:3], 0, v[160:161]
	global_load_dword v162, v[160:161], off
	v_or_b32_e32 v160, v5, v66
	v_lshlrev_b32_e32 v160, 12, v160
	v_mov_b32_e32 v161, v0
	v_lshl_add_u64 v[160:161], v[2:3], 0, v[160:161]
	global_load_dword v160, v[160:161], off
	s_waitcnt vmcnt(2)
	ds_write2_b32 v47, v170, v168 offset0:132 offset1:198
	v_add_u32_e32 v45, 0x400, v47
	v_add_u32_e32 v47, v7, v69
	v_or_b32_e32 v168, v5, v68
	v_lshlrev_b32_e32 v168, 12, v168
	v_mov_b32_e32 v169, v0
	v_lshl_add_u64 v[168:169], v[2:3], 0, v[168:169]
	global_load_dword v170, v[168:169], off
	v_or_b32_e32 v168, v5, v70
	v_lshlrev_b32_e32 v168, 12, v168
	v_mov_b32_e32 v169, v0
	v_lshl_add_u64 v[168:169], v[2:3], 0, v[168:169]
	global_load_dword v168, v[168:169], off
	s_waitcnt vmcnt(2)
	ds_write2_b32 v45, v162, v160 offset0:8 offset1:74
	v_mov_b32_e32 v45, v0
	v_or_b32_e32 v160, v5, v72
	v_lshlrev_b32_e32 v160, 12, v160
	v_mov_b32_e32 v161, v0
	v_lshl_add_u64 v[160:161], v[2:3], 0, v[160:161]
	global_load_dword v162, v[160:161], off
	v_or_b32_e32 v160, v5, v74
	v_lshlrev_b32_e32 v160, 12, v160
	v_mov_b32_e32 v161, v0
	v_lshl_add_u64 v[160:161], v[2:3], 0, v[160:161]
	global_load_dword v160, v[160:161], off
	s_waitcnt vmcnt(2)
	ds_write2_b32 v47, v170, v168 offset1:66
	v_mov_b32_e32 v45, v0
	v_or_b32_e32 v168, v5, v76
	v_lshlrev_b32_e32 v168, 12, v168
	v_mov_b32_e32 v169, v0
	v_lshl_add_u64 v[168:169], v[2:3], 0, v[168:169]
	global_load_dword v170, v[168:169], off
	v_or_b32_e32 v168, v5, v78
	v_lshlrev_b32_e32 v168, 12, v168
	v_mov_b32_e32 v169, v0
	v_lshl_add_u64 v[168:169], v[2:3], 0, v[168:169]
	global_load_dword v168, v[168:169], off
	s_waitcnt vmcnt(2)
	ds_write2_b32 v47, v162, v160 offset0:132 offset1:198
	v_add_u32_e32 v45, 0x400, v47
	v_add_u32_e32 v47, v7, v81
	v_or_b32_e32 v160, v5, v80
	v_lshlrev_b32_e32 v160, 12, v160
	v_mov_b32_e32 v161, v0
	v_lshl_add_u64 v[160:161], v[2:3], 0, v[160:161]
	global_load_dword v162, v[160:161], off
	v_or_b32_e32 v160, v5, v82
	v_lshlrev_b32_e32 v160, 12, v160
	v_mov_b32_e32 v161, v0
	v_lshl_add_u64 v[160:161], v[2:3], 0, v[160:161]
	global_load_dword v160, v[160:161], off
	s_waitcnt vmcnt(2)
	ds_write2_b32 v45, v170, v168 offset0:8 offset1:74
	v_mov_b32_e32 v45, v0
	v_or_b32_e32 v168, v5, v84
	v_lshlrev_b32_e32 v168, 12, v168
	v_mov_b32_e32 v169, v0
	v_lshl_add_u64 v[168:169], v[2:3], 0, v[168:169]
	global_load_dword v170, v[168:169], off
	v_or_b32_e32 v168, v5, v86
	v_lshlrev_b32_e32 v168, 12, v168
	v_mov_b32_e32 v169, v0
	v_lshl_add_u64 v[168:169], v[2:3], 0, v[168:169]
	global_load_dword v168, v[168:169], off
	s_waitcnt vmcnt(2)
	ds_write2_b32 v47, v162, v160 offset1:66
	v_mov_b32_e32 v45, v0
	v_or_b32_e32 v160, v5, v88
	v_lshlrev_b32_e32 v160, 12, v160
	v_mov_b32_e32 v161, v0
	v_lshl_add_u64 v[160:161], v[2:3], 0, v[160:161]
	global_load_dword v162, v[160:161], off
	v_or_b32_e32 v160, v5, v90
	v_lshlrev_b32_e32 v160, 12, v160
	v_mov_b32_e32 v161, v0
	v_lshl_add_u64 v[160:161], v[2:3], 0, v[160:161]
	global_load_dword v160, v[160:161], off
	s_waitcnt vmcnt(2)
	ds_write2_b32 v47, v170, v168 offset0:132 offset1:198
	v_add_u32_e32 v45, 0x400, v47
	v_add_u32_e32 v47, v7, v93
	v_or_b32_e32 v168, v5, v92
	v_lshlrev_b32_e32 v168, 12, v168
	v_mov_b32_e32 v169, v0
	v_lshl_add_u64 v[168:169], v[2:3], 0, v[168:169]
	global_load_dword v170, v[168:169], off
	v_or_b32_e32 v168, v5, v94
	v_lshlrev_b32_e32 v168, 12, v168
	v_mov_b32_e32 v169, v0
	v_lshl_add_u64 v[168:169], v[2:3], 0, v[168:169]
	global_load_dword v168, v[168:169], off
	s_waitcnt vmcnt(2)
	ds_write2_b32 v45, v162, v160 offset0:8 offset1:74
	v_mov_b32_e32 v45, v0
	v_or_b32_e32 v160, v5, v96
	v_lshlrev_b32_e32 v160, 12, v160
	v_mov_b32_e32 v161, v0
	v_lshl_add_u64 v[160:161], v[2:3], 0, v[160:161]
	global_load_dword v162, v[160:161], off
	v_or_b32_e32 v160, v5, v98
	v_lshlrev_b32_e32 v160, 12, v160
	v_mov_b32_e32 v161, v0
	v_lshl_add_u64 v[160:161], v[2:3], 0, v[160:161]
	global_load_dword v160, v[160:161], off
	s_waitcnt vmcnt(2)
	ds_write2_b32 v47, v170, v168 offset1:66
	v_mov_b32_e32 v45, v0
	v_or_b32_e32 v168, v5, v100
	v_lshlrev_b32_e32 v168, 12, v168
	v_mov_b32_e32 v169, v0
	v_lshl_add_u64 v[168:169], v[2:3], 0, v[168:169]
	global_load_dword v170, v[168:169], off
	v_or_b32_e32 v168, v5, v102
	v_lshlrev_b32_e32 v168, 12, v168
	v_mov_b32_e32 v169, v0
	v_lshl_add_u64 v[168:169], v[2:3], 0, v[168:169]
	global_load_dword v168, v[168:169], off
	s_waitcnt vmcnt(2)
	ds_write2_b32 v47, v162, v160 offset0:132 offset1:198
	v_add_u32_e32 v45, 0x400, v47
	v_add_u32_e32 v47, v7, v105
	v_or_b32_e32 v160, v5, v104
	v_lshlrev_b32_e32 v160, 12, v160
	v_mov_b32_e32 v161, v0
	v_lshl_add_u64 v[160:161], v[2:3], 0, v[160:161]
	global_load_dword v162, v[160:161], off
	v_or_b32_e32 v160, v5, v106
	v_lshlrev_b32_e32 v160, 12, v160
	v_mov_b32_e32 v161, v0
	v_lshl_add_u64 v[160:161], v[2:3], 0, v[160:161]
	global_load_dword v160, v[160:161], off
	s_waitcnt vmcnt(2)
	ds_write2_b32 v45, v170, v168 offset0:8 offset1:74
	v_mov_b32_e32 v45, v0
	v_or_b32_e32 v168, v5, v107
	v_lshlrev_b32_e32 v168, 12, v168
	v_mov_b32_e32 v169, v0
	v_lshl_add_u64 v[168:169], v[2:3], 0, v[168:169]
	global_load_dword v170, v[168:169], off
	v_or_b32_e32 v168, v5, v108
	v_lshlrev_b32_e32 v168, 12, v168
	v_mov_b32_e32 v169, v0
	v_lshl_add_u64 v[168:169], v[2:3], 0, v[168:169]
	global_load_dword v168, v[168:169], off
	s_waitcnt vmcnt(2)
	ds_write2_b32 v47, v162, v160 offset1:66
	v_mov_b32_e32 v45, v0
	v_or_b32_e32 v160, v5, v109
	v_lshlrev_b32_e32 v160, 12, v160
	v_mov_b32_e32 v161, v0
	v_lshl_add_u64 v[160:161], v[2:3], 0, v[160:161]
	global_load_dword v162, v[160:161], off
	v_or_b32_e32 v160, v5, v110
	v_lshlrev_b32_e32 v160, 12, v160
	v_mov_b32_e32 v161, v0
	v_lshl_add_u64 v[160:161], v[2:3], 0, v[160:161]
	global_load_dword v160, v[160:161], off
	s_waitcnt vmcnt(2)
	ds_write2_b32 v47, v170, v168 offset0:132 offset1:198
	v_add_u32_e32 v47, 0x400, v47
	v_mov_b32_e32 v45, v0
	v_or_b32_e32 v170, v5, v111
	v_lshlrev_b32_e32 v170, 12, v170
	v_mov_b32_e32 v171, v0
	v_lshl_add_u64 v[170:171], v[2:3], 0, v[170:171]
	global_load_dword v172, v[170:171], off
	v_or_b32_e32 v170, v5, v112
	v_lshlrev_b32_e32 v170, 12, v170
	v_mov_b32_e32 v171, v0
	v_lshl_add_u64 v[168:169], v[2:3], 0, v[170:171]
	global_load_dword v168, v[168:169], off
	s_waitcnt vmcnt(2)
	ds_write2_b32 v47, v162, v160 offset0:8 offset1:74
	v_mov_b32_e32 v3, v0
	s_waitcnt vmcnt(0)
	ds_write2_b32 v47, v172, v168 offset0:140 offset1:206
	s_waitcnt lgkmcnt(0)
	ds_read2_b32 v[48:49], v114 offset0:33 offset1:41
	ds_read2_b32 v[50:51], v114 offset1:8
	ds_read2_b32 v[52:53], v114 offset0:66 offset1:74
	ds_read2_b32 v[54:55], v114 offset0:99 offset1:107
	v_lshlrev_b32_e32 v2, 1, v5
	ds_read2_b32 v[56:57], v114 offset0:132 offset1:140
	ds_read2_b32 v[120:121], v114 offset0:165 offset1:173
	s_waitcnt lgkmcnt(5)
	v_bfe_u32 v44, v48, 16, 1
	s_waitcnt lgkmcnt(4)
	v_bfe_u32 v5, v50, 16, 1
	v_add3_u32 v5, v50, v5, s51
	v_lshrrev_b32_e32 v5, 16, v5
	v_add3_u32 v44, v48, v44, s51
	v_and_or_b32 v44, v44, s33, v5
	s_waitcnt lgkmcnt(3)
	v_bfe_u32 v5, v52, 16, 1
	v_add3_u32 v5, v52, v5, s51
	s_waitcnt lgkmcnt(2)
	v_bfe_u32 v45, v54, 16, 1
	v_lshrrev_b32_e32 v5, 16, v5
	v_add3_u32 v45, v54, v45, s51
	ds_read2_b32 v[122:123], v114 offset0:198 offset1:206
	ds_read2_b32 v[124:125], v114 offset0:231 offset1:239
	v_and_or_b32 v45, v45, s33, v5
	s_waitcnt lgkmcnt(3)
	v_bfe_u32 v5, v56, 16, 1
	v_add3_u32 v5, v56, v5, s51
	s_waitcnt lgkmcnt(2)
	v_bfe_u32 v46, v120, 16, 1
	v_lshrrev_b32_e32 v5, 16, v5
	v_add3_u32 v46, v120, v46, s51
	v_and_or_b32 v46, v46, s33, v5
	s_waitcnt lgkmcnt(1)
	v_bfe_u32 v5, v122, 16, 1
	v_add3_u32 v5, v122, v5, s51
	s_waitcnt lgkmcnt(0)
	v_bfe_u32 v47, v124, 16, 1
	v_lshrrev_b32_e32 v5, 16, v5
	v_add3_u32 v47, v124, v47, s51
	v_and_or_b32 v47, v47, s33, v5
	v_or_b32_e32 v5, v4, v113
	v_mul_u32_u24_e32 v5, 0xb00, v5
	v_lshl_add_u64 v[2:3], v[20:21], 0, v[2:3]
	v_lshlrev_b32_e32 v126, 1, v5
	v_lshl_add_u64 v[126:127], v[2:3], 0, v[126:127]
	v_bfe_u32 v5, v51, 16, 1
	global_store_dwordx4 v[126:127], v[44:47], off
	v_add3_u32 v5, v51, v5, s51
	v_lshrrev_b32_e32 v5, 16, v5
	v_bfe_u32 v44, v49, 16, 1
	v_add3_u32 v44, v49, v44, s51
	v_and_or_b32 v44, v44, s33, v5
	v_bfe_u32 v5, v53, 16, 1
	v_add3_u32 v5, v53, v5, s51
	v_bfe_u32 v45, v55, 16, 1
	v_lshrrev_b32_e32 v5, 16, v5
	v_add3_u32 v45, v55, v45, s51
	v_and_or_b32 v45, v45, s33, v5
	v_bfe_u32 v5, v57, 16, 1
	v_add3_u32 v5, v57, v5, s51
	v_bfe_u32 v46, v121, 16, 1
	v_lshrrev_b32_e32 v5, 16, v5
	v_add3_u32 v46, v121, v46, s51
	v_and_or_b32 v46, v46, s33, v5
	v_bfe_u32 v5, v123, 16, 1
	v_add3_u32 v5, v123, v5, s51
	v_bfe_u32 v47, v125, 16, 1
	v_lshrrev_b32_e32 v5, 16, v5
	v_add3_u32 v47, v125, v47, s51
	v_and_or_b32 v47, v47, s33, v5
	v_or_b32_e32 v5, v4, v115
	v_mul_u32_u24_e32 v5, 0xb00, v5
	v_lshlrev_b32_e32 v48, 1, v5
	v_mov_b32_e32 v49, v0
	v_lshl_add_u64 v[48:49], v[2:3], 0, v[48:49]
	global_store_dwordx4 v[48:49], v[44:47], off
	ds_read2_b32 v[48:49], v114 offset0:16 offset1:24
	ds_read2_b32 v[50:51], v114 offset0:49 offset1:57
	ds_read2_b32 v[52:53], v114 offset0:82 offset1:90
	ds_read2_b32 v[54:55], v114 offset0:115 offset1:123
	ds_read2_b32 v[56:57], v114 offset0:148 offset1:156
	ds_read2_b32 v[120:121], v114 offset0:181 offset1:189
	ds_read2_b32 v[122:123], v114 offset0:214 offset1:222
	ds_read2_b32 v[124:125], v114 offset0:247 offset1:255
	s_waitcnt lgkmcnt(7)
	v_bfe_u32 v5, v48, 16, 1
	v_add3_u32 v5, v48, v5, s51
	s_waitcnt lgkmcnt(6)
	v_bfe_u32 v44, v50, 16, 1
	v_lshrrev_b32_e32 v5, 16, v5
	v_add3_u32 v44, v50, v44, s51
	v_and_or_b32 v44, v44, s33, v5
	s_waitcnt lgkmcnt(5)
	v_bfe_u32 v5, v52, 16, 1
	v_add3_u32 v5, v52, v5, s51
	s_waitcnt lgkmcnt(4)
	v_bfe_u32 v45, v54, 16, 1
	v_lshrrev_b32_e32 v5, 16, v5
	v_add3_u32 v45, v54, v45, s51
	v_and_or_b32 v45, v45, s33, v5
	s_waitcnt lgkmcnt(3)
	v_bfe_u32 v5, v56, 16, 1
	v_add3_u32 v5, v56, v5, s51
	s_waitcnt lgkmcnt(2)
	v_bfe_u32 v46, v120, 16, 1
	v_lshrrev_b32_e32 v5, 16, v5
	v_add3_u32 v46, v120, v46, s51
	v_and_or_b32 v46, v46, s33, v5
	s_waitcnt lgkmcnt(1)
	v_bfe_u32 v5, v122, 16, 1
	v_add3_u32 v5, v122, v5, s51
	s_waitcnt lgkmcnt(0)
	v_bfe_u32 v47, v124, 16, 1
	v_lshrrev_b32_e32 v5, 16, v5
	v_add3_u32 v47, v124, v47, s51
	v_and_or_b32 v47, v47, s33, v5
	v_or_b32_e32 v5, v4, v116
	v_mul_u32_u24_e32 v5, 0xb00, v5
	v_lshlrev_b32_e32 v126, 1, v5
	v_mov_b32_e32 v127, v0
	v_lshl_add_u64 v[126:127], v[2:3], 0, v[126:127]
	v_bfe_u32 v5, v49, 16, 1
	global_store_dwordx4 v[126:127], v[44:47], off
	v_add3_u32 v5, v49, v5, s51
	v_lshrrev_b32_e32 v5, 16, v5
	v_bfe_u32 v44, v51, 16, 1
	v_add3_u32 v44, v51, v44, s51
	v_and_or_b32 v44, v44, s33, v5
	v_bfe_u32 v5, v53, 16, 1
	v_add3_u32 v5, v53, v5, s51
	v_bfe_u32 v45, v55, 16, 1
	v_lshrrev_b32_e32 v5, 16, v5
	v_add3_u32 v45, v55, v45, s51
	v_and_or_b32 v45, v45, s33, v5
	v_bfe_u32 v5, v57, 16, 1
	v_add3_u32 v5, v57, v5, s51
	v_bfe_u32 v46, v121, 16, 1
	v_lshrrev_b32_e32 v5, 16, v5
	v_add3_u32 v46, v121, v46, s51
	v_and_or_b32 v46, v46, s33, v5
	v_bfe_u32 v5, v123, 16, 1
	v_add3_u32 v5, v123, v5, s51
	v_bfe_u32 v47, v125, 16, 1
	v_or_b32_e32 v4, v4, v117
	v_lshrrev_b32_e32 v5, 16, v5
	v_add3_u32 v47, v125, v47, s51
	v_mul_u32_u24_e32 v4, 0xb00, v4
	v_and_or_b32 v47, v47, s33, v5
	v_lshlrev_b32_e32 v4, 1, v4
	v_mov_b32_e32 v5, v0
	v_lshl_add_u64 v[2:3], v[2:3], 0, v[4:5]
	global_store_dwordx4 v[2:3], v[44:47], off
	s_waitcnt lgkmcnt(0)

.LBB0_197:
	s_andn2_saveexec_b64 s[0:1], s[26:27]
	s_cbranch_execz .LBB0_199
	v_add_u32_e32 v2, 0x2880, v118
	v_and_b32_e32 v4, 0x3e0, v42
	v_and_b32_e32 v5, 0x1ffc0, v2
	v_lshlrev_b32_e32 v2, 2, v4
	v_mov_b32_e32 v3, v0
	v_or_b32_e32 v44, v5, v8
	v_lshl_add_u64 v[2:3], v[36:37], 0, v[2:3]
	v_lshlrev_b32_e32 v44, 12, v44
	v_mov_b32_e32 v45, v0
	v_lshl_add_u64 v[44:45], v[2:3], 0, v[44:45]
	global_load_dword v46, v[44:45], off
	v_or_b32_e32 v44, v5, v58
	v_lshlrev_b32_e32 v44, 12, v44
	v_mov_b32_e32 v45, v0
	v_lshl_add_u64 v[44:45], v[2:3], 0, v[44:45]
	global_load_dword v44, v[44:45], off
	v_add_u32_e32 v47, v7, v13
	v_mov_b32_e32 v45, v0
	v_mov_b32_e32 v127, v0
	v_or_b32_e32 v168, v5, v60
	v_lshlrev_b32_e32 v168, 12, v168
	v_mov_b32_e32 v169, v0
	v_lshl_add_u64 v[168:169], v[2:3], 0, v[168:169]
	global_load_dword v170, v[168:169], off
	v_or_b32_e32 v168, v5, v62
	v_lshlrev_b32_e32 v168, 12, v168
	v_mov_b32_e32 v169, v0
	v_lshl_add_u64 v[168:169], v[2:3], 0, v[168:169]
	global_load_dword v168, v[168:169], off
	s_waitcnt vmcnt(2)
	ds_write2_b32 v47, v46, v44 offset1:66
	v_mov_b32_e32 v45, v0
	v_or_b32_e32 v160, v5, v64
	v_lshlrev_b32_e32 v160, 12, v160
	v_mov_b32_e32 v161, v0
	v_lshl_add_u64 v[160:161], v[2:3], 0, v[160:161]
	global_load_dword v162, v[160:161], off
	v_or_b32_e32 v160, v5, v66
	v_lshlrev_b32_e32 v160, 12, v160
	v_mov_b32_e32 v161, v0
	v_lshl_add_u64 v[160:161], v[2:3], 0, v[160:161]
	global_load_dword v160, v[160:161], off
	s_waitcnt vmcnt(2)
	ds_write2_b32 v47, v170, v168 offset0:132 offset1:198
	v_add_u32_e32 v45, 0x400, v47
	v_add_u32_e32 v47, v7, v69
	v_or_b32_e32 v168, v5, v68
	v_lshlrev_b32_e32 v168, 12, v168
	v_mov_b32_e32 v169, v0
	v_lshl_add_u64 v[168:169], v[2:3], 0, v[168:169]
	global_load_dword v170, v[168:169], off
	v_or_b32_e32 v168, v5, v70
	v_lshlrev_b32_e32 v168, 12, v168
	v_mov_b32_e32 v169, v0
	v_lshl_add_u64 v[168:169], v[2:3], 0, v[168:169]
	global_load_dword v168, v[168:169], off
	s_waitcnt vmcnt(2)
	ds_write2_b32 v45, v162, v160 offset0:8 offset1:74
	v_mov_b32_e32 v45, v0
	v_or_b32_e32 v160, v5, v72
	v_lshlrev_b32_e32 v160, 12, v160
	v_mov_b32_e32 v161, v0
	v_lshl_add_u64 v[160:161], v[2:3], 0, v[160:161]
	global_load_dword v162, v[160:161], off
	v_or_b32_e32 v160, v5, v74
	v_lshlrev_b32_e32 v160, 12, v160
	v_mov_b32_e32 v161, v0
	v_lshl_add_u64 v[160:161], v[2:3], 0, v[160:161]
	global_load_dword v160, v[160:161], off
	s_waitcnt vmcnt(2)
	ds_write2_b32 v47, v170, v168 offset1:66
	v_mov_b32_e32 v45, v0
	v_or_b32_e32 v168, v5, v76
	v_lshlrev_b32_e32 v168, 12, v168
	v_mov_b32_e32 v169, v0
	v_lshl_add_u64 v[168:169], v[2:3], 0, v[168:169]
	global_load_dword v170, v[168:169], off
	v_or_b32_e32 v168, v5, v78
	v_lshlrev_b32_e32 v168, 12, v168
	v_mov_b32_e32 v169, v0
	v_lshl_add_u64 v[168:169], v[2:3], 0, v[168:169]
	global_load_dword v168, v[168:169], off
	s_waitcnt vmcnt(2)
	ds_write2_b32 v47, v162, v160 offset0:132 offset1:198
	v_add_u32_e32 v45, 0x400, v47
	v_add_u32_e32 v47, v7, v81
	v_or_b32_e32 v160, v5, v80
	v_lshlrev_b32_e32 v160, 12, v160
	v_mov_b32_e32 v161, v0
	v_lshl_add_u64 v[160:161], v[2:3], 0, v[160:161]
	global_load_dword v162, v[160:161], off
	v_or_b32_e32 v160, v5, v82
	v_lshlrev_b32_e32 v160, 12, v160
	v_mov_b32_e32 v161, v0
	v_lshl_add_u64 v[160:161], v[2:3], 0, v[160:161]
	global_load_dword v160, v[160:161], off
	s_waitcnt vmcnt(2)
	ds_write2_b32 v45, v170, v168 offset0:8 offset1:74
	v_mov_b32_e32 v45, v0
	v_or_b32_e32 v168, v5, v84
	v_lshlrev_b32_e32 v168, 12, v168
	v_mov_b32_e32 v169, v0
	v_lshl_add_u64 v[168:169], v[2:3], 0, v[168:169]
	global_load_dword v170, v[168:169], off
	v_or_b32_e32 v168, v5, v86
	v_lshlrev_b32_e32 v168, 12, v168
	v_mov_b32_e32 v169, v0
	v_lshl_add_u64 v[168:169], v[2:3], 0, v[168:169]
	global_load_dword v168, v[168:169], off
	s_waitcnt vmcnt(2)
	ds_write2_b32 v47, v162, v160 offset1:66
	v_mov_b32_e32 v45, v0
	v_or_b32_e32 v160, v5, v88
	v_lshlrev_b32_e32 v160, 12, v160
	v_mov_b32_e32 v161, v0
	v_lshl_add_u64 v[160:161], v[2:3], 0, v[160:161]
	global_load_dword v162, v[160:161], off
	v_or_b32_e32 v160, v5, v90
	v_lshlrev_b32_e32 v160, 12, v160
	v_mov_b32_e32 v161, v0
	v_lshl_add_u64 v[160:161], v[2:3], 0, v[160:161]
	global_load_dword v160, v[160:161], off
	s_waitcnt vmcnt(2)
	ds_write2_b32 v47, v170, v168 offset0:132 offset1:198
	v_add_u32_e32 v45, 0x400, v47
	v_add_u32_e32 v47, v7, v93
	v_or_b32_e32 v168, v5, v92
	v_lshlrev_b32_e32 v168, 12, v168
	v_mov_b32_e32 v169, v0
	v_lshl_add_u64 v[168:169], v[2:3], 0, v[168:169]
	global_load_dword v170, v[168:169], off
	v_or_b32_e32 v168, v5, v94
	v_lshlrev_b32_e32 v168, 12, v168
	v_mov_b32_e32 v169, v0
	v_lshl_add_u64 v[168:169], v[2:3], 0, v[168:169]
	global_load_dword v168, v[168:169], off
	s_waitcnt vmcnt(2)
	ds_write2_b32 v45, v162, v160 offset0:8 offset1:74
	v_mov_b32_e32 v45, v0
	v_or_b32_e32 v160, v5, v96
	v_lshlrev_b32_e32 v160, 12, v160
	v_mov_b32_e32 v161, v0
	v_lshl_add_u64 v[160:161], v[2:3], 0, v[160:161]
	global_load_dword v162, v[160:161], off
	v_or_b32_e32 v160, v5, v98
	v_lshlrev_b32_e32 v160, 12, v160
	v_mov_b32_e32 v161, v0
	v_lshl_add_u64 v[160:161], v[2:3], 0, v[160:161]
	global_load_dword v160, v[160:161], off
	s_waitcnt vmcnt(2)
	ds_write2_b32 v47, v170, v168 offset1:66
	v_mov_b32_e32 v45, v0
	v_or_b32_e32 v168, v5, v100
	v_lshlrev_b32_e32 v168, 12, v168
	v_mov_b32_e32 v169, v0
	v_lshl_add_u64 v[168:169], v[2:3], 0, v[168:169]
	global_load_dword v170, v[168:169], off
	v_or_b32_e32 v168, v5, v102
	v_lshlrev_b32_e32 v168, 12, v168
	v_mov_b32_e32 v169, v0
	v_lshl_add_u64 v[168:169], v[2:3], 0, v[168:169]
	global_load_dword v168, v[168:169], off
	s_waitcnt vmcnt(2)
	ds_write2_b32 v47, v162, v160 offset0:132 offset1:198
	v_add_u32_e32 v45, 0x400, v47
	v_add_u32_e32 v47, v7, v105
	v_or_b32_e32 v160, v5, v104
	v_lshlrev_b32_e32 v160, 12, v160
	v_mov_b32_e32 v161, v0
	v_lshl_add_u64 v[160:161], v[2:3], 0, v[160:161]
	global_load_dword v162, v[160:161], off
	v_or_b32_e32 v160, v5, v106
	v_lshlrev_b32_e32 v160, 12, v160
	v_mov_b32_e32 v161, v0
	v_lshl_add_u64 v[160:161], v[2:3], 0, v[160:161]
	global_load_dword v160, v[160:161], off
	s_waitcnt vmcnt(2)
	ds_write2_b32 v45, v170, v168 offset0:8 offset1:74
	v_mov_b32_e32 v45, v0
	v_or_b32_e32 v168, v5, v107
	v_lshlrev_b32_e32 v168, 12, v168
	v_mov_b32_e32 v169, v0
	v_lshl_add_u64 v[168:169], v[2:3], 0, v[168:169]
	global_load_dword v170, v[168:169], off
	v_or_b32_e32 v168, v5, v108
	v_lshlrev_b32_e32 v168, 12, v168
	v_mov_b32_e32 v169, v0
	v_lshl_add_u64 v[168:169], v[2:3], 0, v[168:169]
	global_load_dword v168, v[168:169], off
	s_waitcnt vmcnt(2)
	ds_write2_b32 v47, v162, v160 offset1:66
	v_mov_b32_e32 v45, v0
	v_or_b32_e32 v160, v5, v109
	v_lshlrev_b32_e32 v160, 12, v160
	v_mov_b32_e32 v161, v0
	v_lshl_add_u64 v[160:161], v[2:3], 0, v[160:161]
	global_load_dword v162, v[160:161], off
	v_or_b32_e32 v160, v5, v110
	v_lshlrev_b32_e32 v160, 12, v160
	v_mov_b32_e32 v161, v0
	v_lshl_add_u64 v[160:161], v[2:3], 0, v[160:161]
	global_load_dword v160, v[160:161], off
	s_waitcnt vmcnt(2)
	ds_write2_b32 v47, v170, v168 offset0:132 offset1:198
	v_add_u32_e32 v47, 0x400, v47
	v_mov_b32_e32 v45, v0
	v_or_b32_e32 v170, v5, v111
	v_lshlrev_b32_e32 v170, 12, v170
	v_mov_b32_e32 v171, v0
	v_lshl_add_u64 v[170:171], v[2:3], 0, v[170:171]
	global_load_dword v172, v[170:171], off
	v_or_b32_e32 v170, v5, v112
	v_lshlrev_b32_e32 v170, 12, v170
	v_mov_b32_e32 v171, v0
	v_lshl_add_u64 v[168:169], v[2:3], 0, v[170:171]
	global_load_dword v168, v[168:169], off
	s_waitcnt vmcnt(2)
	ds_write2_b32 v47, v162, v160 offset0:8 offset1:74
	v_mov_b32_e32 v3, v0
	s_waitcnt vmcnt(0)
	ds_write2_b32 v47, v172, v168 offset0:140 offset1:206
	s_waitcnt lgkmcnt(0)
	ds_read2_b32 v[48:49], v114 offset0:33 offset1:41
	ds_read2_b32 v[50:51], v114 offset1:8
	ds_read2_b32 v[52:53], v114 offset0:66 offset1:74
	ds_read2_b32 v[54:55], v114 offset0:99 offset1:107
	v_lshlrev_b32_e32 v2, 1, v5
	ds_read2_b32 v[56:57], v114 offset0:132 offset1:140
	ds_read2_b32 v[120:121], v114 offset0:165 offset1:173
	s_waitcnt lgkmcnt(5)
	v_bfe_u32 v44, v48, 16, 1
	s_waitcnt lgkmcnt(4)
	v_bfe_u32 v5, v50, 16, 1
	v_add3_u32 v5, v50, v5, s51
	v_lshrrev_b32_e32 v5, 16, v5
	v_add3_u32 v44, v48, v44, s51
	v_and_or_b32 v44, v44, s33, v5
	s_waitcnt lgkmcnt(3)
	v_bfe_u32 v5, v52, 16, 1
	v_add3_u32 v5, v52, v5, s51
	s_waitcnt lgkmcnt(2)
	v_bfe_u32 v45, v54, 16, 1
	v_lshrrev_b32_e32 v5, 16, v5
	v_add3_u32 v45, v54, v45, s51
	ds_read2_b32 v[122:123], v114 offset0:198 offset1:206
	ds_read2_b32 v[124:125], v114 offset0:231 offset1:239
	v_and_or_b32 v45, v45, s33, v5
	s_waitcnt lgkmcnt(3)
	v_bfe_u32 v5, v56, 16, 1
	v_add3_u32 v5, v56, v5, s51
	s_waitcnt lgkmcnt(2)
	v_bfe_u32 v46, v120, 16, 1
	v_lshrrev_b32_e32 v5, 16, v5
	v_add3_u32 v46, v120, v46, s51
	v_and_or_b32 v46, v46, s33, v5
	s_waitcnt lgkmcnt(1)
	v_bfe_u32 v5, v122, 16, 1
	v_add3_u32 v5, v122, v5, s51
	s_waitcnt lgkmcnt(0)
	v_bfe_u32 v47, v124, 16, 1
	v_lshrrev_b32_e32 v5, 16, v5
	v_add3_u32 v47, v124, v47, s51
	v_and_or_b32 v47, v47, s33, v5
	v_or_b32_e32 v5, v4, v113
	v_mul_u32_u24_e32 v5, 0xb00, v5
	v_lshl_add_u64 v[2:3], v[22:23], 0, v[2:3]
	v_lshlrev_b32_e32 v126, 1, v5
	v_lshl_add_u64 v[126:127], v[2:3], 0, v[126:127]
	v_bfe_u32 v5, v51, 16, 1
	global_store_dwordx4 v[126:127], v[44:47], off
	v_add3_u32 v5, v51, v5, s51
	v_lshrrev_b32_e32 v5, 16, v5
	v_bfe_u32 v44, v49, 16, 1
	v_add3_u32 v44, v49, v44, s51
	v_and_or_b32 v44, v44, s33, v5
	v_bfe_u32 v5, v53, 16, 1
	v_add3_u32 v5, v53, v5, s51
	v_bfe_u32 v45, v55, 16, 1
	v_lshrrev_b32_e32 v5, 16, v5
	v_add3_u32 v45, v55, v45, s51
	v_and_or_b32 v45, v45, s33, v5
	v_bfe_u32 v5, v57, 16, 1
	v_add3_u32 v5, v57, v5, s51
	v_bfe_u32 v46, v121, 16, 1
	v_lshrrev_b32_e32 v5, 16, v5
	v_add3_u32 v46, v121, v46, s51
	v_and_or_b32 v46, v46, s33, v5
	v_bfe_u32 v5, v123, 16, 1
	v_add3_u32 v5, v123, v5, s51
	v_bfe_u32 v47, v125, 16, 1
	v_lshrrev_b32_e32 v5, 16, v5
	v_add3_u32 v47, v125, v47, s51
	v_and_or_b32 v47, v47, s33, v5
	v_or_b32_e32 v5, v4, v115
	v_mul_u32_u24_e32 v5, 0xb00, v5
	v_lshlrev_b32_e32 v48, 1, v5
	v_mov_b32_e32 v49, v0
	v_lshl_add_u64 v[48:49], v[2:3], 0, v[48:49]
	global_store_dwordx4 v[48:49], v[44:47], off
	ds_read2_b32 v[48:49], v114 offset0:16 offset1:24
	ds_read2_b32 v[50:51], v114 offset0:49 offset1:57
	ds_read2_b32 v[52:53], v114 offset0:82 offset1:90
	ds_read2_b32 v[54:55], v114 offset0:115 offset1:123
	ds_read2_b32 v[56:57], v114 offset0:148 offset1:156
	ds_read2_b32 v[120:121], v114 offset0:181 offset1:189
	ds_read2_b32 v[122:123], v114 offset0:214 offset1:222
	ds_read2_b32 v[124:125], v114 offset0:247 offset1:255
	s_waitcnt lgkmcnt(7)
	v_bfe_u32 v5, v48, 16, 1
	v_add3_u32 v5, v48, v5, s51
	s_waitcnt lgkmcnt(6)
	v_bfe_u32 v44, v50, 16, 1
	v_lshrrev_b32_e32 v5, 16, v5
	v_add3_u32 v44, v50, v44, s51
	v_and_or_b32 v44, v44, s33, v5
	s_waitcnt lgkmcnt(5)
	v_bfe_u32 v5, v52, 16, 1
	v_add3_u32 v5, v52, v5, s51
	s_waitcnt lgkmcnt(4)
	v_bfe_u32 v45, v54, 16, 1
	v_lshrrev_b32_e32 v5, 16, v5
	v_add3_u32 v45, v54, v45, s51
	v_and_or_b32 v45, v45, s33, v5
	s_waitcnt lgkmcnt(3)
	v_bfe_u32 v5, v56, 16, 1
	v_add3_u32 v5, v56, v5, s51
	s_waitcnt lgkmcnt(2)
	v_bfe_u32 v46, v120, 16, 1
	v_lshrrev_b32_e32 v5, 16, v5
	v_add3_u32 v46, v120, v46, s51
	v_and_or_b32 v46, v46, s33, v5
	s_waitcnt lgkmcnt(1)
	v_bfe_u32 v5, v122, 16, 1
	v_add3_u32 v5, v122, v5, s51
	s_waitcnt lgkmcnt(0)
	v_bfe_u32 v47, v124, 16, 1
	v_lshrrev_b32_e32 v5, 16, v5
	v_add3_u32 v47, v124, v47, s51
	v_and_or_b32 v47, v47, s33, v5
	v_or_b32_e32 v5, v4, v116
	v_mul_u32_u24_e32 v5, 0xb00, v5
	v_lshlrev_b32_e32 v126, 1, v5
	v_mov_b32_e32 v127, v0
	v_lshl_add_u64 v[126:127], v[2:3], 0, v[126:127]
	v_bfe_u32 v5, v49, 16, 1
	global_store_dwordx4 v[126:127], v[44:47], off
	v_add3_u32 v5, v49, v5, s51
	v_lshrrev_b32_e32 v5, 16, v5
	v_bfe_u32 v44, v51, 16, 1
	v_add3_u32 v44, v51, v44, s51
	v_and_or_b32 v44, v44, s33, v5
	v_bfe_u32 v5, v53, 16, 1
	v_add3_u32 v5, v53, v5, s51
	v_bfe_u32 v45, v55, 16, 1
	v_lshrrev_b32_e32 v5, 16, v5
	v_add3_u32 v45, v55, v45, s51
	v_and_or_b32 v45, v45, s33, v5
	v_bfe_u32 v5, v57, 16, 1
	v_add3_u32 v5, v57, v5, s51
	v_bfe_u32 v46, v121, 16, 1
	v_lshrrev_b32_e32 v5, 16, v5
	v_add3_u32 v46, v121, v46, s51
	v_and_or_b32 v46, v46, s33, v5
	v_bfe_u32 v5, v123, 16, 1
	v_add3_u32 v5, v123, v5, s51
	v_bfe_u32 v47, v125, 16, 1
	v_or_b32_e32 v4, v4, v117
	v_lshrrev_b32_e32 v5, 16, v5
	v_add3_u32 v47, v125, v47, s51
	v_mul_u32_u24_e32 v4, 0xb00, v4
	v_and_or_b32 v47, v47, s33, v5
	v_lshlrev_b32_e32 v4, 1, v4
	v_mov_b32_e32 v5, v0
	v_lshl_add_u64 v[2:3], v[2:3], 0, v[4:5]
	global_store_dwordx4 v[2:3], v[44:47], off
	s_waitcnt lgkmcnt(0)

.LBB0_203:
	v_mul_lo_u16_e32 v3, 0xb0, v3
	v_sub_u16_e32 v44, v2, v3
	v_lshlrev_b16_e32 v5, 5, v44
	v_lshlrev_b32_e32 v2, 2, v5
	v_mov_b32_e32 v3, v0
	v_lshl_add_u64 v[2:3], v[38:39], 0, v[2:3]
	v_mad_u64_u32 v[48:49], s[8:9], v45, s48, v[2:3]
	global_load_dword v45, v[48:49], off
	v_add_u32_e32 v48, v7, v13
	s_and_b64 vcc, exec, s[0:1]
	v_or_b32_e32 v170, v58, v4
	v_mad_u64_u32 v[168:169], s[8:9], v170, s48, v[2:3]
	global_load_dword v168, v[168:169], off
	s_waitcnt vmcnt(1)
	v_mul_f32_e32 v45, v47, v45
	ds_write_b32 v48, v45
	v_add_lshl_u32 v45, v8, v4, 2
	s_cbranch_vccnz .LBB0_205
	global_load_dword v46, v45, s[76:77] offset:8
.LBB0_205:
	v_add_u32_e32 v49, v7, v59
	v_mov_b32_e32 v47, 1.0
	s_and_b64 vcc, exec, s[0:1]
	v_or_b32_e32 v160, v60, v4
	v_mad_u64_u32 v[160:161], s[8:9], v160, s48, v[2:3]
	global_load_dword v160, v[160:161], off
	s_waitcnt vmcnt(1)
	v_mul_f32_e32 v46, v46, v168
	ds_write_b32 v49, v46
	v_mov_b32_e32 v46, 1.0
	s_cbranch_vccnz .LBB0_207
	global_load_dword v46, v45, s[76:77] offset:16
.LBB0_207:
	v_add_u32_e32 v49, v7, v61
	s_and_b64 vcc, exec, s[0:1]
	v_or_b32_e32 v170, v62, v4
	v_mad_u64_u32 v[168:169], s[8:9], v170, s48, v[2:3]
	global_load_dword v168, v[168:169], off
	s_waitcnt vmcnt(1)
	v_mul_f32_e32 v46, v46, v160
	ds_write_b32 v49, v46
	s_cbranch_vccnz .LBB0_209
	global_load_dword v47, v45, s[76:77] offset:24
.LBB0_209:
	v_add_u32_e32 v49, v7, v63
	v_mov_b32_e32 v46, 1.0
	s_and_b64 vcc, exec, s[0:1]
	v_or_b32_e32 v160, v64, v4
	v_mad_u64_u32 v[160:161], s[8:9], v160, s48, v[2:3]
	global_load_dword v160, v[160:161], off
	s_waitcnt vmcnt(1)
	v_mul_f32_e32 v47, v47, v168
	ds_write_b32 v49, v47
	v_mov_b32_e32 v47, 1.0
	s_cbranch_vccnz .LBB0_211
	global_load_dword v47, v45, s[76:77] offset:32
.LBB0_211:
	v_add_u32_e32 v49, v7, v65
	s_and_b64 vcc, exec, s[0:1]
	v_or_b32_e32 v170, v66, v4
	v_mad_u64_u32 v[168:169], s[8:9], v170, s48, v[2:3]
	global_load_dword v168, v[168:169], off
	s_waitcnt vmcnt(1)
	v_mul_f32_e32 v47, v47, v160
	ds_write_b32 v49, v47
	s_cbranch_vccnz .LBB0_213
	global_load_dword v46, v45, s[76:77] offset:40
.LBB0_213:
	v_add_u32_e32 v49, v7, v67
	v_mov_b32_e32 v47, 1.0
	s_and_b64 vcc, exec, s[0:1]
	v_or_b32_e32 v160, v68, v4
	v_mad_u64_u32 v[160:161], s[8:9], v160, s48, v[2:3]
	global_load_dword v160, v[160:161], off
	s_waitcnt vmcnt(1)
	v_mul_f32_e32 v46, v46, v168
	ds_write_b32 v49, v46
	v_mov_b32_e32 v46, 1.0
	s_cbranch_vccnz .LBB0_215
	global_load_dword v46, v45, s[76:77] offset:48
.LBB0_215:
	v_add_u32_e32 v49, v7, v69
	s_and_b64 vcc, exec, s[0:1]
	v_or_b32_e32 v170, v70, v4
	v_mad_u64_u32 v[168:169], s[8:9], v170, s48, v[2:3]
	global_load_dword v168, v[168:169], off
	s_waitcnt vmcnt(1)
	v_mul_f32_e32 v46, v46, v160
	ds_write_b32 v49, v46
	s_cbranch_vccnz .LBB0_217
	global_load_dword v47, v45, s[76:77] offset:56
.LBB0_217:
	v_add_u32_e32 v49, v7, v71
	v_mov_b32_e32 v46, 1.0
	s_and_b64 vcc, exec, s[0:1]
	v_or_b32_e32 v160, v72, v4
	v_mad_u64_u32 v[160:161], s[8:9], v160, s48, v[2:3]
	global_load_dword v160, v[160:161], off
	s_waitcnt vmcnt(1)
	v_mul_f32_e32 v47, v47, v168
	ds_write_b32 v49, v47
	v_mov_b32_e32 v47, 1.0
	s_cbranch_vccnz .LBB0_219
	global_load_dword v47, v45, s[76:77] offset:64
.LBB0_219:
	v_add_u32_e32 v49, v7, v73
	s_and_b64 vcc, exec, s[0:1]
	v_or_b32_e32 v170, v74, v4
	v_mad_u64_u32 v[168:169], s[8:9], v170, s48, v[2:3]
	global_load_dword v168, v[168:169], off
	s_waitcnt vmcnt(1)
	v_mul_f32_e32 v47, v47, v160
	ds_write_b32 v49, v47
	s_cbranch_vccnz .LBB0_221
	global_load_dword v46, v45, s[76:77] offset:72
.LBB0_221:
	v_add_u32_e32 v49, v7, v75
	v_mov_b32_e32 v47, 1.0
	s_and_b64 vcc, exec, s[0:1]
	v_or_b32_e32 v160, v76, v4
	v_mad_u64_u32 v[160:161], s[8:9], v160, s48, v[2:3]
	global_load_dword v160, v[160:161], off
	s_waitcnt vmcnt(1)
	v_mul_f32_e32 v46, v46, v168
	ds_write_b32 v49, v46
	v_mov_b32_e32 v46, 1.0
	s_cbranch_vccnz .LBB0_223
	global_load_dword v46, v45, s[76:77] offset:80
.LBB0_223:
	v_add_u32_e32 v49, v7, v77
	s_and_b64 vcc, exec, s[0:1]
	v_or_b32_e32 v170, v78, v4
	v_mad_u64_u32 v[168:169], s[8:9], v170, s48, v[2:3]
	global_load_dword v168, v[168:169], off
	s_waitcnt vmcnt(1)
	v_mul_f32_e32 v46, v46, v160
	ds_write_b32 v49, v46
	s_cbranch_vccnz .LBB0_225
	global_load_dword v47, v45, s[76:77] offset:88
.LBB0_225:
	v_add_u32_e32 v49, v7, v79
	v_mov_b32_e32 v46, 1.0
	s_and_b64 vcc, exec, s[0:1]
	v_or_b32_e32 v160, v80, v4
	v_mad_u64_u32 v[160:161], s[8:9], v160, s48, v[2:3]
	global_load_dword v160, v[160:161], off
	s_waitcnt vmcnt(1)
	v_mul_f32_e32 v47, v47, v168
	ds_write_b32 v49, v47
	v_mov_b32_e32 v47, 1.0
	s_cbranch_vccnz .LBB0_227
	global_load_dword v47, v45, s[76:77] offset:96
.LBB0_227:
	v_add_u32_e32 v49, v7, v81
	s_and_b64 vcc, exec, s[0:1]
	v_or_b32_e32 v170, v82, v4
	v_mad_u64_u32 v[168:169], s[8:9], v170, s48, v[2:3]
	global_load_dword v168, v[168:169], off
	s_waitcnt vmcnt(1)
	v_mul_f32_e32 v47, v47, v160
	ds_write_b32 v49, v47
	s_cbranch_vccnz .LBB0_229
	global_load_dword v46, v45, s[76:77] offset:104
.LBB0_229:
	v_add_u32_e32 v49, v7, v83
	v_mov_b32_e32 v47, 1.0
	s_and_b64 vcc, exec, s[0:1]
	v_or_b32_e32 v160, v84, v4
	v_mad_u64_u32 v[160:161], s[8:9], v160, s48, v[2:3]
	global_load_dword v160, v[160:161], off
	s_waitcnt vmcnt(1)
	v_mul_f32_e32 v46, v46, v168
	ds_write_b32 v49, v46
	v_mov_b32_e32 v46, 1.0
	s_cbranch_vccnz .LBB0_231
	global_load_dword v46, v45, s[76:77] offset:112
.LBB0_231:
	v_add_u32_e32 v49, v7, v85
	s_and_b64 vcc, exec, s[0:1]
	v_or_b32_e32 v170, v86, v4
	v_mad_u64_u32 v[168:169], s[8:9], v170, s48, v[2:3]
	global_load_dword v168, v[168:169], off
	s_waitcnt vmcnt(1)
	v_mul_f32_e32 v46, v46, v160
	ds_write_b32 v49, v46
	s_cbranch_vccnz .LBB0_233
	global_load_dword v47, v45, s[76:77] offset:120
.LBB0_233:
	v_add_u32_e32 v49, v7, v87
	v_mov_b32_e32 v46, 1.0
	s_and_b64 vcc, exec, s[0:1]
	v_or_b32_e32 v160, v88, v4
	v_mad_u64_u32 v[160:161], s[8:9], v160, s48, v[2:3]
	global_load_dword v160, v[160:161], off
	s_waitcnt vmcnt(1)
	v_mul_f32_e32 v47, v47, v168
	ds_write_b32 v49, v47
	v_mov_b32_e32 v47, 1.0
	s_cbranch_vccnz .LBB0_235
	global_load_dword v47, v45, s[76:77] offset:128
.LBB0_235:
	v_add_u32_e32 v49, v7, v89
	s_and_b64 vcc, exec, s[0:1]
	v_or_b32_e32 v170, v90, v4
	v_mad_u64_u32 v[168:169], s[8:9], v170, s48, v[2:3]
	global_load_dword v168, v[168:169], off
	s_waitcnt vmcnt(1)
	v_mul_f32_e32 v47, v47, v160
	ds_write_b32 v49, v47
	s_cbranch_vccnz .LBB0_237
	global_load_dword v46, v45, s[76:77] offset:136
.LBB0_237:
	v_add_u32_e32 v49, v7, v91
	v_mov_b32_e32 v47, 1.0
	s_and_b64 vcc, exec, s[0:1]
	v_or_b32_e32 v160, v92, v4
	v_mad_u64_u32 v[160:161], s[8:9], v160, s48, v[2:3]
	global_load_dword v160, v[160:161], off
	s_waitcnt vmcnt(1)
	v_mul_f32_e32 v46, v46, v168
	ds_write_b32 v49, v46
	v_mov_b32_e32 v46, 1.0
	s_cbranch_vccnz .LBB0_239
	global_load_dword v46, v45, s[76:77] offset:144
.LBB0_239:
	v_add_u32_e32 v49, v7, v93
	s_and_b64 vcc, exec, s[0:1]
	v_or_b32_e32 v170, v94, v4
	v_mad_u64_u32 v[168:169], s[8:9], v170, s48, v[2:3]
	global_load_dword v168, v[168:169], off
	s_waitcnt vmcnt(1)
	v_mul_f32_e32 v46, v46, v160
	ds_write_b32 v49, v46
	s_cbranch_vccnz .LBB0_241
	global_load_dword v47, v45, s[76:77] offset:152
.LBB0_241:
	v_add_u32_e32 v49, v7, v95
	v_mov_b32_e32 v46, 1.0
	s_and_b64 vcc, exec, s[0:1]
	v_or_b32_e32 v160, v96, v4
	v_mad_u64_u32 v[160:161], s[8:9], v160, s48, v[2:3]
	global_load_dword v160, v[160:161], off
	s_waitcnt vmcnt(1)
	v_mul_f32_e32 v47, v47, v168
	ds_write_b32 v49, v47
	v_mov_b32_e32 v47, 1.0
	s_cbranch_vccnz .LBB0_243
	global_load_dword v47, v45, s[76:77] offset:160
.LBB0_243:
	v_add_u32_e32 v49, v7, v97
	s_and_b64 vcc, exec, s[0:1]
	v_or_b32_e32 v170, v98, v4
	v_mad_u64_u32 v[168:169], s[8:9], v170, s48, v[2:3]
	global_load_dword v168, v[168:169], off
	s_waitcnt vmcnt(1)
	v_mul_f32_e32 v47, v47, v160
	ds_write_b32 v49, v47
	s_cbranch_vccnz .LBB0_245
	global_load_dword v46, v45, s[76:77] offset:168
.LBB0_245:
	v_add_u32_e32 v49, v7, v99
	v_mov_b32_e32 v47, 1.0
	s_and_b64 vcc, exec, s[0:1]
	v_or_b32_e32 v160, v100, v4
	v_mad_u64_u32 v[160:161], s[8:9], v160, s48, v[2:3]
	global_load_dword v160, v[160:161], off
	s_waitcnt vmcnt(1)
	v_mul_f32_e32 v46, v46, v168
	ds_write_b32 v49, v46
	v_mov_b32_e32 v46, 1.0
	s_cbranch_vccnz .LBB0_247
	global_load_dword v46, v45, s[76:77] offset:176
.LBB0_247:
	v_add_u32_e32 v49, v7, v101
	s_and_b64 vcc, exec, s[0:1]
	v_or_b32_e32 v170, v102, v4
	v_mad_u64_u32 v[168:169], s[8:9], v170, s48, v[2:3]
	global_load_dword v170, v[168:169], off
	s_waitcnt vmcnt(1)
	v_mul_f32_e32 v46, v46, v160
	ds_write_b32 v49, v46
	s_cbranch_vccnz .LBB0_249
	global_load_dword v47, v45, s[76:77] offset:184
.LBB0_249:
	v_add_u32_e32 v49, v7, v103
	v_mov_b32_e32 v48, 1.0
	s_and_b64 vcc, exec, s[0:1]
	v_or_b32_e32 v162, v104, v4
	v_mad_u64_u32 v[160:161], s[8:9], v162, s48, v[2:3]
	global_load_dword v163, v[160:161], off
	s_waitcnt vmcnt(1)
	v_mul_f32_e32 v46, v47, v170
	v_mov_b32_e32 v47, 1.0
	ds_write_b32 v49, v46
	s_cbranch_vccnz .LBB0_251
	global_load_dword v47, v45, s[76:77] offset:192
.LBB0_251:
	v_add_u32_e32 v46, v7, v105
	s_and_b64 vcc, exec, s[0:1]
	v_or_b32_e32 v170, v106, v4
	v_mad_u64_u32 v[168:169], s[8:9], v170, s48, v[2:3]
	global_load_dword v171, v[168:169], off
	s_waitcnt vmcnt(1)
	v_mul_f32_e32 v47, v47, v163
	ds_write_b32 v46, v47
	s_cbranch_vccnz .LBB0_253
	global_load_dword v48, v45, s[76:77] offset:200
.LBB0_253:
	v_mov_b32_e32 v47, 1.0
	s_and_b64 vcc, exec, s[0:1]
	v_or_b32_e32 v162, v107, v4
	v_mad_u64_u32 v[160:161], s[8:9], v162, s48, v[2:3]
	global_load_dword v162, v[160:161], off
	s_waitcnt vmcnt(1)
	v_mul_f32_e32 v48, v48, v171
	ds_write_b32 v46, v48 offset:264
	v_mov_b32_e32 v48, 1.0
	s_cbranch_vccnz .LBB0_255
	global_load_dword v48, v45, s[76:77] offset:208
.LBB0_255:
	s_and_b64 vcc, exec, s[0:1]
	v_or_b32_e32 v168, v108, v4
	v_mad_u64_u32 v[168:169], s[8:9], v168, s48, v[2:3]
	global_load_dword v169, v[168:169], off
	s_waitcnt vmcnt(1)
	v_mul_f32_e32 v48, v48, v162
	ds_write_b32 v46, v48 offset:528
	s_cbranch_vccnz .LBB0_257
	global_load_dword v47, v45, s[76:77] offset:216
.LBB0_257:
	v_mov_b32_e32 v48, 1.0
	s_and_b64 vcc, exec, s[0:1]
	v_or_b32_e32 v162, v109, v4
	v_mad_u64_u32 v[160:161], s[8:9], v162, s48, v[2:3]
	global_load_dword v162, v[160:161], off
	s_waitcnt vmcnt(1)
	v_mul_f32_e32 v47, v47, v169
	ds_write_b32 v46, v47 offset:792
	v_mov_b32_e32 v47, 1.0
	s_cbranch_vccnz .LBB0_259
	global_load_dword v47, v45, s[76:77] offset:224
.LBB0_259:
	s_and_b64 vcc, exec, s[0:1]
	v_or_b32_e32 v170, v110, v4
	v_mad_u64_u32 v[168:169], s[8:9], v170, s48, v[2:3]
	global_load_dword v171, v[168:169], off
	s_waitcnt vmcnt(1)
	v_mul_f32_e32 v47, v47, v162
	ds_write_b32 v46, v47 offset:1056
	s_cbranch_vccnz .LBB0_261
	global_load_dword v48, v45, s[76:77] offset:232
.LBB0_261:
	v_mov_b32_e32 v47, 1.0
	s_and_b64 vcc, exec, s[0:1]
	v_or_b32_e32 v162, v111, v4
	v_mad_u64_u32 v[160:161], s[8:9], v162, s48, v[2:3]
	global_load_dword v162, v[160:161], off
	s_waitcnt vmcnt(1)
	v_mul_f32_e32 v48, v48, v171
	ds_write_b32 v46, v48 offset:1320
	v_mov_b32_e32 v48, 1.0
	s_cbranch_vccnz .LBB0_263
	global_load_dword v48, v45, s[76:77] offset:240
.LBB0_263:
	s_and_b64 vcc, exec, s[0:1]
	s_waitcnt vmcnt(0)
	v_mul_f32_e32 v48, v48, v162
	ds_write_b32 v46, v48 offset:1584
	s_cbranch_vccnz .LBB0_265
	global_load_dword v47, v45, s[76:77] offset:248

.LBB0_270:
	s_movk_i32 s8, 0xea00
	v_mad_u64_u32 v[44:45], s[8:9], v48, s8, v[42:43]
	v_ashrrev_i32_e32 v45, 31, v44
	v_lshl_add_u64 v[4:5], v[44:45], 2, v[40:41]
	v_mad_i64_i32 v[46:47], s[8:9], v46, s48, v[4:5]
	global_load_dword v45, v[46:47], off
	v_add_u32_e32 v46, v7, v13
	s_and_b64 vcc, exec, s[0:1]
	v_or_b32_e32 v170, v2, v58
	v_mad_i64_i32 v[168:169], s[8:9], v170, s48, v[4:5]
	global_load_dword v168, v[168:169], off
	s_waitcnt vmcnt(1)
	v_mul_f32_e32 v3, v3, v45
	ds_write_b32 v46, v3
	v_ashrrev_i32_e32 v3, 31, v2
	s_cbranch_vccnz .LBB0_272
	v_readlane_b32 s52, v252, 14
	v_lshl_add_u64 v[46:47], v[2:3], 0, v[8:9]
	v_readlane_b32 s56, v252, 18
	v_readlane_b32 s57, v252, 19
	v_readlane_b32 s53, v252, 15
	v_readlane_b32 s54, v252, 16
	v_lshl_add_u64 v[46:47], v[46:47], 2, s[56:57]
	global_load_dword v49, v[46:47], off offset:8
	v_readlane_b32 s55, v252, 17
	v_readlane_b32 s58, v252, 20
	v_readlane_b32 s59, v252, 21
	v_readlane_b32 s60, v252, 22
	v_readlane_b32 s61, v252, 23
	v_readlane_b32 s62, v252, 24
	v_readlane_b32 s63, v252, 25
	v_readlane_b32 s64, v252, 26
	v_readlane_b32 s65, v252, 27
	v_readlane_b32 s66, v252, 28
	v_readlane_b32 s67, v252, 29
.LBB0_272:
	v_add_u32_e32 v47, v7, v59
	v_mov_b32_e32 v45, 1.0
	s_and_b64 vcc, exec, s[0:1]
	v_or_b32_e32 v162, v2, v60
	v_mad_i64_i32 v[160:161], s[8:9], v162, s48, v[4:5]
	global_load_dword v162, v[160:161], off
	s_waitcnt vmcnt(1)
	v_mul_f32_e32 v46, v49, v168
	ds_write_b32 v47, v46
	v_mov_b32_e32 v46, 1.0
	s_cbranch_vccnz .LBB0_274
	v_readlane_b32 s52, v252, 14
	v_lshl_add_u64 v[46:47], v[2:3], 0, v[8:9]
	v_readlane_b32 s56, v252, 18
	v_readlane_b32 s57, v252, 19
	v_readlane_b32 s53, v252, 15
	v_readlane_b32 s54, v252, 16
	v_lshl_add_u64 v[46:47], v[46:47], 2, s[56:57]
	global_load_dword v46, v[46:47], off offset:16
	v_readlane_b32 s55, v252, 17
	v_readlane_b32 s58, v252, 20
	v_readlane_b32 s59, v252, 21
	v_readlane_b32 s60, v252, 22
	v_readlane_b32 s61, v252, 23
	v_readlane_b32 s62, v252, 24
	v_readlane_b32 s63, v252, 25
	v_readlane_b32 s64, v252, 26
	v_readlane_b32 s65, v252, 27
	v_readlane_b32 s66, v252, 28
	v_readlane_b32 s67, v252, 29
.LBB0_274:
	v_add_u32_e32 v49, v7, v61
	s_and_b64 vcc, exec, s[0:1]
	v_or_b32_e32 v168, v2, v62
	v_mad_i64_i32 v[168:169], s[8:9], v168, s48, v[4:5]
	global_load_dword v169, v[168:169], off
	s_waitcnt vmcnt(1)
	v_mul_f32_e32 v46, v46, v162
	ds_write_b32 v49, v46
	s_cbranch_vccnz .LBB0_276
	v_readlane_b32 s52, v252, 14
	v_lshl_add_u64 v[46:47], v[2:3], 0, v[8:9]
	v_readlane_b32 s56, v252, 18
	v_readlane_b32 s57, v252, 19
	v_readlane_b32 s53, v252, 15
	v_readlane_b32 s54, v252, 16
	v_lshl_add_u64 v[46:47], v[46:47], 2, s[56:57]
	global_load_dword v45, v[46:47], off offset:24
	v_readlane_b32 s55, v252, 17
	v_readlane_b32 s58, v252, 20
	v_readlane_b32 s59, v252, 21
	v_readlane_b32 s60, v252, 22
	v_readlane_b32 s61, v252, 23
	v_readlane_b32 s62, v252, 24
	v_readlane_b32 s63, v252, 25
	v_readlane_b32 s64, v252, 26
	v_readlane_b32 s65, v252, 27
	v_readlane_b32 s66, v252, 28
	v_readlane_b32 s67, v252, 29
.LBB0_276:
	v_add_u32_e32 v49, v7, v63
	v_mov_b32_e32 v46, 1.0
	s_and_b64 vcc, exec, s[0:1]
	v_or_b32_e32 v162, v2, v64
	v_mad_i64_i32 v[160:161], s[8:9], v162, s48, v[4:5]
	global_load_dword v162, v[160:161], off
	s_waitcnt vmcnt(1)
	v_mul_f32_e32 v45, v45, v169
	ds_write_b32 v49, v45
	v_mov_b32_e32 v45, 1.0
	s_cbranch_vccnz .LBB0_278
	v_readlane_b32 s52, v252, 14
	v_lshl_add_u64 v[50:51], v[2:3], 0, v[8:9]
	v_readlane_b32 s56, v252, 18
	v_readlane_b32 s57, v252, 19
	v_readlane_b32 s53, v252, 15
	v_readlane_b32 s54, v252, 16
	v_lshl_add_u64 v[50:51], v[50:51], 2, s[56:57]
	global_load_dword v45, v[50:51], off offset:32
	v_readlane_b32 s55, v252, 17
	v_readlane_b32 s58, v252, 20
	v_readlane_b32 s59, v252, 21
	v_readlane_b32 s60, v252, 22
	v_readlane_b32 s61, v252, 23
	v_readlane_b32 s62, v252, 24
	v_readlane_b32 s63, v252, 25
	v_readlane_b32 s64, v252, 26
	v_readlane_b32 s65, v252, 27
	v_readlane_b32 s66, v252, 28
	v_readlane_b32 s67, v252, 29
.LBB0_278:
	v_add_u32_e32 v49, v7, v65
	s_and_b64 vcc, exec, s[0:1]
	v_or_b32_e32 v170, v2, v66
	v_mad_i64_i32 v[168:169], s[8:9], v170, s48, v[4:5]
	global_load_dword v171, v[168:169], off
	s_waitcnt vmcnt(1)
	v_mul_f32_e32 v45, v45, v162
	ds_write_b32 v49, v45
	s_cbranch_vccnz .LBB0_280
	v_readlane_b32 s52, v252, 14
	v_lshl_add_u64 v[46:47], v[2:3], 0, v[8:9]
	v_readlane_b32 s56, v252, 18
	v_readlane_b32 s57, v252, 19
	v_readlane_b32 s53, v252, 15
	v_readlane_b32 s54, v252, 16
	v_lshl_add_u64 v[46:47], v[46:47], 2, s[56:57]
	global_load_dword v46, v[46:47], off offset:40
	v_readlane_b32 s55, v252, 17
	v_readlane_b32 s58, v252, 20
	v_readlane_b32 s59, v252, 21
	v_readlane_b32 s60, v252, 22
	v_readlane_b32 s61, v252, 23
	v_readlane_b32 s62, v252, 24
	v_readlane_b32 s63, v252, 25
	v_readlane_b32 s64, v252, 26
	v_readlane_b32 s65, v252, 27
	v_readlane_b32 s66, v252, 28
	v_readlane_b32 s67, v252, 29
.LBB0_280:
	v_add_u32_e32 v49, v7, v67
	v_mov_b32_e32 v45, 1.0
	s_and_b64 vcc, exec, s[0:1]
	v_or_b32_e32 v162, v2, v68
	v_mad_i64_i32 v[160:161], s[8:9], v162, s48, v[4:5]
	global_load_dword v162, v[160:161], off
	s_waitcnt vmcnt(1)
	v_mul_f32_e32 v46, v46, v171
	ds_write_b32 v49, v46
	v_mov_b32_e32 v46, 1.0
	s_cbranch_vccnz .LBB0_282
	v_readlane_b32 s52, v252, 14
	v_lshl_add_u64 v[46:47], v[2:3], 0, v[8:9]
	v_readlane_b32 s56, v252, 18
	v_readlane_b32 s57, v252, 19
	v_readlane_b32 s53, v252, 15
	v_readlane_b32 s54, v252, 16
	v_lshl_add_u64 v[46:47], v[46:47], 2, s[56:57]
	global_load_dword v46, v[46:47], off offset:48
	v_readlane_b32 s55, v252, 17
	v_readlane_b32 s58, v252, 20
	v_readlane_b32 s59, v252, 21
	v_readlane_b32 s60, v252, 22
	v_readlane_b32 s61, v252, 23
	v_readlane_b32 s62, v252, 24
	v_readlane_b32 s63, v252, 25
	v_readlane_b32 s64, v252, 26
	v_readlane_b32 s65, v252, 27
	v_readlane_b32 s66, v252, 28
	v_readlane_b32 s67, v252, 29
.LBB0_282:
	v_add_u32_e32 v49, v7, v69
	s_and_b64 vcc, exec, s[0:1]
	v_or_b32_e32 v168, v2, v70
	v_mad_i64_i32 v[168:169], s[8:9], v168, s48, v[4:5]
	global_load_dword v169, v[168:169], off
	s_waitcnt vmcnt(1)
	v_mul_f32_e32 v46, v46, v162
	ds_write_b32 v49, v46
	s_cbranch_vccnz .LBB0_284
	v_readlane_b32 s52, v252, 14
	v_lshl_add_u64 v[46:47], v[2:3], 0, v[8:9]
	v_readlane_b32 s56, v252, 18
	v_readlane_b32 s57, v252, 19
	v_readlane_b32 s53, v252, 15
	v_readlane_b32 s54, v252, 16
	v_lshl_add_u64 v[46:47], v[46:47], 2, s[56:57]
	global_load_dword v45, v[46:47], off offset:56
	v_readlane_b32 s55, v252, 17
	v_readlane_b32 s58, v252, 20
	v_readlane_b32 s59, v252, 21
	v_readlane_b32 s60, v252, 22
	v_readlane_b32 s61, v252, 23
	v_readlane_b32 s62, v252, 24
	v_readlane_b32 s63, v252, 25
	v_readlane_b32 s64, v252, 26
	v_readlane_b32 s65, v252, 27
	v_readlane_b32 s66, v252, 28
	v_readlane_b32 s67, v252, 29
.LBB0_284:
	v_add_u32_e32 v49, v7, v71
	v_mov_b32_e32 v46, 1.0
	s_and_b64 vcc, exec, s[0:1]
	v_or_b32_e32 v162, v2, v72
	v_mad_i64_i32 v[160:161], s[8:9], v162, s48, v[4:5]
	global_load_dword v162, v[160:161], off
	s_waitcnt vmcnt(1)
	v_mul_f32_e32 v45, v45, v169
	ds_write_b32 v49, v45
	v_mov_b32_e32 v45, 1.0
	s_cbranch_vccnz .LBB0_286
	v_readlane_b32 s52, v252, 14
	v_lshl_add_u64 v[50:51], v[2:3], 0, v[8:9]
	v_readlane_b32 s56, v252, 18
	v_readlane_b32 s57, v252, 19
	v_readlane_b32 s53, v252, 15
	v_readlane_b32 s54, v252, 16
	v_lshl_add_u64 v[50:51], v[50:51], 2, s[56:57]
	global_load_dword v45, v[50:51], off offset:64
	v_readlane_b32 s55, v252, 17
	v_readlane_b32 s58, v252, 20
	v_readlane_b32 s59, v252, 21
	v_readlane_b32 s60, v252, 22
	v_readlane_b32 s61, v252, 23
	v_readlane_b32 s62, v252, 24
	v_readlane_b32 s63, v252, 25
	v_readlane_b32 s64, v252, 26
	v_readlane_b32 s65, v252, 27
	v_readlane_b32 s66, v252, 28
	v_readlane_b32 s67, v252, 29
.LBB0_286:
	v_add_u32_e32 v49, v7, v73
	s_and_b64 vcc, exec, s[0:1]
	v_or_b32_e32 v170, v2, v74
	v_mad_i64_i32 v[168:169], s[8:9], v170, s48, v[4:5]
	global_load_dword v171, v[168:169], off
	s_waitcnt vmcnt(1)
	v_mul_f32_e32 v45, v45, v162
	ds_write_b32 v49, v45
	s_cbranch_vccnz .LBB0_288
	v_readlane_b32 s52, v252, 14
	v_lshl_add_u64 v[46:47], v[2:3], 0, v[8:9]
	v_readlane_b32 s56, v252, 18
	v_readlane_b32 s57, v252, 19
	v_readlane_b32 s53, v252, 15
	v_readlane_b32 s54, v252, 16
	v_lshl_add_u64 v[46:47], v[46:47], 2, s[56:57]
	global_load_dword v46, v[46:47], off offset:72
	v_readlane_b32 s55, v252, 17
	v_readlane_b32 s58, v252, 20
	v_readlane_b32 s59, v252, 21
	v_readlane_b32 s60, v252, 22
	v_readlane_b32 s61, v252, 23
	v_readlane_b32 s62, v252, 24
	v_readlane_b32 s63, v252, 25
	v_readlane_b32 s64, v252, 26
	v_readlane_b32 s65, v252, 27
	v_readlane_b32 s66, v252, 28
	v_readlane_b32 s67, v252, 29
.LBB0_288:
	v_add_u32_e32 v49, v7, v75
	v_mov_b32_e32 v45, 1.0
	s_and_b64 vcc, exec, s[0:1]
	v_or_b32_e32 v162, v2, v76
	v_mad_i64_i32 v[160:161], s[8:9], v162, s48, v[4:5]
	global_load_dword v162, v[160:161], off
	s_waitcnt vmcnt(1)
	v_mul_f32_e32 v46, v46, v171
	ds_write_b32 v49, v46
	v_mov_b32_e32 v46, 1.0
	s_cbranch_vccnz .LBB0_290
	v_readlane_b32 s52, v252, 14
	v_lshl_add_u64 v[46:47], v[2:3], 0, v[8:9]
	v_readlane_b32 s56, v252, 18
	v_readlane_b32 s57, v252, 19
	v_readlane_b32 s53, v252, 15
	v_readlane_b32 s54, v252, 16
	v_lshl_add_u64 v[46:47], v[46:47], 2, s[56:57]
	global_load_dword v46, v[46:47], off offset:80
	v_readlane_b32 s55, v252, 17
	v_readlane_b32 s58, v252, 20
	v_readlane_b32 s59, v252, 21
	v_readlane_b32 s60, v252, 22
	v_readlane_b32 s61, v252, 23
	v_readlane_b32 s62, v252, 24
	v_readlane_b32 s63, v252, 25
	v_readlane_b32 s64, v252, 26
	v_readlane_b32 s65, v252, 27
	v_readlane_b32 s66, v252, 28
	v_readlane_b32 s67, v252, 29
.LBB0_290:
	v_add_u32_e32 v49, v7, v77
	s_and_b64 vcc, exec, s[0:1]
	v_or_b32_e32 v168, v2, v78
	v_mad_i64_i32 v[168:169], s[8:9], v168, s48, v[4:5]
	global_load_dword v169, v[168:169], off
	s_waitcnt vmcnt(1)
	v_mul_f32_e32 v46, v46, v162
	ds_write_b32 v49, v46
	s_cbranch_vccnz .LBB0_292
	v_readlane_b32 s52, v252, 14
	v_lshl_add_u64 v[46:47], v[2:3], 0, v[8:9]
	v_readlane_b32 s56, v252, 18
	v_readlane_b32 s57, v252, 19
	v_readlane_b32 s53, v252, 15
	v_readlane_b32 s54, v252, 16
	v_lshl_add_u64 v[46:47], v[46:47], 2, s[56:57]
	global_load_dword v45, v[46:47], off offset:88
	v_readlane_b32 s55, v252, 17
	v_readlane_b32 s58, v252, 20
	v_readlane_b32 s59, v252, 21
	v_readlane_b32 s60, v252, 22
	v_readlane_b32 s61, v252, 23
	v_readlane_b32 s62, v252, 24
	v_readlane_b32 s63, v252, 25
	v_readlane_b32 s64, v252, 26
	v_readlane_b32 s65, v252, 27
	v_readlane_b32 s66, v252, 28
	v_readlane_b32 s67, v252, 29
.LBB0_292:
	v_add_u32_e32 v49, v7, v79
	v_mov_b32_e32 v46, 1.0
	s_and_b64 vcc, exec, s[0:1]
	v_or_b32_e32 v162, v2, v80
	v_mad_i64_i32 v[160:161], s[8:9], v162, s48, v[4:5]
	global_load_dword v162, v[160:161], off
	s_waitcnt vmcnt(1)
	v_mul_f32_e32 v45, v45, v169
	ds_write_b32 v49, v45
	v_mov_b32_e32 v45, 1.0
	s_cbranch_vccnz .LBB0_294
	v_readlane_b32 s52, v252, 14
	v_lshl_add_u64 v[50:51], v[2:3], 0, v[8:9]
	v_readlane_b32 s56, v252, 18
	v_readlane_b32 s57, v252, 19
	v_readlane_b32 s53, v252, 15
	v_readlane_b32 s54, v252, 16
	v_lshl_add_u64 v[50:51], v[50:51], 2, s[56:57]
	global_load_dword v45, v[50:51], off offset:96
	v_readlane_b32 s55, v252, 17
	v_readlane_b32 s58, v252, 20
	v_readlane_b32 s59, v252, 21
	v_readlane_b32 s60, v252, 22
	v_readlane_b32 s61, v252, 23
	v_readlane_b32 s62, v252, 24
	v_readlane_b32 s63, v252, 25
	v_readlane_b32 s64, v252, 26
	v_readlane_b32 s65, v252, 27
	v_readlane_b32 s66, v252, 28
	v_readlane_b32 s67, v252, 29
.LBB0_294:
	v_add_u32_e32 v49, v7, v81
	s_and_b64 vcc, exec, s[0:1]
	v_or_b32_e32 v170, v2, v82
	v_mad_i64_i32 v[168:169], s[8:9], v170, s48, v[4:5]
	global_load_dword v171, v[168:169], off
	s_waitcnt vmcnt(1)
	v_mul_f32_e32 v45, v45, v162
	ds_write_b32 v49, v45
	s_cbranch_vccnz .LBB0_296
	v_readlane_b32 s52, v252, 14
	v_lshl_add_u64 v[46:47], v[2:3], 0, v[8:9]
	v_readlane_b32 s56, v252, 18
	v_readlane_b32 s57, v252, 19
	v_readlane_b32 s53, v252, 15
	v_readlane_b32 s54, v252, 16
	v_lshl_add_u64 v[46:47], v[46:47], 2, s[56:57]
	global_load_dword v46, v[46:47], off offset:104
	v_readlane_b32 s55, v252, 17
	v_readlane_b32 s58, v252, 20
	v_readlane_b32 s59, v252, 21
	v_readlane_b32 s60, v252, 22
	v_readlane_b32 s61, v252, 23
	v_readlane_b32 s62, v252, 24
	v_readlane_b32 s63, v252, 25
	v_readlane_b32 s64, v252, 26
	v_readlane_b32 s65, v252, 27
	v_readlane_b32 s66, v252, 28
	v_readlane_b32 s67, v252, 29
.LBB0_296:
	v_add_u32_e32 v49, v7, v83
	v_mov_b32_e32 v45, 1.0
	s_and_b64 vcc, exec, s[0:1]
	v_or_b32_e32 v162, v2, v84
	v_mad_i64_i32 v[160:161], s[8:9], v162, s48, v[4:5]
	global_load_dword v162, v[160:161], off
	s_waitcnt vmcnt(1)
	v_mul_f32_e32 v46, v46, v171
	ds_write_b32 v49, v46
	v_mov_b32_e32 v46, 1.0
	s_cbranch_vccnz .LBB0_298
	v_readlane_b32 s52, v252, 14
	v_lshl_add_u64 v[46:47], v[2:3], 0, v[8:9]
	v_readlane_b32 s56, v252, 18
	v_readlane_b32 s57, v252, 19
	v_readlane_b32 s53, v252, 15
	v_readlane_b32 s54, v252, 16
	v_lshl_add_u64 v[46:47], v[46:47], 2, s[56:57]
	global_load_dword v46, v[46:47], off offset:112
	v_readlane_b32 s55, v252, 17
	v_readlane_b32 s58, v252, 20
	v_readlane_b32 s59, v252, 21
	v_readlane_b32 s60, v252, 22
	v_readlane_b32 s61, v252, 23
	v_readlane_b32 s62, v252, 24
	v_readlane_b32 s63, v252, 25
	v_readlane_b32 s64, v252, 26
	v_readlane_b32 s65, v252, 27
	v_readlane_b32 s66, v252, 28
	v_readlane_b32 s67, v252, 29
.LBB0_298:
	v_add_u32_e32 v49, v7, v85
	s_and_b64 vcc, exec, s[0:1]
	v_or_b32_e32 v168, v2, v86
	v_mad_i64_i32 v[168:169], s[8:9], v168, s48, v[4:5]
	global_load_dword v169, v[168:169], off
	s_waitcnt vmcnt(1)
	v_mul_f32_e32 v46, v46, v162
	ds_write_b32 v49, v46
	s_cbranch_vccnz .LBB0_300
	v_readlane_b32 s52, v252, 14
	v_lshl_add_u64 v[46:47], v[2:3], 0, v[8:9]
	v_readlane_b32 s56, v252, 18
	v_readlane_b32 s57, v252, 19
	v_readlane_b32 s53, v252, 15
	v_readlane_b32 s54, v252, 16
	v_lshl_add_u64 v[46:47], v[46:47], 2, s[56:57]
	global_load_dword v45, v[46:47], off offset:120
	v_readlane_b32 s55, v252, 17
	v_readlane_b32 s58, v252, 20
	v_readlane_b32 s59, v252, 21
	v_readlane_b32 s60, v252, 22
	v_readlane_b32 s61, v252, 23
	v_readlane_b32 s62, v252, 24
	v_readlane_b32 s63, v252, 25
	v_readlane_b32 s64, v252, 26
	v_readlane_b32 s65, v252, 27
	v_readlane_b32 s66, v252, 28
	v_readlane_b32 s67, v252, 29
.LBB0_300:
	v_add_u32_e32 v49, v7, v87
	v_mov_b32_e32 v46, 1.0
	s_and_b64 vcc, exec, s[0:1]
	v_or_b32_e32 v162, v2, v88
	v_mad_i64_i32 v[160:161], s[8:9], v162, s48, v[4:5]
	global_load_dword v162, v[160:161], off
	s_waitcnt vmcnt(1)
	v_mul_f32_e32 v45, v45, v169
	ds_write_b32 v49, v45
	v_mov_b32_e32 v45, 1.0
	s_cbranch_vccnz .LBB0_302
	v_readlane_b32 s52, v252, 14
	v_lshl_add_u64 v[50:51], v[2:3], 0, v[8:9]
	v_readlane_b32 s56, v252, 18
	v_readlane_b32 s57, v252, 19
	v_readlane_b32 s53, v252, 15
	v_readlane_b32 s54, v252, 16
	v_lshl_add_u64 v[50:51], v[50:51], 2, s[56:57]
	global_load_dword v45, v[50:51], off offset:128
	v_readlane_b32 s55, v252, 17
	v_readlane_b32 s58, v252, 20
	v_readlane_b32 s59, v252, 21
	v_readlane_b32 s60, v252, 22
	v_readlane_b32 s61, v252, 23
	v_readlane_b32 s62, v252, 24
	v_readlane_b32 s63, v252, 25
	v_readlane_b32 s64, v252, 26
	v_readlane_b32 s65, v252, 27
	v_readlane_b32 s66, v252, 28
	v_readlane_b32 s67, v252, 29
.LBB0_302:
	v_add_u32_e32 v49, v7, v89
	s_and_b64 vcc, exec, s[0:1]
	v_or_b32_e32 v170, v2, v90
	v_mad_i64_i32 v[168:169], s[8:9], v170, s48, v[4:5]
	global_load_dword v171, v[168:169], off
	s_waitcnt vmcnt(1)
	v_mul_f32_e32 v45, v45, v162
	ds_write_b32 v49, v45
	s_cbranch_vccnz .LBB0_304
	v_readlane_b32 s52, v252, 14
	v_lshl_add_u64 v[46:47], v[2:3], 0, v[8:9]
	v_readlane_b32 s56, v252, 18
	v_readlane_b32 s57, v252, 19
	v_readlane_b32 s53, v252, 15
	v_readlane_b32 s54, v252, 16
	v_lshl_add_u64 v[46:47], v[46:47], 2, s[56:57]
	global_load_dword v46, v[46:47], off offset:136
	v_readlane_b32 s55, v252, 17
	v_readlane_b32 s58, v252, 20
	v_readlane_b32 s59, v252, 21
	v_readlane_b32 s60, v252, 22
	v_readlane_b32 s61, v252, 23
	v_readlane_b32 s62, v252, 24
	v_readlane_b32 s63, v252, 25
	v_readlane_b32 s64, v252, 26
	v_readlane_b32 s65, v252, 27
	v_readlane_b32 s66, v252, 28
	v_readlane_b32 s67, v252, 29
.LBB0_304:
	v_add_u32_e32 v49, v7, v91
	v_mov_b32_e32 v45, 1.0
	s_and_b64 vcc, exec, s[0:1]
	v_or_b32_e32 v162, v2, v92
	v_mad_i64_i32 v[160:161], s[8:9], v162, s48, v[4:5]
	global_load_dword v162, v[160:161], off
	s_waitcnt vmcnt(1)
	v_mul_f32_e32 v46, v46, v171
	ds_write_b32 v49, v46
	v_mov_b32_e32 v46, 1.0
	s_cbranch_vccnz .LBB0_306
	v_readlane_b32 s52, v252, 14
	v_lshl_add_u64 v[46:47], v[2:3], 0, v[8:9]
	v_readlane_b32 s56, v252, 18
	v_readlane_b32 s57, v252, 19
	v_readlane_b32 s53, v252, 15
	v_readlane_b32 s54, v252, 16
	v_lshl_add_u64 v[46:47], v[46:47], 2, s[56:57]
	global_load_dword v46, v[46:47], off offset:144
	v_readlane_b32 s55, v252, 17
	v_readlane_b32 s58, v252, 20
	v_readlane_b32 s59, v252, 21
	v_readlane_b32 s60, v252, 22
	v_readlane_b32 s61, v252, 23
	v_readlane_b32 s62, v252, 24
	v_readlane_b32 s63, v252, 25
	v_readlane_b32 s64, v252, 26
	v_readlane_b32 s65, v252, 27
	v_readlane_b32 s66, v252, 28
	v_readlane_b32 s67, v252, 29
.LBB0_306:
	v_add_u32_e32 v49, v7, v93
	s_and_b64 vcc, exec, s[0:1]
	v_or_b32_e32 v168, v2, v94
	v_mad_i64_i32 v[168:169], s[8:9], v168, s48, v[4:5]
	global_load_dword v169, v[168:169], off
	s_waitcnt vmcnt(1)
	v_mul_f32_e32 v46, v46, v162
	ds_write_b32 v49, v46
	s_cbranch_vccnz .LBB0_308
	v_readlane_b32 s52, v252, 14
	v_lshl_add_u64 v[46:47], v[2:3], 0, v[8:9]
	v_readlane_b32 s56, v252, 18
	v_readlane_b32 s57, v252, 19
	v_readlane_b32 s53, v252, 15
	v_readlane_b32 s54, v252, 16
	v_lshl_add_u64 v[46:47], v[46:47], 2, s[56:57]
	global_load_dword v45, v[46:47], off offset:152
	v_readlane_b32 s55, v252, 17
	v_readlane_b32 s58, v252, 20
	v_readlane_b32 s59, v252, 21
	v_readlane_b32 s60, v252, 22
	v_readlane_b32 s61, v252, 23
	v_readlane_b32 s62, v252, 24
	v_readlane_b32 s63, v252, 25
	v_readlane_b32 s64, v252, 26
	v_readlane_b32 s65, v252, 27
	v_readlane_b32 s66, v252, 28
	v_readlane_b32 s67, v252, 29
.LBB0_308:
	v_add_u32_e32 v49, v7, v95
	v_mov_b32_e32 v46, 1.0
	s_and_b64 vcc, exec, s[0:1]
	v_or_b32_e32 v162, v2, v96
	v_mad_i64_i32 v[160:161], s[8:9], v162, s48, v[4:5]
	global_load_dword v162, v[160:161], off
	s_waitcnt vmcnt(1)
	v_mul_f32_e32 v45, v45, v169
	ds_write_b32 v49, v45
	v_mov_b32_e32 v45, 1.0
	s_cbranch_vccnz .LBB0_310
	v_readlane_b32 s52, v252, 14
	v_lshl_add_u64 v[50:51], v[2:3], 0, v[8:9]
	v_readlane_b32 s56, v252, 18
	v_readlane_b32 s57, v252, 19
	v_readlane_b32 s53, v252, 15
	v_readlane_b32 s54, v252, 16
	v_lshl_add_u64 v[50:51], v[50:51], 2, s[56:57]
	global_load_dword v45, v[50:51], off offset:160
	v_readlane_b32 s55, v252, 17
	v_readlane_b32 s58, v252, 20
	v_readlane_b32 s59, v252, 21
	v_readlane_b32 s60, v252, 22
	v_readlane_b32 s61, v252, 23
	v_readlane_b32 s62, v252, 24
	v_readlane_b32 s63, v252, 25
	v_readlane_b32 s64, v252, 26
	v_readlane_b32 s65, v252, 27
	v_readlane_b32 s66, v252, 28
	v_readlane_b32 s67, v252, 29
.LBB0_310:
	v_add_u32_e32 v49, v7, v97
	s_and_b64 vcc, exec, s[0:1]
	v_or_b32_e32 v170, v2, v98
	v_mad_i64_i32 v[168:169], s[8:9], v170, s48, v[4:5]
	global_load_dword v171, v[168:169], off
	s_waitcnt vmcnt(1)
	v_mul_f32_e32 v45, v45, v162
	ds_write_b32 v49, v45
	s_cbranch_vccnz .LBB0_312
	v_readlane_b32 s52, v252, 14
	v_lshl_add_u64 v[46:47], v[2:3], 0, v[8:9]
	v_readlane_b32 s56, v252, 18
	v_readlane_b32 s57, v252, 19
	v_readlane_b32 s53, v252, 15
	v_readlane_b32 s54, v252, 16
	v_lshl_add_u64 v[46:47], v[46:47], 2, s[56:57]
	global_load_dword v46, v[46:47], off offset:168
	v_readlane_b32 s55, v252, 17
	v_readlane_b32 s58, v252, 20
	v_readlane_b32 s59, v252, 21
	v_readlane_b32 s60, v252, 22
	v_readlane_b32 s61, v252, 23
	v_readlane_b32 s62, v252, 24
	v_readlane_b32 s63, v252, 25
	v_readlane_b32 s64, v252, 26
	v_readlane_b32 s65, v252, 27
	v_readlane_b32 s66, v252, 28
	v_readlane_b32 s67, v252, 29
.LBB0_312:
	v_add_u32_e32 v49, v7, v99
	v_mov_b32_e32 v45, 1.0
	s_and_b64 vcc, exec, s[0:1]
	v_or_b32_e32 v162, v2, v100
	v_mad_i64_i32 v[160:161], s[8:9], v162, s48, v[4:5]
	global_load_dword v162, v[160:161], off
	s_waitcnt vmcnt(1)
	v_mul_f32_e32 v46, v46, v171
	ds_write_b32 v49, v46
	v_mov_b32_e32 v46, 1.0
	s_cbranch_vccnz .LBB0_314
	v_readlane_b32 s52, v252, 14
	v_lshl_add_u64 v[46:47], v[2:3], 0, v[8:9]
	v_readlane_b32 s56, v252, 18
	v_readlane_b32 s57, v252, 19
	v_readlane_b32 s53, v252, 15
	v_readlane_b32 s54, v252, 16
	v_lshl_add_u64 v[46:47], v[46:47], 2, s[56:57]
	global_load_dword v46, v[46:47], off offset:176
	v_readlane_b32 s55, v252, 17
	v_readlane_b32 s58, v252, 20
	v_readlane_b32 s59, v252, 21
	v_readlane_b32 s60, v252, 22
	v_readlane_b32 s61, v252, 23
	v_readlane_b32 s62, v252, 24
	v_readlane_b32 s63, v252, 25
	v_readlane_b32 s64, v252, 26
	v_readlane_b32 s65, v252, 27
	v_readlane_b32 s66, v252, 28
	v_readlane_b32 s67, v252, 29
.LBB0_314:
	v_add_u32_e32 v49, v7, v101
	s_and_b64 vcc, exec, s[0:1]
	v_or_b32_e32 v168, v2, v102
	v_mad_i64_i32 v[168:169], s[8:9], v168, s48, v[4:5]
	global_load_dword v169, v[168:169], off
	s_waitcnt vmcnt(1)
	v_mul_f32_e32 v46, v46, v162
	ds_write_b32 v49, v46
	s_cbranch_vccnz .LBB0_316
	v_readlane_b32 s52, v252, 14
	v_lshl_add_u64 v[46:47], v[2:3], 0, v[8:9]
	v_readlane_b32 s56, v252, 18
	v_readlane_b32 s57, v252, 19
	v_readlane_b32 s53, v252, 15
	v_readlane_b32 s54, v252, 16
	v_lshl_add_u64 v[46:47], v[46:47], 2, s[56:57]
	global_load_dword v45, v[46:47], off offset:184
	v_readlane_b32 s55, v252, 17
	v_readlane_b32 s58, v252, 20
	v_readlane_b32 s59, v252, 21
	v_readlane_b32 s60, v252, 22
	v_readlane_b32 s61, v252, 23
	v_readlane_b32 s62, v252, 24
	v_readlane_b32 s63, v252, 25
	v_readlane_b32 s64, v252, 26
	v_readlane_b32 s65, v252, 27
	v_readlane_b32 s66, v252, 28
	v_readlane_b32 s67, v252, 29
.LBB0_316:
	v_add_u32_e32 v49, v7, v103
	v_mov_b32_e32 v46, 1.0
	s_and_b64 vcc, exec, s[0:1]
	v_or_b32_e32 v162, v2, v104
	v_mad_i64_i32 v[160:161], s[8:9], v162, s48, v[4:5]
	global_load_dword v163, v[160:161], off
	s_waitcnt vmcnt(1)
	v_mul_f32_e32 v45, v45, v169
	v_mov_b32_e32 v47, 1.0
	ds_write_b32 v49, v45
	s_cbranch_vccnz .LBB0_318
	v_readlane_b32 s52, v252, 14
	v_lshl_add_u64 v[50:51], v[2:3], 0, v[8:9]
	v_readlane_b32 s56, v252, 18
	v_readlane_b32 s57, v252, 19
	v_readlane_b32 s53, v252, 15
	v_readlane_b32 s54, v252, 16
	v_lshl_add_u64 v[50:51], v[50:51], 2, s[56:57]
	global_load_dword v47, v[50:51], off offset:192
	v_readlane_b32 s55, v252, 17
	v_readlane_b32 s58, v252, 20
	v_readlane_b32 s59, v252, 21
	v_readlane_b32 s60, v252, 22
	v_readlane_b32 s61, v252, 23
	v_readlane_b32 s62, v252, 24
	v_readlane_b32 s63, v252, 25
	v_readlane_b32 s64, v252, 26
	v_readlane_b32 s65, v252, 27
	v_readlane_b32 s66, v252, 28
	v_readlane_b32 s67, v252, 29
.LBB0_318:
	v_add_u32_e32 v45, v7, v105
	s_and_b64 vcc, exec, s[0:1]
	v_or_b32_e32 v170, v2, v106
	v_mad_i64_i32 v[168:169], s[8:9], v170, s48, v[4:5]
	global_load_dword v171, v[168:169], off
	s_waitcnt vmcnt(1)
	v_mul_f32_e32 v47, v47, v163
	ds_write_b32 v45, v47
	s_cbranch_vccnz .LBB0_320
	v_readlane_b32 s52, v252, 14
	v_lshl_add_u64 v[46:47], v[2:3], 0, v[8:9]
	v_readlane_b32 s56, v252, 18
	v_readlane_b32 s57, v252, 19
	v_readlane_b32 s53, v252, 15
	v_readlane_b32 s54, v252, 16
	v_lshl_add_u64 v[46:47], v[46:47], 2, s[56:57]
	global_load_dword v46, v[46:47], off offset:200
	v_readlane_b32 s55, v252, 17
	v_readlane_b32 s58, v252, 20
	v_readlane_b32 s59, v252, 21
	v_readlane_b32 s60, v252, 22
	v_readlane_b32 s61, v252, 23
	v_readlane_b32 s62, v252, 24
	v_readlane_b32 s63, v252, 25
	v_readlane_b32 s64, v252, 26
	v_readlane_b32 s65, v252, 27
	v_readlane_b32 s66, v252, 28
	v_readlane_b32 s67, v252, 29
.LBB0_320:
	v_mov_b32_e32 v47, 1.0
	s_and_b64 vcc, exec, s[0:1]
	v_or_b32_e32 v162, v2, v107
	v_mad_i64_i32 v[160:161], s[8:9], v162, s48, v[4:5]
	global_load_dword v162, v[160:161], off
	s_waitcnt vmcnt(1)
	v_mul_f32_e32 v46, v46, v171
	ds_write_b32 v45, v46 offset:264
	v_mov_b32_e32 v46, 1.0
	s_cbranch_vccnz .LBB0_322
	v_readlane_b32 s52, v252, 14
	v_lshl_add_u64 v[50:51], v[2:3], 0, v[8:9]
	v_readlane_b32 s56, v252, 18
	v_readlane_b32 s57, v252, 19
	v_readlane_b32 s53, v252, 15
	v_readlane_b32 s54, v252, 16
	v_lshl_add_u64 v[50:51], v[50:51], 2, s[56:57]
	global_load_dword v46, v[50:51], off offset:208
	v_readlane_b32 s55, v252, 17
	v_readlane_b32 s58, v252, 20
	v_readlane_b32 s59, v252, 21
	v_readlane_b32 s60, v252, 22
	v_readlane_b32 s61, v252, 23
	v_readlane_b32 s62, v252, 24
	v_readlane_b32 s63, v252, 25
	v_readlane_b32 s64, v252, 26
	v_readlane_b32 s65, v252, 27
	v_readlane_b32 s66, v252, 28
	v_readlane_b32 s67, v252, 29
.LBB0_322:
	s_and_b64 vcc, exec, s[0:1]
	v_or_b32_e32 v170, v2, v108
	v_mad_i64_i32 v[168:169], s[8:9], v170, s48, v[4:5]
	global_load_dword v171, v[168:169], off
	s_waitcnt vmcnt(1)
	v_mul_f32_e32 v46, v46, v162
	ds_write_b32 v45, v46 offset:528
	s_cbranch_vccnz .LBB0_324
	v_readlane_b32 s52, v252, 14
	v_lshl_add_u64 v[46:47], v[2:3], 0, v[8:9]
	v_readlane_b32 s56, v252, 18
	v_readlane_b32 s57, v252, 19
	v_readlane_b32 s53, v252, 15
	v_readlane_b32 s54, v252, 16
	v_lshl_add_u64 v[46:47], v[46:47], 2, s[56:57]
	global_load_dword v47, v[46:47], off offset:216
	v_readlane_b32 s55, v252, 17
	v_readlane_b32 s58, v252, 20
	v_readlane_b32 s59, v252, 21
	v_readlane_b32 s60, v252, 22
	v_readlane_b32 s61, v252, 23
	v_readlane_b32 s62, v252, 24
	v_readlane_b32 s63, v252, 25
	v_readlane_b32 s64, v252, 26
	v_readlane_b32 s65, v252, 27
	v_readlane_b32 s66, v252, 28
	v_readlane_b32 s67, v252, 29
.LBB0_324:
	v_mov_b32_e32 v46, 1.0
	s_and_b64 vcc, exec, s[0:1]
	v_or_b32_e32 v162, v2, v109
	v_mad_i64_i32 v[160:161], s[8:9], v162, s48, v[4:5]
	global_load_dword v162, v[160:161], off
	s_waitcnt vmcnt(1)
	v_mul_f32_e32 v47, v47, v171
	ds_write_b32 v45, v47 offset:792
	v_mov_b32_e32 v47, 1.0
	s_cbranch_vccnz .LBB0_326
	v_readlane_b32 s52, v252, 14
	v_lshl_add_u64 v[50:51], v[2:3], 0, v[8:9]
	v_readlane_b32 s56, v252, 18
	v_readlane_b32 s57, v252, 19
	v_readlane_b32 s53, v252, 15
	v_readlane_b32 s54, v252, 16
	v_lshl_add_u64 v[50:51], v[50:51], 2, s[56:57]
	global_load_dword v47, v[50:51], off offset:224
	v_readlane_b32 s55, v252, 17
	v_readlane_b32 s58, v252, 20
	v_readlane_b32 s59, v252, 21
	v_readlane_b32 s60, v252, 22
	v_readlane_b32 s61, v252, 23
	v_readlane_b32 s62, v252, 24
	v_readlane_b32 s63, v252, 25
	v_readlane_b32 s64, v252, 26
	v_readlane_b32 s65, v252, 27
	v_readlane_b32 s66, v252, 28
	v_readlane_b32 s67, v252, 29
.LBB0_326:
	s_and_b64 vcc, exec, s[0:1]
	v_or_b32_e32 v170, v2, v110
	v_mad_i64_i32 v[168:169], s[8:9], v170, s48, v[4:5]
	global_load_dword v170, v[168:169], off
	s_waitcnt vmcnt(1)
	v_mul_f32_e32 v47, v47, v162
	ds_write_b32 v45, v47 offset:1056
	s_cbranch_vccnz .LBB0_328
	v_readlane_b32 s52, v252, 14
	v_lshl_add_u64 v[46:47], v[2:3], 0, v[8:9]
	v_readlane_b32 s56, v252, 18
	v_readlane_b32 s57, v252, 19
	v_readlane_b32 s53, v252, 15
	v_readlane_b32 s54, v252, 16
	v_lshl_add_u64 v[46:47], v[46:47], 2, s[56:57]
	global_load_dword v46, v[46:47], off offset:232
	v_readlane_b32 s55, v252, 17
	v_readlane_b32 s58, v252, 20
	v_readlane_b32 s59, v252, 21
	v_readlane_b32 s60, v252, 22
	v_readlane_b32 s61, v252, 23
	v_readlane_b32 s62, v252, 24
	v_readlane_b32 s63, v252, 25
	v_readlane_b32 s64, v252, 26
	v_readlane_b32 s65, v252, 27
	v_readlane_b32 s66, v252, 28
	v_readlane_b32 s67, v252, 29
.LBB0_328:
	s_and_b64 vcc, exec, s[0:1]
	v_or_b32_e32 v162, v2, v111
	v_mad_i64_i32 v[160:161], s[0:1], v162, s48, v[4:5]
	global_load_dword v162, v[160:161], off
	s_waitcnt vmcnt(1)
	v_mul_f32_e32 v46, v46, v170
	ds_write_b32 v45, v46 offset:1320
	s_cbranch_vccnz .LBB0_330
	v_readlane_b32 s52, v252, 14
	v_lshl_add_u64 v[46:47], v[2:3], 0, v[8:9]
	v_readlane_b32 s56, v252, 18
	v_readlane_b32 s57, v252, 19
	v_readlane_b32 s53, v252, 15
	v_readlane_b32 s54, v252, 16
	v_lshl_add_u64 v[46:47], v[46:47], 2, s[56:57]
	global_load_dword v46, v[46:47], off offset:240
	v_readlane_b32 s55, v252, 17
	v_readlane_b32 s58, v252, 20
	v_readlane_b32 s59, v252, 21
	v_readlane_b32 s60, v252, 22
	v_readlane_b32 s61, v252, 23
	v_readlane_b32 s62, v252, 24
	v_readlane_b32 s63, v252, 25
	v_readlane_b32 s64, v252, 26
	v_readlane_b32 s65, v252, 27
	v_readlane_b32 s66, v252, 28
	v_readlane_b32 s67, v252, 29
	s_branch .LBB0_331

.LBB0_331:
	v_readlane_b32 s0, v250, 38
	v_readlane_b32 s1, v250, 39
	s_and_b64 vcc, exec, s[0:1]
	s_waitcnt vmcnt(0)
	v_mul_f32_e32 v46, v46, v162
	ds_write_b32 v45, v46 offset:1584
	s_cbranch_vccz .LBB0_333
	v_readlane_b32 s52, v252, 14
	v_lshl_add_u64 v[46:47], v[2:3], 0, v[8:9]
	v_readlane_b32 s56, v252, 18
	v_readlane_b32 s57, v252, 19
	v_readlane_b32 s53, v252, 15
	v_readlane_b32 s54, v252, 16
	v_lshl_add_u64 v[46:47], v[46:47], 2, s[56:57]
	global_load_dword v46, v[46:47], off offset:248
	v_readlane_b32 s55, v252, 17
	v_readlane_b32 s58, v252, 20
	v_readlane_b32 s59, v252, 21
	v_readlane_b32 s60, v252, 22
	v_readlane_b32 s61, v252, 23
	v_readlane_b32 s62, v252, 24
	v_readlane_b32 s63, v252, 25
	v_readlane_b32 s64, v252, 26
	v_readlane_b32 s65, v252, 27
	v_readlane_b32 s66, v252, 28
	v_readlane_b32 s67, v252, 29
	s_cbranch_execnz .LBB0_115
	s_branch .LBB0_114

.LBB0_360:
	v_lshlrev_b16_e32 v8, 6, v8
	v_ashrrev_i32_e32 v15, 31, v14
	v_sub_u16_e32 v5, v5, v8
	v_mov_b32_e32 v8, 5
	v_lshlrev_b64 v[16:17], 23, v[14:15]
	v_lshlrev_b32_sdwa v8, v8, sext(v5) dst_sel:DWORD dst_unused:UNUSED_PAD src0_sel:DWORD src1_sel:WORD_0
	v_lshl_add_u64 v[16:17], s[72:73], 0, v[16:17]
	v_ashrrev_i32_e32 v9, 31, v8
	v_lshl_add_u64 v[16:17], v[8:9], 2, v[16:17]
	v_mov_b32_e32 v5, v0
	v_lshl_add_u64 v[16:17], v[16:17], 0, v[4:5]
	v_lshlrev_b64 v[20:21], 13, v[20:21]
	v_lshl_add_u64 v[20:21], v[16:17], 0, v[20:21]
	global_load_dword v5, v[20:21], off
	s_and_b64 vcc, exec, s[38:39]
	v_or_b32_e32 v168, v12, v11
	v_ashrrev_i32_e32 v169, 31, v168
	v_lshlrev_b64 v[168:169], 13, v[168:169]
	v_lshl_add_u64 v[168:169], v[16:17], 0, v[168:169]
	global_load_dword v170, v[168:169], off
	s_waitcnt vmcnt(1)
	v_mul_f32_e32 v5, v13, v5
	v_ashrrev_i32_e32 v13, 31, v12
	ds_write_b32 v56, v5
	s_cbranch_vccnz .LBB0_362
	v_lshl_add_u64 v[20:21], v[12:13], 0, v[2:3]
	v_lshl_add_u64 v[20:21], v[20:21], 2, v[18:19]
	global_load_dword v7, v[20:21], off offset:8
.LBB0_362:
	v_mov_b32_e32 v5, 1.0
	s_and_b64 vcc, exec, s[38:39]
	v_or_b32_e32 v160, v12, v22
	v_ashrrev_i32_e32 v161, 31, v160
	v_lshlrev_b64 v[160:161], 13, v[160:161]
	v_lshl_add_u64 v[160:161], v[16:17], 0, v[160:161]
	global_load_dword v162, v[160:161], off
	s_waitcnt vmcnt(1)
	v_mul_f32_e32 v7, v7, v170
	ds_write_b32 v56, v7 offset:264
	v_mov_b32_e32 v7, 1.0
	s_cbranch_vccnz .LBB0_364
	v_lshl_add_u64 v[20:21], v[12:13], 0, v[2:3]
	v_lshl_add_u64 v[20:21], v[20:21], 2, v[18:19]
	global_load_dword v7, v[20:21], off offset:16
.LBB0_364:
	s_and_b64 vcc, exec, s[38:39]
	v_or_b32_e32 v168, v12, v23
	v_ashrrev_i32_e32 v169, 31, v168
	v_lshlrev_b64 v[168:169], 13, v[168:169]
	v_lshl_add_u64 v[168:169], v[16:17], 0, v[168:169]
	global_load_dword v170, v[168:169], off
	s_waitcnt vmcnt(1)
	v_mul_f32_e32 v7, v7, v162
	ds_write_b32 v56, v7 offset:528
	s_cbranch_vccnz .LBB0_366
	v_lshl_add_u64 v[20:21], v[12:13], 0, v[2:3]
	v_lshl_add_u64 v[20:21], v[20:21], 2, v[18:19]
	global_load_dword v5, v[20:21], off offset:24
.LBB0_366:
	v_mov_b32_e32 v7, 1.0
	s_and_b64 vcc, exec, s[38:39]
	v_or_b32_e32 v160, v12, v24
	v_ashrrev_i32_e32 v161, 31, v160
	v_lshlrev_b64 v[160:161], 13, v[160:161]
	v_lshl_add_u64 v[160:161], v[16:17], 0, v[160:161]
	global_load_dword v162, v[160:161], off
	s_waitcnt vmcnt(1)
	v_mul_f32_e32 v5, v5, v170
	ds_write_b32 v56, v5 offset:792
	v_mov_b32_e32 v5, 1.0
	s_cbranch_vccnz .LBB0_368
	v_lshl_add_u64 v[20:21], v[12:13], 0, v[2:3]
	v_lshl_add_u64 v[20:21], v[20:21], 2, v[18:19]
	global_load_dword v5, v[20:21], off offset:32
.LBB0_368:
	s_and_b64 vcc, exec, s[38:39]
	v_or_b32_e32 v168, v12, v25
	v_ashrrev_i32_e32 v169, 31, v168
	v_lshlrev_b64 v[168:169], 13, v[168:169]
	v_lshl_add_u64 v[168:169], v[16:17], 0, v[168:169]
	global_load_dword v170, v[168:169], off
	s_waitcnt vmcnt(1)
	v_mul_f32_e32 v5, v5, v162
	ds_write_b32 v56, v5 offset:1056
	s_cbranch_vccnz .LBB0_370
	v_lshl_add_u64 v[20:21], v[12:13], 0, v[2:3]
	v_lshl_add_u64 v[20:21], v[20:21], 2, v[18:19]
	global_load_dword v7, v[20:21], off offset:40
.LBB0_370:
	v_mov_b32_e32 v5, 1.0
	s_and_b64 vcc, exec, s[38:39]
	v_or_b32_e32 v160, v12, v26
	v_ashrrev_i32_e32 v161, 31, v160
	v_lshlrev_b64 v[160:161], 13, v[160:161]
	v_lshl_add_u64 v[160:161], v[16:17], 0, v[160:161]
	global_load_dword v162, v[160:161], off
	s_waitcnt vmcnt(1)
	v_mul_f32_e32 v7, v7, v170
	ds_write_b32 v56, v7 offset:1320
	v_mov_b32_e32 v7, 1.0
	s_cbranch_vccnz .LBB0_372
	v_lshl_add_u64 v[20:21], v[12:13], 0, v[2:3]
	v_lshl_add_u64 v[20:21], v[20:21], 2, v[18:19]
	global_load_dword v7, v[20:21], off offset:48
.LBB0_372:
	s_and_b64 vcc, exec, s[38:39]
	v_or_b32_e32 v168, v12, v27
	v_ashrrev_i32_e32 v169, 31, v168
	v_lshlrev_b64 v[168:169], 13, v[168:169]
	v_lshl_add_u64 v[168:169], v[16:17], 0, v[168:169]
	global_load_dword v170, v[168:169], off
	s_waitcnt vmcnt(1)
	v_mul_f32_e32 v7, v7, v162
	ds_write_b32 v56, v7 offset:1584
	s_cbranch_vccnz .LBB0_374
	v_lshl_add_u64 v[20:21], v[12:13], 0, v[2:3]
	v_lshl_add_u64 v[20:21], v[20:21], 2, v[18:19]
	global_load_dword v5, v[20:21], off offset:56
.LBB0_374:
	v_mov_b32_e32 v7, 1.0
	s_and_b64 vcc, exec, s[38:39]
	v_or_b32_e32 v160, v12, v28
	v_ashrrev_i32_e32 v161, 31, v160
	v_lshlrev_b64 v[160:161], 13, v[160:161]
	v_lshl_add_u64 v[160:161], v[16:17], 0, v[160:161]
	global_load_dword v162, v[160:161], off
	s_waitcnt vmcnt(1)
	v_mul_f32_e32 v5, v5, v170
	ds_write_b32 v56, v5 offset:1848
	v_mov_b32_e32 v5, 1.0
	s_cbranch_vccnz .LBB0_376
	v_lshl_add_u64 v[20:21], v[12:13], 0, v[2:3]
	v_lshl_add_u64 v[20:21], v[20:21], 2, v[18:19]
	global_load_dword v5, v[20:21], off offset:64
.LBB0_376:
	s_and_b64 vcc, exec, s[38:39]
	v_or_b32_e32 v168, v12, v29
	v_ashrrev_i32_e32 v169, 31, v168
	v_lshlrev_b64 v[168:169], 13, v[168:169]
	v_lshl_add_u64 v[168:169], v[16:17], 0, v[168:169]
	global_load_dword v170, v[168:169], off
	s_waitcnt vmcnt(1)
	v_mul_f32_e32 v5, v5, v162
	ds_write_b32 v56, v5 offset:2112
	s_cbranch_vccnz .LBB0_378
	v_lshl_add_u64 v[20:21], v[12:13], 0, v[2:3]
	v_lshl_add_u64 v[20:21], v[20:21], 2, v[18:19]
	global_load_dword v7, v[20:21], off offset:72
.LBB0_378:
	v_mov_b32_e32 v5, 1.0
	s_and_b64 vcc, exec, s[38:39]
	v_or_b32_e32 v160, v12, v30
	v_ashrrev_i32_e32 v161, 31, v160
	v_lshlrev_b64 v[160:161], 13, v[160:161]
	v_lshl_add_u64 v[160:161], v[16:17], 0, v[160:161]
	global_load_dword v162, v[160:161], off
	s_waitcnt vmcnt(1)
	v_mul_f32_e32 v7, v7, v170
	ds_write_b32 v56, v7 offset:2376
	v_mov_b32_e32 v7, 1.0
	s_cbranch_vccnz .LBB0_380
	v_lshl_add_u64 v[20:21], v[12:13], 0, v[2:3]
	v_lshl_add_u64 v[20:21], v[20:21], 2, v[18:19]
	global_load_dword v7, v[20:21], off offset:80
.LBB0_380:
	s_and_b64 vcc, exec, s[38:39]
	v_or_b32_e32 v168, v12, v31
	v_ashrrev_i32_e32 v169, 31, v168
	v_lshlrev_b64 v[168:169], 13, v[168:169]
	v_lshl_add_u64 v[168:169], v[16:17], 0, v[168:169]
	global_load_dword v170, v[168:169], off
	s_waitcnt vmcnt(1)
	v_mul_f32_e32 v7, v7, v162
	ds_write_b32 v56, v7 offset:2640
	s_cbranch_vccnz .LBB0_382
	v_lshl_add_u64 v[20:21], v[12:13], 0, v[2:3]
	v_lshl_add_u64 v[20:21], v[20:21], 2, v[18:19]
	global_load_dword v5, v[20:21], off offset:88
.LBB0_382:
	v_mov_b32_e32 v7, 1.0
	s_and_b64 vcc, exec, s[38:39]
	v_or_b32_e32 v160, v12, v32
	v_ashrrev_i32_e32 v161, 31, v160
	v_lshlrev_b64 v[160:161], 13, v[160:161]
	v_lshl_add_u64 v[160:161], v[16:17], 0, v[160:161]
	global_load_dword v162, v[160:161], off
	s_waitcnt vmcnt(1)
	v_mul_f32_e32 v5, v5, v170
	ds_write_b32 v56, v5 offset:2904
	v_mov_b32_e32 v5, 1.0
	s_cbranch_vccnz .LBB0_384
	v_lshl_add_u64 v[20:21], v[12:13], 0, v[2:3]
	v_lshl_add_u64 v[20:21], v[20:21], 2, v[18:19]
	global_load_dword v5, v[20:21], off offset:96
.LBB0_384:
	s_and_b64 vcc, exec, s[38:39]
	v_or_b32_e32 v168, v12, v33
	v_ashrrev_i32_e32 v169, 31, v168
	v_lshlrev_b64 v[168:169], 13, v[168:169]
	v_lshl_add_u64 v[168:169], v[16:17], 0, v[168:169]
	global_load_dword v170, v[168:169], off
	s_waitcnt vmcnt(1)
	v_mul_f32_e32 v5, v5, v162
	ds_write_b32 v56, v5 offset:3168
	s_cbranch_vccnz .LBB0_386
	v_lshl_add_u64 v[20:21], v[12:13], 0, v[2:3]
	v_lshl_add_u64 v[20:21], v[20:21], 2, v[18:19]
	global_load_dword v7, v[20:21], off offset:104
.LBB0_386:
	v_mov_b32_e32 v5, 1.0
	s_and_b64 vcc, exec, s[38:39]
	v_or_b32_e32 v160, v12, v34
	v_ashrrev_i32_e32 v161, 31, v160
	v_lshlrev_b64 v[160:161], 13, v[160:161]
	v_lshl_add_u64 v[160:161], v[16:17], 0, v[160:161]
	global_load_dword v162, v[160:161], off
	s_waitcnt vmcnt(1)
	v_mul_f32_e32 v7, v7, v170
	ds_write_b32 v56, v7 offset:3432
	v_mov_b32_e32 v7, 1.0
	s_cbranch_vccnz .LBB0_388
	v_lshl_add_u64 v[20:21], v[12:13], 0, v[2:3]
	v_lshl_add_u64 v[20:21], v[20:21], 2, v[18:19]
	global_load_dword v7, v[20:21], off offset:112
.LBB0_388:
	s_and_b64 vcc, exec, s[38:39]
	v_or_b32_e32 v168, v12, v35
	v_ashrrev_i32_e32 v169, 31, v168
	v_lshlrev_b64 v[168:169], 13, v[168:169]
	v_lshl_add_u64 v[168:169], v[16:17], 0, v[168:169]
	global_load_dword v170, v[168:169], off
	s_waitcnt vmcnt(1)
	v_mul_f32_e32 v7, v7, v162
	ds_write_b32 v56, v7 offset:3696
	s_cbranch_vccnz .LBB0_390
	v_lshl_add_u64 v[20:21], v[12:13], 0, v[2:3]
	v_lshl_add_u64 v[20:21], v[20:21], 2, v[18:19]
	global_load_dword v5, v[20:21], off offset:120
.LBB0_390:
	v_mov_b32_e32 v7, 1.0
	s_and_b64 vcc, exec, s[38:39]
	v_or_b32_e32 v160, v12, v36
	v_ashrrev_i32_e32 v161, 31, v160
	v_lshlrev_b64 v[160:161], 13, v[160:161]
	v_lshl_add_u64 v[160:161], v[16:17], 0, v[160:161]
	global_load_dword v162, v[160:161], off
	s_waitcnt vmcnt(1)
	v_mul_f32_e32 v5, v5, v170
	ds_write_b32 v56, v5 offset:3960
	v_mov_b32_e32 v5, 1.0
	s_cbranch_vccnz .LBB0_392
	v_lshl_add_u64 v[20:21], v[12:13], 0, v[2:3]
	v_lshl_add_u64 v[20:21], v[20:21], 2, v[18:19]
	global_load_dword v5, v[20:21], off offset:128
.LBB0_392:
	s_and_b64 vcc, exec, s[38:39]
	v_or_b32_e32 v168, v12, v37
	v_ashrrev_i32_e32 v169, 31, v168
	v_lshlrev_b64 v[168:169], 13, v[168:169]
	v_lshl_add_u64 v[168:169], v[16:17], 0, v[168:169]
	global_load_dword v170, v[168:169], off
	s_waitcnt vmcnt(1)
	v_mul_f32_e32 v5, v5, v162
	ds_write_b32 v56, v5 offset:4224
	s_cbranch_vccnz .LBB0_394
	v_lshl_add_u64 v[20:21], v[12:13], 0, v[2:3]
	v_lshl_add_u64 v[20:21], v[20:21], 2, v[18:19]
	global_load_dword v7, v[20:21], off offset:136
.LBB0_394:
	v_mov_b32_e32 v5, 1.0
	s_and_b64 vcc, exec, s[38:39]
	v_or_b32_e32 v160, v12, v38
	v_ashrrev_i32_e32 v161, 31, v160
	v_lshlrev_b64 v[160:161], 13, v[160:161]
	v_lshl_add_u64 v[160:161], v[16:17], 0, v[160:161]
	global_load_dword v162, v[160:161], off
	s_waitcnt vmcnt(1)
	v_mul_f32_e32 v7, v7, v170
	ds_write_b32 v56, v7 offset:4488
	v_mov_b32_e32 v7, 1.0
	s_cbranch_vccnz .LBB0_396
	v_lshl_add_u64 v[20:21], v[12:13], 0, v[2:3]
	v_lshl_add_u64 v[20:21], v[20:21], 2, v[18:19]
	global_load_dword v7, v[20:21], off offset:144
.LBB0_396:
	s_and_b64 vcc, exec, s[38:39]
	v_or_b32_e32 v168, v12, v39
	v_ashrrev_i32_e32 v169, 31, v168
	v_lshlrev_b64 v[168:169], 13, v[168:169]
	v_lshl_add_u64 v[168:169], v[16:17], 0, v[168:169]
	global_load_dword v170, v[168:169], off
	s_waitcnt vmcnt(1)
	v_mul_f32_e32 v7, v7, v162
	ds_write_b32 v56, v7 offset:4752
	s_cbranch_vccnz .LBB0_398
	v_lshl_add_u64 v[20:21], v[12:13], 0, v[2:3]
	v_lshl_add_u64 v[20:21], v[20:21], 2, v[18:19]
	global_load_dword v5, v[20:21], off offset:152
.LBB0_398:
	v_mov_b32_e32 v7, 1.0
	s_and_b64 vcc, exec, s[38:39]
	v_or_b32_e32 v160, v12, v40
	v_ashrrev_i32_e32 v161, 31, v160
	v_lshlrev_b64 v[160:161], 13, v[160:161]
	v_lshl_add_u64 v[160:161], v[16:17], 0, v[160:161]
	global_load_dword v162, v[160:161], off
	s_waitcnt vmcnt(1)
	v_mul_f32_e32 v5, v5, v170
	ds_write_b32 v56, v5 offset:5016
	v_mov_b32_e32 v5, 1.0
	s_cbranch_vccnz .LBB0_400
	v_lshl_add_u64 v[20:21], v[12:13], 0, v[2:3]
	v_lshl_add_u64 v[20:21], v[20:21], 2, v[18:19]
	global_load_dword v5, v[20:21], off offset:160
.LBB0_400:
	s_and_b64 vcc, exec, s[38:39]
	v_or_b32_e32 v168, v12, v41
	v_ashrrev_i32_e32 v169, 31, v168
	v_lshlrev_b64 v[168:169], 13, v[168:169]
	v_lshl_add_u64 v[168:169], v[16:17], 0, v[168:169]
	global_load_dword v170, v[168:169], off
	s_waitcnt vmcnt(1)
	v_mul_f32_e32 v5, v5, v162
	ds_write_b32 v56, v5 offset:5280
	s_cbranch_vccnz .LBB0_402
	v_lshl_add_u64 v[20:21], v[12:13], 0, v[2:3]
	v_lshl_add_u64 v[20:21], v[20:21], 2, v[18:19]
	global_load_dword v7, v[20:21], off offset:168
.LBB0_402:
	v_mov_b32_e32 v5, 1.0
	s_and_b64 vcc, exec, s[38:39]
	v_or_b32_e32 v160, v12, v42
	v_ashrrev_i32_e32 v161, 31, v160
	v_lshlrev_b64 v[160:161], 13, v[160:161]
	v_lshl_add_u64 v[160:161], v[16:17], 0, v[160:161]
	global_load_dword v162, v[160:161], off
	s_waitcnt vmcnt(1)
	v_mul_f32_e32 v7, v7, v170
	ds_write_b32 v56, v7 offset:5544
	v_mov_b32_e32 v7, 1.0
	s_cbranch_vccnz .LBB0_404
	v_lshl_add_u64 v[20:21], v[12:13], 0, v[2:3]
	v_lshl_add_u64 v[20:21], v[20:21], 2, v[18:19]
	global_load_dword v7, v[20:21], off offset:176
.LBB0_404:
	s_and_b64 vcc, exec, s[38:39]
	v_or_b32_e32 v168, v12, v43
	v_ashrrev_i32_e32 v169, 31, v168
	v_lshlrev_b64 v[168:169], 13, v[168:169]
	v_lshl_add_u64 v[168:169], v[16:17], 0, v[168:169]
	global_load_dword v170, v[168:169], off
	s_waitcnt vmcnt(1)
	v_mul_f32_e32 v7, v7, v162
	ds_write_b32 v56, v7 offset:5808
	s_cbranch_vccnz .LBB0_406
	v_lshl_add_u64 v[20:21], v[12:13], 0, v[2:3]
	v_lshl_add_u64 v[20:21], v[20:21], 2, v[18:19]
	global_load_dword v5, v[20:21], off offset:184
.LBB0_406:
	v_mov_b32_e32 v7, 1.0
	s_and_b64 vcc, exec, s[38:39]
	v_or_b32_e32 v160, v12, v44
	v_ashrrev_i32_e32 v161, 31, v160
	v_lshlrev_b64 v[160:161], 13, v[160:161]
	v_lshl_add_u64 v[160:161], v[16:17], 0, v[160:161]
	global_load_dword v162, v[160:161], off
	s_waitcnt vmcnt(1)
	v_mul_f32_e32 v5, v5, v170
	ds_write_b32 v56, v5 offset:6072
	v_mov_b32_e32 v5, 1.0
	s_cbranch_vccnz .LBB0_408
	v_lshl_add_u64 v[20:21], v[12:13], 0, v[2:3]
	v_lshl_add_u64 v[20:21], v[20:21], 2, v[18:19]
	global_load_dword v5, v[20:21], off offset:192
.LBB0_408:
	s_and_b64 vcc, exec, s[38:39]
	v_or_b32_e32 v168, v12, v45
	v_ashrrev_i32_e32 v169, 31, v168
	v_lshlrev_b64 v[168:169], 13, v[168:169]
	v_lshl_add_u64 v[168:169], v[16:17], 0, v[168:169]
	global_load_dword v170, v[168:169], off
	s_waitcnt vmcnt(1)
	v_mul_f32_e32 v5, v5, v162
	ds_write_b32 v56, v5 offset:6336
	s_cbranch_vccnz .LBB0_410
	v_lshl_add_u64 v[20:21], v[12:13], 0, v[2:3]
	v_lshl_add_u64 v[20:21], v[20:21], 2, v[18:19]
	global_load_dword v7, v[20:21], off offset:200
.LBB0_410:
	v_mov_b32_e32 v5, 1.0
	s_and_b64 vcc, exec, s[38:39]
	v_or_b32_e32 v160, v12, v46
	v_ashrrev_i32_e32 v161, 31, v160
	v_lshlrev_b64 v[160:161], 13, v[160:161]
	v_lshl_add_u64 v[160:161], v[16:17], 0, v[160:161]
	global_load_dword v162, v[160:161], off
	s_waitcnt vmcnt(1)
	v_mul_f32_e32 v7, v7, v170
	ds_write_b32 v56, v7 offset:6600
	v_mov_b32_e32 v7, 1.0
	s_cbranch_vccnz .LBB0_412
	v_lshl_add_u64 v[20:21], v[12:13], 0, v[2:3]
	v_lshl_add_u64 v[20:21], v[20:21], 2, v[18:19]
	global_load_dword v7, v[20:21], off offset:208
.LBB0_412:
	s_and_b64 vcc, exec, s[38:39]
	v_or_b32_e32 v168, v12, v47
	v_ashrrev_i32_e32 v169, 31, v168
	v_lshlrev_b64 v[168:169], 13, v[168:169]
	v_lshl_add_u64 v[168:169], v[16:17], 0, v[168:169]
	global_load_dword v170, v[168:169], off
	s_waitcnt vmcnt(1)
	v_mul_f32_e32 v7, v7, v162
	ds_write_b32 v56, v7 offset:6864
	s_cbranch_vccnz .LBB0_414
	v_lshl_add_u64 v[20:21], v[12:13], 0, v[2:3]
	v_lshl_add_u64 v[20:21], v[20:21], 2, v[18:19]
	global_load_dword v5, v[20:21], off offset:216
.LBB0_414:
	v_mov_b32_e32 v7, 1.0
	s_and_b64 vcc, exec, s[38:39]
	v_or_b32_e32 v160, v12, v48
	v_ashrrev_i32_e32 v161, 31, v160
	v_lshlrev_b64 v[160:161], 13, v[160:161]
	v_lshl_add_u64 v[160:161], v[16:17], 0, v[160:161]
	global_load_dword v162, v[160:161], off
	s_waitcnt vmcnt(1)
	v_mul_f32_e32 v5, v5, v170
	ds_write_b32 v56, v5 offset:7128
	v_mov_b32_e32 v5, 1.0
	s_cbranch_vccnz .LBB0_416
	v_lshl_add_u64 v[20:21], v[12:13], 0, v[2:3]
	v_lshl_add_u64 v[20:21], v[20:21], 2, v[18:19]
	global_load_dword v5, v[20:21], off offset:224
.LBB0_416:
	s_and_b64 vcc, exec, s[38:39]
	v_or_b32_e32 v168, v12, v49
	v_ashrrev_i32_e32 v169, 31, v168
	v_lshlrev_b64 v[168:169], 13, v[168:169]
	v_lshl_add_u64 v[168:169], v[16:17], 0, v[168:169]
	global_load_dword v170, v[168:169], off
	s_waitcnt vmcnt(1)
	v_mul_f32_e32 v5, v5, v162
	ds_write_b32 v56, v5 offset:7392
	s_cbranch_vccnz .LBB0_418
	v_lshl_add_u64 v[20:21], v[12:13], 0, v[2:3]
	v_lshl_add_u64 v[20:21], v[20:21], 2, v[18:19]
	global_load_dword v7, v[20:21], off offset:232
.LBB0_418:
	s_and_b64 vcc, exec, s[38:39]
	v_or_b32_e32 v160, v12, v50
	v_ashrrev_i32_e32 v161, 31, v160
	v_lshlrev_b64 v[160:161], 13, v[160:161]
	v_lshl_add_u64 v[160:161], v[16:17], 0, v[160:161]
	global_load_dword v162, v[160:161], off
	s_waitcnt vmcnt(1)
	v_mul_f32_e32 v5, v7, v170
	ds_write_b32 v56, v5 offset:7656
	s_cbranch_vccnz .LBB0_420
	v_lshl_add_u64 v[20:21], v[12:13], 0, v[2:3]
	v_lshl_add_u64 v[20:21], v[20:21], 2, v[18:19]
	global_load_dword v5, v[20:21], off offset:240
	s_branch .LBB0_421

.LBB0_421:
	s_and_b64 vcc, exec, s[92:93]
	s_waitcnt vmcnt(0)
	v_mul_f32_e32 v5, v5, v162
	ds_write_b32 v56, v5 offset:7920
	s_cbranch_vccz .LBB0_423
	v_lshl_add_u64 v[20:21], v[12:13], 0, v[2:3]
	v_lshl_add_u64 v[18:19], v[20:21], 2, v[18:19]
	global_load_dword v5, v[18:19], off offset:248
	s_cbranch_execnz .LBB0_357
	s_branch .LBB0_356
